# baseline (speedup 1.0000x reference)
; DI int my_tid() { int t = tid_raw(); asm volatile("" : "+v"(t)); return t; }
; #define STAGE_A(b, h, kt) { const u16* ap_ = A + (size_t)((h) * ahalf + (unsigned)(kt) * 64u); glds16(ap_ + ao0, l0 + SA_(b, h)); glds16(ap_ + ao1, l0 + SA_(b, h) + 8192); }
; #define STAGE_B(b, h, kt) { const u16* bp_ = ((h) ? B1 : B0) + (unsigned)(kt) * 64u; glds16(bp_ + bo0, l0 + SB_(b, h)); glds16(bp_ + bo1, l0 + SB_(b, h) + 8192); }
; #define WAIT_V(n) asm volatile("s_waitcnt vmcnt(" #n ")" ::: "memory");
; #define BAR __builtin_amdgcn_s_barrier();
; DI void gemm256(const u16* __restrict__ A, int lda, const u16* __restrict__ B0, const u16* __restrict__ B1, int ldb, int nt, acc_t& acc, char* lds) {
;   const int tid = my_tid();
;   const int lane = tid & 63, wid = tid >> 6, wr = wid >> 2, wc = wid & 3, fr = lane & 15, fq = lane >> 4;
;   int r0, c0, r1, c1;
;   stage_rc(tid * 16, r0, c0); stage_rc(tid * 16 + 8192, r1, c1);
;   const unsigned ao0 = (unsigned)(r0 * lda + c0), ao1 = (unsigned)(r1 * lda + c1);
;   const unsigned ahalf = 128u * (unsigned)lda;
;   const int p0 = (r0 & ~31) + (((r0 & 15) >> 2) * 8) + (((r0 >> 4) & 1) * 4) + (r0 & 3), p1 = (r1 & ~31) + (((r1 & 15) >> 2) * 8) + (((r1 >> 4) & 1) * 4) + (r1 & 3);
;   const unsigned bo0 = (unsigned)(p0 * ldb + c0), bo1 = (unsigned)(p1 * ldb + c1);
;   char* l0 = lds + tid * 16;
;     ...
;   bf16x8 At[4][2], Bq0[2][2], Bq1[2][2];
;   WAIT_V(0)
;   STAGE_B(0, 0, 0) STAGE_A(0, 0, 0) STAGE_B(0, 1, 0) STAGE_A(0, 1, 0)
;   if (wr == 1) BAR
; DI void p1_phase(const Params& p, int layer, char* lds) {
;     ...
;     gemm256(xb + (size_t)row0 * D, D, wt + (size_t)col0 * D, wt + (size_t)(col0 + 128) * D, D, 16, acc, lds);
.LBB0_164:
	s_mul_i32 s7, s2, s7
	s_sub_i32 s7, s19, s7
	s_sext_i32_i8 s50, s7
	s_sext_i32_i8 s47, s2
	s_add_i32 s3, s3, s50
	s_lshl_b32 s42, s3, 8
	s_andn2_b64 vcc, exec, s[22:23]
	s_lshl_b32 s44, s47, 8
	v_readlane_b32 s19, v255, 31
	s_cbranch_vccnz .LBB0_560
	s_ashr_i32 s43, s42, 31
	s_lshl_b64 s[22:23], s[42:43], 11
	v_readlane_b32 s8, v254, 22
	v_readlane_b32 s9, v254, 23
	s_add_u32 s8, s8, s22
	s_addc_u32 s9, s9, s23
	s_ashr_i32 s45, s44, 31
	s_lshl_b64 s[28:29], s[44:45], 11
	s_add_u32 s38, s90, s28
	s_addc_u32 s39, s91, s29
	s_or_b32 s36, s44, 0x80
	s_ashr_i32 s37, s36, 31
	s_lshl_b64 s[36:37], s[36:37], 11
	s_add_u32 s36, s90, s36
	s_getreg_b32 s3, hwreg(HW_REG_HW_ID, 0, 6)
	s_addc_u32 s37, s91, s37
	s_lshl_b32 s3, s3, 2
	s_and_b32 s3, s3, 0xfc
	s_add_i32 s3, s3, 0x20040
	v_mov_b32_e32 v0, s3
	ds_read_b32 v0, v0
	v_mov_b32_e32 v131, v65
	s_waitcnt lgkmcnt(0)
	v_readfirstlane_b32 s3, v0
	s_nop 1
	v_lshl_or_b32 v140, s3, 6, v214
	s_nop 0
	v_bfe_i32 v2, v140, 27, 1
	v_lshlrev_b32_e32 v0, 4, v140
	v_lshrrev_b32_e32 v2, 22, v2
	v_add_u32_e32 v2, v0, v2
	v_and_b32_e32 v2, 0xfffffc00, v2
	v_sub_u32_e32 v2, v0, v2
	v_ashrrev_i32_e32 v1, 31, v140
	v_lshrrev_b32_e32 v3, 4, v2
	v_lshrrev_b32_e32 v1, 26, v1
	v_bitop3_b32 v3, v3, v2, 32 bitop3:0x6c
	v_ashrrev_i32_e32 v2, 31, v2
	v_add_u32_e32 v1, v140, v1
	v_lshrrev_b32_e32 v2, 26, v2
	v_ashrrev_i32_e32 v1, 6, v1
	v_add_u32_e32 v2, v3, v2
	v_lshlrev_b32_e32 v4, 3, v1
	v_ashrrev_i32_e32 v2, 6, v2
	v_lshlrev_b32_e32 v1, 5, v1
	v_and_b32_e32 v14, 32, v1
	v_mul_i32_i24_e32 v1, 64, v2
	v_sub_u32_e32 v1, v3, v1
	v_add_u32_e32 v3, 0x2000, v0
	v_ashrrev_i32_e32 v5, 31, v3
	v_lshrrev_b32_e32 v5, 22, v5
	v_add_u32_e32 v5, v3, v5
	v_ashrrev_i32_e32 v13, 10, v5
	v_mul_i32_i24_e32 v5, 0x400, v13
	v_sub_u32_e32 v3, v3, v5
	v_lshrrev_b32_e32 v5, 4, v3
	v_bitop3_b32 v3, v5, v3, 32 bitop3:0x6c
	v_ashrrev_i32_e32 v6, 31, v3
	v_lshrrev_b32_e32 v6, 26, v6
	v_and_b32_e32 v4, -16, v4
	v_ashrrev_i16_sdwa v15, v215, sext(v1) dst_sel:DWORD dst_unused:UNUSED_PAD src0_sel:DWORD src1_sel:BYTE_0
	v_lshlrev_b32_e32 v5, 3, v13
	v_add_u32_e32 v6, v3, v6
	v_add_u32_e32 v4, v2, v4
	v_add_u32_sdwa v1, v14, sext(v15) dst_sel:DWORD dst_unused:UNUSED_PAD src0_sel:DWORD src1_sel:WORD_0
	v_and_b32_e32 v5, -16, v5
	v_ashrrev_i32_e32 v16, 6, v6
	v_and_b32_e32 v6, 0xc0, v6
	v_add_u32_e32 v5, v16, v5
	v_sub_u32_e32 v3, v3, v6
	v_lshl_add_u32 v8, v4, 10, v1
	v_and_b32_e32 v19, 0xffffffe0, v4
	v_lshlrev_b32_e32 v6, 1, v4
	v_lshrrev_b32_e32 v4, 2, v4
	v_and_b32_e32 v22, 4, v4
	v_and_b32_e32 v24, 3, v2
	v_lshlrev_b32_e32 v4, 1, v5
	v_lshlrev_b32_e32 v7, 5, v13
	v_and_b32_e32 v21, 24, v6
	v_or_b32_e32 v2, v19, v24
	v_and_b32_e32 v20, 0xffffffe0, v5
	v_and_b32_e32 v23, 24, v4
	v_lshrrev_b32_e32 v4, 2, v5
	v_and_b32_e32 v26, 3, v16
	v_and_b32_e32 v17, 32, v7
	v_ashrrev_i16_sdwa v18, v215, sext(v3) dst_sel:DWORD dst_unused:UNUSED_PAD src0_sel:DWORD src1_sel:BYTE_0
	v_or3_b32 v2, v2, v21, v22
	v_and_b32_e32 v25, 4, v4
	v_or_b32_e32 v4, v20, v26
	v_add_u32_e32 v149, 0, v0
	v_add_u32_sdwa v3, v17, sext(v18) dst_sel:DWORD dst_unused:UNUSED_PAD src0_sel:DWORD src1_sel:WORD_0
	v_or3_b32 v4, v4, v23, v25
	v_lshl_add_u32 v64, v2, 10, v1
	v_add_u32_e32 v151, 0x10000, v149
	v_lshl_add_u32 v130, v5, 10, v3
	v_lshl_add_u32 v2, v4, 10, v3
	v_lshlrev_b64 v[6:7], 1, v[64:65]
	v_readfirstlane_b32 s3, v151
	v_mov_b32_e32 v3, v65
	v_add_u32_e32 v152, 0x12000, v149
	v_lshl_add_u64 v[0:1], s[38:39], 0, v[6:7]
	s_mov_b32 m0, s3
	v_lshlrev_b64 v[28:29], 1, v[2:3]
	v_readfirstlane_b32 s3, v152
	v_mov_b32_e32 v64, v8
	global_load_lds_dwordx4 v[0:1], off
	v_lshl_add_u64 v[2:3], s[38:39], 0, v[28:29]
	s_mov_b32 m0, s3
	v_lshlrev_b64 v[30:31], 1, v[64:65]
	v_readfirstlane_b32 s3, v149
	v_add_u32_e32 v153, 0x2000, v149
	global_load_lds_dwordx4 v[2:3], off
	v_lshl_add_u64 v[4:5], s[8:9], 0, v[30:31]
	s_mov_b32 m0, s3
	v_lshlrev_b64 v[32:33], 1, v[130:131]
	v_readfirstlane_b32 s3, v153
	v_add_u32_e32 v154, 0x14000, v149
	global_load_lds_dwordx4 v[4:5], off
	v_lshl_add_u64 v[8:9], s[8:9], 0, v[32:33]
	s_mov_b32 m0, s3
	v_readfirstlane_b32 s3, v154
	v_add_u32_e32 v156, 0x16000, v149
	global_load_lds_dwordx4 v[8:9], off
	v_lshl_add_u64 v[10:11], s[36:37], 0, v[6:7]
	s_mov_b32 m0, s3
	v_lshl_add_u64 v[6:7], s[36:37], 0, v[28:29]
	v_readfirstlane_b32 s3, v156
	s_add_u32 s36, s8, 0x40000
	v_add_u32_e32 v157, 0x4000, v149
	global_load_lds_dwordx4 v[10:11], off
	s_mov_b32 m0, s3
	s_addc_u32 s37, s9, 0
	v_readfirstlane_b32 s3, v157
	v_add_u32_e32 v158, 0x6000, v149
	global_load_lds_dwordx4 v[6:7], off
	v_lshl_add_u64 v[28:29], s[36:37], 0, v[30:31]
	s_mov_b32 m0, s3
	v_readfirstlane_b32 s3, v158
	global_load_lds_dwordx4 v[28:29], off
	v_lshl_add_u64 v[28:29], s[36:37], 0, v[32:33]
	s_mov_b32 m0, s3
	v_ashrrev_i32_e32 v12, 8, v140
	global_load_lds_dwordx4 v[28:29], off
	v_cmp_eq_u32_e32 vcc, 1, v12
	s_and_saveexec_b64 s[36:37], vcc
	s_cbranch_execz .LBB0_167
	s_barrier

; DI int my_tid() { int t = tid_raw(); asm volatile("" : "+v"(t)); return t; }
; #define STAGE_A(b, h, kt) { const u16* ap_ = A + (size_t)((h) * ahalf + (unsigned)(kt) * 64u); glds16(ap_ + ao0, l0 + SA_(b, h)); glds16(ap_ + ao1, l0 + SA_(b, h) + 8192); }
; #define STAGE_B(b, h, kt) { const u16* bp_ = ((h) ? B1 : B0) + (unsigned)(kt) * 64u; glds16(bp_ + bo0, l0 + SB_(b, h)); glds16(bp_ + bo1, l0 + SB_(b, h) + 8192); }
; #define WAIT_V(n) asm volatile("s_waitcnt vmcnt(" #n ")" ::: "memory");
; #define BAR __builtin_amdgcn_s_barrier();
; DI void gemm256(const u16* __restrict__ A, int lda, const u16* __restrict__ B0, const u16* __restrict__ B1, int ldb, int nt, acc_t& acc, char* lds) {
;   const int tid = my_tid();
;   const int lane = tid & 63, wid = tid >> 6, wr = wid >> 2, wc = wid & 3, fr = lane & 15, fq = lane >> 4;
;   int r0, c0, r1, c1;
;   stage_rc(tid * 16, r0, c0); stage_rc(tid * 16 + 8192, r1, c1);
;   const unsigned ao0 = (unsigned)(r0 * lda + c0), ao1 = (unsigned)(r1 * lda + c1);
;   const unsigned ahalf = 128u * (unsigned)lda;
;   const int p0 = (r0 & ~31) + (((r0 & 15) >> 2) * 8) + (((r0 >> 4) & 1) * 4) + (r0 & 3), p1 = (r1 & ~31) + (((r1 & 15) >> 2) * 8) + (((r1 >> 4) & 1) * 4) + (r1 & 3);
;   const unsigned bo0 = (unsigned)(p0 * ldb + c0), bo1 = (unsigned)(p1 * ldb + c1);
;   char* l0 = lds + tid * 16;
;     ...
;   bf16x8 At[4][2], Bq0[2][2], Bq1[2][2];
;   WAIT_V(0)
;   STAGE_B(0, 0, 0) STAGE_A(0, 0, 0) STAGE_B(0, 1, 0) STAGE_A(0, 1, 0)
;   if (wr == 1) BAR
; DI void p1_phase(const Params& p, int layer, char* lds) {
;     ...
;     if (seg == 2 || seg == 6) {
;       gemm256(wt + (size_t)col0 * D, D, xb + (size_t)row0 * D, xb + (size_t)(row0 + 128) * D, D, 16, acc, lds);
.LBB0_560:
	s_and_b64 vcc, exec, s[8:9]
	s_cbranch_vccz .LBB0_159
	s_lshl_b32 s92, s47, 18
	s_lshl_b64 s[28:29], s[92:93], 1
	s_add_u32 s8, s90, s28
	s_addc_u32 s9, s91, s29
	s_ashr_i32 s43, s42, 31
	s_lshl_b64 s[2:3], s[42:43], 11
	v_readlane_b32 s22, v254, 22
	v_readlane_b32 s23, v254, 23
	s_add_u32 s36, s22, s2
	s_addc_u32 s37, s23, s3
	s_or_b32 s2, s42, 0x80
	s_ashr_i32 s3, s2, 31
	s_lshl_b64 s[2:3], s[2:3], 11
	s_add_u32 s22, s22, s2
	s_getreg_b32 s2, hwreg(HW_REG_HW_ID, 0, 6)
	s_addc_u32 s23, s23, s3
	s_lshl_b32 s2, s2, 2
	s_and_b32 s2, s2, 0xfc
	s_add_i32 s2, s2, 0x20040
	v_mov_b32_e32 v0, s2
	ds_read_b32 v0, v0
	v_mov_b32_e32 v131, v65
	s_waitcnt lgkmcnt(0)
	v_readfirstlane_b32 s2, v0
	s_nop 1
	v_lshl_or_b32 v140, s2, 6, v214
	s_nop 0
	v_bfe_i32 v2, v140, 27, 1
	v_lshlrev_b32_e32 v0, 4, v140
	v_lshrrev_b32_e32 v2, 22, v2
	v_add_u32_e32 v2, v0, v2
	v_and_b32_e32 v2, 0xfffffc00, v2
	v_sub_u32_e32 v2, v0, v2
	v_ashrrev_i32_e32 v1, 31, v140
	v_lshrrev_b32_e32 v3, 4, v2
	v_lshrrev_b32_e32 v1, 26, v1
	v_bitop3_b32 v3, v3, v2, 32 bitop3:0x6c
	v_ashrrev_i32_e32 v2, 31, v2
	v_add_u32_e32 v1, v140, v1
	v_lshrrev_b32_e32 v2, 26, v2
	v_ashrrev_i32_e32 v1, 6, v1
	v_add_u32_e32 v2, v3, v2
	v_lshlrev_b32_e32 v4, 3, v1
	v_ashrrev_i32_e32 v2, 6, v2
	v_lshlrev_b32_e32 v1, 5, v1
	v_and_b32_e32 v13, 32, v1
	v_mul_i32_i24_e32 v1, 64, v2
	v_sub_u32_e32 v1, v3, v1
	v_add_u32_e32 v3, 0x2000, v0
	v_ashrrev_i32_e32 v5, 31, v3
	v_lshrrev_b32_e32 v5, 22, v5
	v_add_u32_e32 v5, v3, v5
	v_ashrrev_i32_e32 v12, 10, v5
	v_mul_i32_i24_e32 v5, 0x400, v12
	v_sub_u32_e32 v3, v3, v5
	v_lshrrev_b32_e32 v5, 4, v3
	v_bitop3_b32 v3, v5, v3, 32 bitop3:0x6c
	v_ashrrev_i32_e32 v6, 31, v3
	v_lshrrev_b32_e32 v6, 26, v6
	v_and_b32_e32 v4, -16, v4
	v_ashrrev_i16_sdwa v14, v215, sext(v1) dst_sel:DWORD dst_unused:UNUSED_PAD src0_sel:DWORD src1_sel:BYTE_0
	v_lshlrev_b32_e32 v5, 3, v12
	v_add_u32_e32 v6, v3, v6
	v_add_u32_e32 v4, v2, v4
	v_add_u32_sdwa v1, v13, sext(v14) dst_sel:DWORD dst_unused:UNUSED_PAD src0_sel:DWORD src1_sel:WORD_0
	v_and_b32_e32 v5, -16, v5
	v_ashrrev_i32_e32 v15, 6, v6
	v_and_b32_e32 v6, 0xc0, v6
	v_add_u32_e32 v5, v15, v5
	v_sub_u32_e32 v3, v3, v6
	v_lshl_add_u32 v8, v4, 10, v1
	v_and_b32_e32 v18, 0xffffffe0, v4
	v_lshlrev_b32_e32 v6, 1, v4
	v_lshrrev_b32_e32 v4, 2, v4
	v_and_b32_e32 v21, 4, v4
	v_and_b32_e32 v23, 3, v2
	v_lshlrev_b32_e32 v4, 1, v5
	v_lshlrev_b32_e32 v7, 5, v12
	v_and_b32_e32 v20, 24, v6
	v_or_b32_e32 v2, v18, v23
	v_and_b32_e32 v19, 0xffffffe0, v5
	v_and_b32_e32 v22, 24, v4
	v_lshrrev_b32_e32 v4, 2, v5
	v_and_b32_e32 v25, 3, v15
	v_and_b32_e32 v16, 32, v7
	v_ashrrev_i16_sdwa v17, v215, sext(v3) dst_sel:DWORD dst_unused:UNUSED_PAD src0_sel:DWORD src1_sel:BYTE_0
	v_or3_b32 v2, v2, v20, v21
	v_and_b32_e32 v24, 4, v4
	v_or_b32_e32 v4, v19, v25
	v_add_u32_e32 v149, 0, v0
	v_add_u32_sdwa v3, v16, sext(v17) dst_sel:DWORD dst_unused:UNUSED_PAD src0_sel:DWORD src1_sel:WORD_0
	v_or3_b32 v4, v4, v22, v24
	v_lshl_add_u32 v64, v2, 10, v1
	v_add_u32_e32 v150, 0x10000, v149
	v_lshl_add_u32 v130, v5, 10, v3
	v_lshl_add_u32 v2, v4, 10, v3
	v_lshlrev_b64 v[6:7], 1, v[64:65]
	v_readfirstlane_b32 s2, v150
	v_mov_b32_e32 v3, v65
	v_add_u32_e32 v152, 0x12000, v149
	v_lshl_add_u64 v[0:1], s[36:37], 0, v[6:7]
	s_mov_b32 m0, s2
	v_lshlrev_b64 v[26:27], 1, v[2:3]
	v_readfirstlane_b32 s2, v152
	v_mov_b32_e32 v64, v8
	global_load_lds_dwordx4 v[0:1], off
	v_lshl_add_u64 v[2:3], s[36:37], 0, v[26:27]
	s_mov_b32 m0, s2
	v_lshlrev_b64 v[28:29], 1, v[64:65]
	v_readfirstlane_b32 s2, v149
	v_add_u32_e32 v153, 0x2000, v149
	global_load_lds_dwordx4 v[2:3], off
	v_lshl_add_u64 v[4:5], s[8:9], 0, v[28:29]
	s_mov_b32 m0, s2
	v_lshlrev_b64 v[30:31], 1, v[130:131]
	v_readfirstlane_b32 s2, v153
	v_add_u32_e32 v154, 0x14000, v149
	global_load_lds_dwordx4 v[4:5], off
	v_lshl_add_u64 v[8:9], s[8:9], 0, v[30:31]
	s_mov_b32 m0, s2
	v_readfirstlane_b32 s2, v154
	v_add_u32_e32 v155, 0x16000, v149
	global_load_lds_dwordx4 v[8:9], off
	v_lshl_add_u64 v[10:11], s[22:23], 0, v[6:7]
	s_mov_b32 m0, s2
	v_readfirstlane_b32 s2, v155
	global_load_lds_dwordx4 v[10:11], off
	s_mov_b32 m0, s2
	s_add_u32 s2, s8, 0x40000
	v_add_u32_e32 v157, 0x4000, v149
	v_lshl_add_u64 v[6:7], s[22:23], 0, v[26:27]
	s_addc_u32 s3, s9, 0
	v_readfirstlane_b32 s7, v157
	global_load_lds_dwordx4 v[6:7], off
	v_lshl_add_u64 v[26:27], s[2:3], 0, v[28:29]
	s_mov_b32 m0, s7
	v_add_u32_e32 v158, 0x6000, v149
	global_load_lds_dwordx4 v[26:27], off
	v_lshl_add_u64 v[26:27], s[2:3], 0, v[30:31]
	v_readfirstlane_b32 s2, v158
	s_mov_b32 m0, s2
	s_nop 0
	global_load_lds_dwordx4 v[26:27], off
	v_ashrrev_i32_e32 v26, 8, v140
	v_cmp_eq_u32_e32 vcc, 1, v26
	s_and_saveexec_b64 s[22:23], vcc
	s_cbranch_execz .LBB0_563
	s_barrier

; DI int my_tid() { int t = tid_raw(); asm volatile("" : "+v"(t)); return t; }
; #define STAGE_A(b, h, kt) { const u16* ap_ = A + (size_t)((h) * ahalf + (unsigned)(kt) * 64u); glds16(ap_ + ao0, l0 + SA_(b, h)); glds16(ap_ + ao1, l0 + SA_(b, h) + 8192); }
; #define STAGE_B(b, h, kt) { const u16* bp_ = ((h) ? B1 : B0) + (unsigned)(kt) * 64u; glds16(bp_ + bo0, l0 + SB_(b, h)); glds16(bp_ + bo1, l0 + SB_(b, h) + 8192); }
; #define WAIT_V(n) asm volatile("s_waitcnt vmcnt(" #n ")" ::: "memory");
; #define BAR __builtin_amdgcn_s_barrier();
; DI void gemm256(const u16* __restrict__ A, int lda, const u16* __restrict__ B0, const u16* __restrict__ B1, int ldb, int nt, acc_t& acc, char* lds) {
;   const int tid = my_tid();
;   const int lane = tid & 63, wid = tid >> 6, wr = wid >> 2, wc = wid & 3, fr = lane & 15, fq = lane >> 4;
;   int r0, c0, r1, c1;
;   stage_rc(tid * 16, r0, c0); stage_rc(tid * 16 + 8192, r1, c1);
;   const unsigned ao0 = (unsigned)(r0 * lda + c0), ao1 = (unsigned)(r1 * lda + c1);
;   const unsigned ahalf = 128u * (unsigned)lda;
;   const int p0 = (r0 & ~31) + (((r0 & 15) >> 2) * 8) + (((r0 >> 4) & 1) * 4) + (r0 & 3), p1 = (r1 & ~31) + (((r1 & 15) >> 2) * 8) + (((r1 >> 4) & 1) * 4) + (r1 & 3);
;   const unsigned bo0 = (unsigned)(p0 * ldb + c0), bo1 = (unsigned)(p1 * ldb + c1);
;   char* l0 = lds + tid * 16;
;     ...
;   bf16x8 At[4][2], Bq0[2][2], Bq1[2][2];
;   WAIT_V(0)
;   STAGE_B(0, 0, 0) STAGE_A(0, 0, 0) STAGE_B(0, 1, 0) STAGE_A(0, 1, 0)
;   if (wr == 1) BAR
.LBB0_970:
	s_ashr_i32 s2, s36, 31
	s_lshr_b32 s2, s2, 29
	s_add_i32 s2, s36, s2
	s_ashr_i32 s3, s2, 3
	s_and_b32 s2, s2, -8
	s_sub_i32 s2, s36, s2
	s_lshr_b32 s7, s2, 31
	s_or_b32 s7, s7, 32
	s_mul_i32 s7, s7, s2
	s_add_i32 s7, s7, s3
	s_ashr_i32 s2, s7, 31
	s_lshr_b32 s2, s2, 27
	s_add_i32 s2, s7, s2
	s_ashr_i32 s19, s2, 5
	s_lshl_b32 s8, s19, 3
	s_sub_i32 s3, 64, s8
	s_andn2_b32 s2, s2, 31
	s_min_u32 s9, s3, 8
	s_sub_i32 s22, s7, s2
	s_sext_i32_i8 s2, s22
	v_cvt_f32_ubyte0_e32 v1, s9
	v_cvt_f32_i32_e32 v0, s2
	v_rcp_iflag_f32_e32 v2, v1
	s_ashr_i32 s3, s2, 30
	s_or_b32 s23, s3, 1
	v_mov_b32_e32 v131, v65
	v_mul_f32_e32 v2, v0, v2
	v_trunc_f32_e32 v2, v2
	v_fma_f32 v0, -v2, v1, v0
	v_cvt_i32_f32_e32 v2, v2
	v_cmp_ge_f32_e64 s[2:3], |v0|, v1
	s_and_b64 s[2:3], s[2:3], exec
	s_cselect_b32 s2, s23, 0
	v_readfirstlane_b32 s3, v2
	s_add_i32 s28, s3, s2
	s_sext_i32_i8 s3, s28
	s_mul_i32 s28, s28, s9
	s_sub_i32 s2, s22, s28
	s_sext_i32_i8 s2, s2
	s_add_i32 s8, s8, s2
	s_lshl_b32 s40, s8, 8
	s_ashr_i32 s41, s40, 31
	s_lshl_b32 s38, s3, 8
	s_lshl_b64 s[42:43], s[40:41], 11
	v_readlane_b32 s8, v254, 22
	v_readlane_b32 s9, v254, 23
	s_add_u32 s50, s8, s42
	s_addc_u32 s51, s9, s43
	s_ashr_i32 s39, s38, 31
	s_lshl_b64 s[46:47], s[38:39], 11
	s_add_u32 s3, s90, s46
	s_addc_u32 s9, s91, s47
	s_add_u32 s22, s3, 0x700000
	s_addc_u32 s23, s9, 0
	s_add_u32 s8, s3, 0x740000
	s_getreg_b32 s3, hwreg(HW_REG_HW_ID, 0, 6)
	s_addc_u32 s9, s9, 0
	s_lshl_b32 s3, s3, 2
	s_and_b32 s3, s3, 0xfc
	s_add_i32 s3, s3, 0x20040
	v_mov_b32_e32 v0, s3
	ds_read_b32 v0, v0
	s_add_u32 s52, s50, 0x40000
	s_addc_u32 s53, s51, 0
	s_waitcnt lgkmcnt(0)
	v_readfirstlane_b32 s3, v0
	s_nop 1
	v_lshl_or_b32 v140, s3, 6, v214
	s_nop 0
	v_bfe_i32 v2, v140, 27, 1
	v_lshlrev_b32_e32 v0, 4, v140
	v_lshrrev_b32_e32 v2, 22, v2
	v_add_u32_e32 v2, v0, v2
	v_and_b32_e32 v2, 0xfffffc00, v2
	v_sub_u32_e32 v2, v0, v2
	v_ashrrev_i32_e32 v1, 31, v140
	v_lshrrev_b32_e32 v3, 4, v2
	v_lshrrev_b32_e32 v1, 26, v1
	v_bitop3_b32 v3, v3, v2, 32 bitop3:0x6c
	v_ashrrev_i32_e32 v2, 31, v2
	v_add_u32_e32 v1, v140, v1
	v_lshrrev_b32_e32 v2, 26, v2
	v_ashrrev_i32_e32 v1, 6, v1
	v_add_u32_e32 v2, v3, v2
	v_lshlrev_b32_e32 v4, 3, v1
	v_ashrrev_i32_e32 v2, 6, v2
	v_lshlrev_b32_e32 v1, 5, v1
	v_and_b32_e32 v17, 32, v1
	v_mul_i32_i24_e32 v1, 64, v2
	v_sub_u32_e32 v1, v3, v1
	v_add_u32_e32 v3, 0x2000, v0
	v_ashrrev_i32_e32 v5, 31, v3
	v_lshrrev_b32_e32 v5, 22, v5
	v_add_u32_e32 v5, v3, v5
	v_ashrrev_i32_e32 v13, 10, v5
	v_mul_i32_i24_e32 v5, 0x400, v13
	v_sub_u32_e32 v3, v3, v5
	v_lshrrev_b32_e32 v5, 4, v3
	v_bitop3_b32 v3, v5, v3, 32 bitop3:0x6c
	v_ashrrev_i32_e32 v6, 31, v3
	v_lshrrev_b32_e32 v6, 26, v6
	v_and_b32_e32 v4, -16, v4
	v_ashrrev_i16_sdwa v18, v215, sext(v1) dst_sel:DWORD dst_unused:UNUSED_PAD src0_sel:DWORD src1_sel:BYTE_0
	v_lshlrev_b32_e32 v5, 3, v13
	v_add_u32_e32 v6, v3, v6
	v_add_u32_e32 v4, v2, v4
	v_add_u32_sdwa v1, v17, sext(v18) dst_sel:DWORD dst_unused:UNUSED_PAD src0_sel:DWORD src1_sel:WORD_0
	v_and_b32_e32 v5, -16, v5
	v_ashrrev_i32_e32 v14, 6, v6
	v_and_b32_e32 v6, 0xc0, v6
	v_add_u32_e32 v5, v14, v5
	v_sub_u32_e32 v3, v3, v6
	v_lshl_add_u32 v8, v4, 10, v1
	v_and_b32_e32 v19, 0xffffffe0, v4
	v_lshlrev_b32_e32 v6, 1, v4
	v_lshrrev_b32_e32 v4, 2, v4
	v_and_b32_e32 v22, 4, v4
	v_and_b32_e32 v24, 3, v2
	v_lshlrev_b32_e32 v4, 1, v5
	v_lshlrev_b32_e32 v7, 5, v13
	v_and_b32_e32 v21, 24, v6
	v_or_b32_e32 v2, v19, v24
	v_and_b32_e32 v20, 0xffffffe0, v5
	v_and_b32_e32 v23, 24, v4
	v_lshrrev_b32_e32 v4, 2, v5
	v_and_b32_e32 v26, 3, v14
	v_and_b32_e32 v15, 32, v7
	v_ashrrev_i16_sdwa v16, v215, sext(v3) dst_sel:DWORD dst_unused:UNUSED_PAD src0_sel:DWORD src1_sel:BYTE_0
	v_or3_b32 v2, v2, v21, v22
	v_and_b32_e32 v25, 4, v4
	v_or_b32_e32 v4, v20, v26
	v_add_u32_e32 v149, 0, v0
	v_add_u32_sdwa v3, v15, sext(v16) dst_sel:DWORD dst_unused:UNUSED_PAD src0_sel:DWORD src1_sel:WORD_0
	v_or3_b32 v4, v4, v23, v25
	v_lshl_add_u32 v64, v2, 10, v1
	v_add_u32_e32 v150, 0x10000, v149
	v_lshl_add_u32 v130, v5, 10, v3
	v_lshl_add_u32 v2, v4, 10, v3
	v_lshlrev_b64 v[6:7], 1, v[64:65]
	v_readfirstlane_b32 s3, v150
	v_mov_b32_e32 v3, v65
	v_add_u32_e32 v151, 0x12000, v149
	v_lshl_add_u64 v[0:1], s[22:23], 0, v[6:7]
	s_mov_b32 m0, s3
	v_lshlrev_b64 v[28:29], 1, v[2:3]
	v_readfirstlane_b32 s3, v151
	v_mov_b32_e32 v64, v8
	global_load_lds_dwordx4 v[0:1], off
	v_lshl_add_u64 v[2:3], s[22:23], 0, v[28:29]
	s_mov_b32 m0, s3
	v_lshlrev_b64 v[30:31], 1, v[64:65]
	v_readfirstlane_b32 s3, v149
	v_add_u32_e32 v153, 0x2000, v149
	global_load_lds_dwordx4 v[2:3], off
	v_lshl_add_u64 v[4:5], s[50:51], 0, v[30:31]
	s_mov_b32 m0, s3
	v_lshlrev_b64 v[32:33], 1, v[130:131]
	v_readfirstlane_b32 s3, v153
	v_add_u32_e32 v154, 0x14000, v149
	global_load_lds_dwordx4 v[4:5], off
	v_lshl_add_u64 v[8:9], s[50:51], 0, v[32:33]
	s_mov_b32 m0, s3
	v_readfirstlane_b32 s3, v154
	v_add_u32_e32 v155, 0x16000, v149
	global_load_lds_dwordx4 v[8:9], off
	v_lshl_add_u64 v[10:11], s[8:9], 0, v[6:7]
	s_mov_b32 m0, s3
	v_readfirstlane_b32 s3, v155
	v_add_u32_e32 v157, 0x4000, v149
	global_load_lds_dwordx4 v[10:11], off
	v_lshl_add_u64 v[6:7], s[8:9], 0, v[28:29]
	s_mov_b32 m0, s3
	v_readfirstlane_b32 s3, v157
	v_add_u32_e32 v158, 0x6000, v149
	global_load_lds_dwordx4 v[6:7], off
	v_lshl_add_u64 v[28:29], s[52:53], 0, v[30:31]
	s_mov_b32 m0, s3
	v_readfirstlane_b32 s3, v158
	global_load_lds_dwordx4 v[28:29], off
	v_lshl_add_u64 v[28:29], s[52:53], 0, v[32:33]
	s_mov_b32 m0, s3
	v_ashrrev_i32_e32 v12, 8, v140
	global_load_lds_dwordx4 v[28:29], off
	v_cmp_eq_u32_e32 vcc, 1, v12
	s_and_saveexec_b64 s[8:9], vcc
	s_cbranch_execz .LBB0_972
	s_barrier

; DI unsigned pk_bf16(float lo, float hi) { f32x2_t v = {lo, hi}; return __builtin_bit_cast(unsigned, __builtin_convertvector(v, bf16x2_t)); }
; DI float fsigmoid(float x) { return __builtin_amdgcn_rcpf(1.0f + __expf(-x)); }
; #define EPI_M _Pragma("unroll") for (int m = 0; m < 8; ++m)
; #define EPI_N _Pragma("unroll") for (int n = 0; n < 4; ++n)
; DI void p5_phase(const Params& p, char* lds) {
;     ...
;     EPI_IDX_N
;     EPI_M {
;       EPI_N {
;         u32x2 o; o[0] = pk_bf16(fsigmoid(ACC(m, n)[0]), fsigmoid(ACC(m, n)[1])); o[1] = pk_bf16(fsigmoid(ACC(m, n)[2]), fsigmoid(ACC(m, n)[3]));
;         tg[(m * 4 + n) * 512 + tid] = o;
;       }
;       __builtin_amdgcn_sched_barrier(0);
;     }
.LBB0_976:
	s_or_b64 exec, exec, s[22:23]
	s_waitcnt vmcnt(0)
	s_barrier
	s_getreg_b32 s7, hwreg(HW_REG_HW_ID, 0, 6)
	s_lshl_b32 s7, s7, 2
	s_and_b32 s7, s7, 0xfc
	s_add_i32 s7, s7, 0x20040
	v_mov_b32_e32 v64, s7
	ds_read_b32 v64, v64
	v_mul_f32_e32 v126, 0xbfb8aa3b, v126
	v_mul_f32_e32 v127, 0xbfb8aa3b, v127
	v_exp_f32_e32 v126, v126
	v_exp_f32_e32 v127, v127
	s_waitcnt lgkmcnt(0)
	v_readfirstlane_b32 s7, v64
	v_add_f32_e32 v64, 1.0, v126
	v_add_f32_e32 v126, 1.0, v127
	v_mul_f32_e32 v127, 0xbfb8aa3b, v128
	v_exp_f32_e32 v127, v127
	v_mul_f32_e32 v128, 0xbfb8aa3b, v129
	v_rcp_f32_e32 v64, v64
	v_exp_f32_e32 v128, v128
	v_rcp_f32_e32 v129, v126
	v_add_f32_e32 v126, 1.0, v127
	v_rcp_f32_e32 v127, v126
	v_add_f32_e32 v126, 1.0, v128
	v_cvt_pk_bf16_f32 v128, v64, v129
	v_mul_f32_e32 v64, 0xbfb8aa3b, v122
	v_mul_f32_e32 v122, 0xbfb8aa3b, v123
	v_exp_f32_e32 v64, v64
	v_exp_f32_e32 v122, v122
	v_mul_f32_e32 v123, 0xbfb8aa3b, v124
	v_exp_f32_e32 v123, v123
	v_mul_f32_e32 v124, 0xbfb8aa3b, v125
	v_rcp_f32_e32 v130, v126
	v_exp_f32_e32 v124, v124
	v_add_f32_e32 v64, 1.0, v64
	v_add_f32_e32 v122, 1.0, v122
	v_rcp_f32_e32 v64, v64
	v_rcp_f32_e32 v125, v122
	v_lshl_or_b32 v126, s7, 6, v214
	v_add_f32_e32 v122, 1.0, v123
	v_cvt_pk_bf16_f32 v129, v127, v130
	v_ashrrev_i32_e32 v127, 31, v126
	v_rcp_f32_e32 v130, v122
	v_add_f32_e32 v122, 1.0, v124
	v_rcp_f32_e32 v124, v122
	v_lshl_add_u64 v[122:123], v[126:127], 3, s[10:11]
	global_store_dwordx2 v[122:123], v[128:129], off
	v_cvt_pk_bf16_f32 v122, v64, v125
	v_mul_f32_e32 v64, 0xbfb8aa3b, v118
	v_mul_f32_e32 v118, 0xbfb8aa3b, v119
	v_exp_f32_e32 v64, v64
	v_exp_f32_e32 v118, v118
	v_mul_f32_e32 v119, 0xbfb8aa3b, v120
	v_exp_f32_e32 v119, v119
	v_mul_f32_e32 v120, 0xbfb8aa3b, v121
	v_exp_f32_e32 v120, v120
	v_add_f32_e32 v64, 1.0, v64
	v_add_f32_e32 v118, 1.0, v118
	v_rcp_f32_e32 v64, v64
	v_rcp_f32_e32 v121, v118
	v_cvt_pk_bf16_f32 v123, v130, v124
	v_add_u32_e32 v124, 0x200, v126
	v_add_f32_e32 v118, 1.0, v119
	v_ashrrev_i32_e32 v125, 31, v124
	v_rcp_f32_e32 v127, v118
	v_add_f32_e32 v118, 1.0, v120
	v_rcp_f32_e32 v120, v118
	v_lshl_add_u64 v[118:119], v[124:125], 3, s[10:11]
	global_store_dwordx2 v[118:119], v[122:123], off
	v_cvt_pk_bf16_f32 v118, v64, v121
	v_mul_f32_e32 v64, 0xbfb8aa3b, v114
	v_mul_f32_e32 v114, 0xbfb8aa3b, v115
	v_exp_f32_e32 v114, v114
	v_mul_f32_e32 v115, 0xbfb8aa3b, v116
	v_exp_f32_e32 v115, v115
	v_mul_f32_e32 v116, 0xbfb8aa3b, v117
	v_exp_f32_e32 v116, v116
	v_exp_f32_e32 v64, v64
	v_add_f32_e32 v114, 1.0, v114
	v_rcp_f32_e32 v117, v114
	v_add_f32_e32 v114, 1.0, v115
	v_rcp_f32_e32 v122, v114
	v_add_f32_e32 v114, 1.0, v116
	v_add_f32_e32 v64, 1.0, v64
	v_rcp_f32_e32 v116, v114
	v_cvt_pk_bf16_f32 v119, v127, v120
	v_add_u32_e32 v120, 0x400, v126
	v_rcp_f32_e32 v64, v64
	v_ashrrev_i32_e32 v121, 31, v120
	v_lshl_add_u64 v[114:115], v[120:121], 3, s[10:11]
	global_store_dwordx2 v[114:115], v[118:119], off
	v_cvt_pk_bf16_f32 v115, v122, v116
	v_add_u32_e32 v116, 0x600, v126
	v_cvt_pk_bf16_f32 v114, v64, v117
	v_ashrrev_i32_e32 v117, 31, v116
	v_lshl_add_u64 v[116:117], v[116:117], 3, s[10:11]
	global_store_dwordx2 v[116:117], v[114:115], off
	v_mul_f32_e32 v64, 0xbfb8aa3b, v110
	v_mul_f32_e32 v110, 0xbfb8aa3b, v111
	v_exp_f32_e32 v64, v64
	v_exp_f32_e32 v110, v110
	v_mul_f32_e32 v111, 0xbfb8aa3b, v112
	v_exp_f32_e32 v111, v111
	v_add_f32_e32 v64, 1.0, v64
	v_add_f32_e32 v110, 1.0, v110
	v_mul_f32_e32 v112, 0xbfb8aa3b, v113
	v_rcp_f32_e32 v64, v64
	v_exp_f32_e32 v112, v112
	v_rcp_f32_e32 v113, v110
	v_add_f32_e32 v110, 1.0, v111
	v_rcp_f32_e32 v111, v110
	v_add_f32_e32 v110, 1.0, v112
	v_cvt_pk_bf16_f32 v112, v64, v113
	v_mul_f32_e32 v64, 0xbfb8aa3b, v106
	v_mul_f32_e32 v106, 0xbfb8aa3b, v107
	v_exp_f32_e32 v64, v64
	v_exp_f32_e32 v106, v106
	v_mul_f32_e32 v107, 0xbfb8aa3b, v108
	v_exp_f32_e32 v107, v107
	v_mul_f32_e32 v108, 0xbfb8aa3b, v109
	v_rcp_f32_e32 v114, v110
	v_exp_f32_e32 v108, v108
	v_add_f32_e32 v64, 1.0, v64
	v_add_f32_e32 v106, 1.0, v106
	v_rcp_f32_e32 v64, v64
	v_rcp_f32_e32 v109, v106
	v_add_u32_e32 v110, 0x800, v126
	v_add_f32_e32 v106, 1.0, v107
	v_cvt_pk_bf16_f32 v113, v111, v114
	v_ashrrev_i32_e32 v111, 31, v110
	v_rcp_f32_e32 v114, v106
	v_add_f32_e32 v106, 1.0, v108
	v_rcp_f32_e32 v108, v106
	v_lshl_add_u64 v[106:107], v[110:111], 3, s[10:11]
	global_store_dwordx2 v[106:107], v[112:113], off
	v_cvt_pk_bf16_f32 v106, v64, v109
	v_mul_f32_e32 v64, 0xbfb8aa3b, v102
	v_mul_f32_e32 v102, 0xbfb8aa3b, v103
	v_exp_f32_e32 v64, v64
	v_exp_f32_e32 v102, v102
	v_mul_f32_e32 v103, 0xbfb8aa3b, v104
	v_exp_f32_e32 v103, v103
	v_mul_f32_e32 v104, 0xbfb8aa3b, v105
	v_exp_f32_e32 v104, v104
	v_add_f32_e32 v64, 1.0, v64
	v_add_f32_e32 v102, 1.0, v102
	v_rcp_f32_e32 v64, v64
	v_rcp_f32_e32 v105, v102
	v_cvt_pk_bf16_f32 v107, v114, v108
	v_add_u32_e32 v108, 0xa00, v126
	v_add_f32_e32 v102, 1.0, v103
	v_ashrrev_i32_e32 v109, 31, v108
	v_rcp_f32_e32 v110, v102
	v_add_f32_e32 v102, 1.0, v104
	v_rcp_f32_e32 v104, v102
	v_lshl_add_u64 v[102:103], v[108:109], 3, s[10:11]
	global_store_dwordx2 v[102:103], v[106:107], off
	v_cvt_pk_bf16_f32 v102, v64, v105
	v_mul_f32_e32 v64, 0xbfb8aa3b, v98
	v_mul_f32_e32 v98, 0xbfb8aa3b, v99
	v_exp_f32_e32 v98, v98
	v_mul_f32_e32 v99, 0xbfb8aa3b, v100
	v_exp_f32_e32 v99, v99
	v_mul_f32_e32 v100, 0xbfb8aa3b, v101
	v_exp_f32_e32 v100, v100
	v_exp_f32_e32 v64, v64
	v_add_f32_e32 v98, 1.0, v98
	v_rcp_f32_e32 v101, v98
	v_add_f32_e32 v98, 1.0, v99
	v_rcp_f32_e32 v106, v98
	v_add_f32_e32 v98, 1.0, v100
	v_add_f32_e32 v64, 1.0, v64
	v_rcp_f32_e32 v100, v98
	v_cvt_pk_bf16_f32 v103, v110, v104
	v_add_u32_e32 v104, 0xc00, v126
	v_rcp_f32_e32 v64, v64
; DI unsigned pk_bf16(float lo, float hi) { f32x2_t v = {lo, hi}; return __builtin_bit_cast(unsigned, __builtin_convertvector(v, bf16x2_t)); }
; DI float fsigmoid(float x) { return __builtin_amdgcn_rcpf(1.0f + __expf(-x)); }
; #define EPI_M _Pragma("unroll") for (int m = 0; m < 8; ++m)
; #define EPI_N _Pragma("unroll") for (int n = 0; n < 4; ++n)
; DI void p5_phase(const Params& p, char* lds) {
;     ...
;     EPI_M {
;       EPI_N {
;         u32x2 o; o[0] = pk_bf16(fsigmoid(ACC(m, n)[0]), fsigmoid(ACC(m, n)[1])); o[1] = pk_bf16(fsigmoid(ACC(m, n)[2]), fsigmoid(ACC(m, n)[3]));
;         tg[(m * 4 + n) * 512 + tid] = o;
;       }
;       __builtin_amdgcn_sched_barrier(0);
;     }
	v_ashrrev_i32_e32 v105, 31, v104
	v_lshl_add_u64 v[98:99], v[104:105], 3, s[10:11]
	global_store_dwordx2 v[98:99], v[102:103], off
	v_cvt_pk_bf16_f32 v99, v106, v100
	v_add_u32_e32 v100, 0xe00, v126
	v_cvt_pk_bf16_f32 v98, v64, v101
	v_ashrrev_i32_e32 v101, 31, v100
	v_lshl_add_u64 v[100:101], v[100:101], 3, s[10:11]
	global_store_dwordx2 v[100:101], v[98:99], off
	v_mul_f32_e32 v64, 0xbfb8aa3b, v94
	v_mul_f32_e32 v94, 0xbfb8aa3b, v95
	v_exp_f32_e32 v64, v64
	v_exp_f32_e32 v94, v94
	v_mul_f32_e32 v95, 0xbfb8aa3b, v96
	v_exp_f32_e32 v95, v95
	v_add_f32_e32 v64, 1.0, v64
	v_add_f32_e32 v94, 1.0, v94
	v_mul_f32_e32 v96, 0xbfb8aa3b, v97
	v_rcp_f32_e32 v64, v64
	v_exp_f32_e32 v96, v96
	v_rcp_f32_e32 v97, v94
	v_add_f32_e32 v94, 1.0, v95
	v_rcp_f32_e32 v95, v94
	v_add_f32_e32 v94, 1.0, v96
	v_cvt_pk_bf16_f32 v96, v64, v97
	v_mul_f32_e32 v64, 0xbfb8aa3b, v90
	v_mul_f32_e32 v90, 0xbfb8aa3b, v91
	v_exp_f32_e32 v64, v64
	v_exp_f32_e32 v90, v90
	v_mul_f32_e32 v91, 0xbfb8aa3b, v92
	v_exp_f32_e32 v91, v91
	v_mul_f32_e32 v92, 0xbfb8aa3b, v93
	v_rcp_f32_e32 v98, v94
	v_exp_f32_e32 v92, v92
	v_add_f32_e32 v64, 1.0, v64
	v_add_f32_e32 v90, 1.0, v90
	v_rcp_f32_e32 v64, v64
	v_rcp_f32_e32 v93, v90
	v_add_u32_e32 v94, 0x1000, v126
	v_add_f32_e32 v90, 1.0, v91
	v_cvt_pk_bf16_f32 v97, v95, v98
	v_ashrrev_i32_e32 v95, 31, v94
	v_rcp_f32_e32 v98, v90
	v_add_f32_e32 v90, 1.0, v92
	v_rcp_f32_e32 v92, v90
	v_lshl_add_u64 v[90:91], v[94:95], 3, s[10:11]
	global_store_dwordx2 v[90:91], v[96:97], off
	v_cvt_pk_bf16_f32 v90, v64, v93
	v_mul_f32_e32 v64, 0xbfb8aa3b, v86
	v_mul_f32_e32 v86, 0xbfb8aa3b, v87
	v_exp_f32_e32 v64, v64
	v_exp_f32_e32 v86, v86
	v_mul_f32_e32 v87, 0xbfb8aa3b, v88
	v_exp_f32_e32 v87, v87
	v_mul_f32_e32 v88, 0xbfb8aa3b, v89
	v_exp_f32_e32 v88, v88
	v_add_f32_e32 v64, 1.0, v64
	v_add_f32_e32 v86, 1.0, v86
	v_rcp_f32_e32 v64, v64
	v_rcp_f32_e32 v89, v86
	v_cvt_pk_bf16_f32 v91, v98, v92
	v_add_u32_e32 v92, 0x1200, v126
	v_add_f32_e32 v86, 1.0, v87
	v_ashrrev_i32_e32 v93, 31, v92
	v_rcp_f32_e32 v94, v86
	v_add_f32_e32 v86, 1.0, v88
	v_rcp_f32_e32 v88, v86
	v_lshl_add_u64 v[86:87], v[92:93], 3, s[10:11]
	global_store_dwordx2 v[86:87], v[90:91], off
	v_cvt_pk_bf16_f32 v86, v64, v89
	v_mul_f32_e32 v64, 0xbfb8aa3b, v82
	v_mul_f32_e32 v82, 0xbfb8aa3b, v83
	v_exp_f32_e32 v82, v82
	v_mul_f32_e32 v83, 0xbfb8aa3b, v84
	v_exp_f32_e32 v83, v83
	v_mul_f32_e32 v84, 0xbfb8aa3b, v85
	v_exp_f32_e32 v84, v84
	v_exp_f32_e32 v64, v64
	v_add_f32_e32 v82, 1.0, v82
	v_rcp_f32_e32 v85, v82
	v_add_f32_e32 v82, 1.0, v83
	v_rcp_f32_e32 v90, v82
	v_add_f32_e32 v82, 1.0, v84
	v_add_f32_e32 v64, 1.0, v64
	v_rcp_f32_e32 v84, v82
	v_cvt_pk_bf16_f32 v87, v94, v88
	v_add_u32_e32 v88, 0x1400, v126
	v_rcp_f32_e32 v64, v64
	v_ashrrev_i32_e32 v89, 31, v88
	v_lshl_add_u64 v[82:83], v[88:89], 3, s[10:11]
	global_store_dwordx2 v[82:83], v[86:87], off
	v_cvt_pk_bf16_f32 v83, v90, v84
	v_add_u32_e32 v84, 0x1600, v126
	v_cvt_pk_bf16_f32 v82, v64, v85
	v_ashrrev_i32_e32 v85, 31, v84
	v_lshl_add_u64 v[84:85], v[84:85], 3, s[10:11]
	global_store_dwordx2 v[84:85], v[82:83], off
	v_mul_f32_e32 v64, 0xbfb8aa3b, v78
	v_mul_f32_e32 v78, 0xbfb8aa3b, v79
	v_exp_f32_e32 v64, v64
	v_exp_f32_e32 v78, v78
	v_mul_f32_e32 v79, 0xbfb8aa3b, v80
	v_exp_f32_e32 v79, v79
	v_add_f32_e32 v64, 1.0, v64
	v_add_f32_e32 v78, 1.0, v78
	v_mul_f32_e32 v80, 0xbfb8aa3b, v81
	v_rcp_f32_e32 v64, v64
	v_exp_f32_e32 v80, v80
	v_rcp_f32_e32 v81, v78
	v_add_f32_e32 v78, 1.0, v79
	v_rcp_f32_e32 v79, v78
	v_add_f32_e32 v78, 1.0, v80
	v_cvt_pk_bf16_f32 v80, v64, v81
	v_mul_f32_e32 v64, 0xbfb8aa3b, v74
	v_mul_f32_e32 v74, 0xbfb8aa3b, v75
	v_exp_f32_e32 v64, v64
	v_exp_f32_e32 v74, v74
	v_mul_f32_e32 v75, 0xbfb8aa3b, v76
	v_exp_f32_e32 v75, v75
	v_mul_f32_e32 v76, 0xbfb8aa3b, v77
	v_rcp_f32_e32 v82, v78
	v_exp_f32_e32 v76, v76
	v_add_f32_e32 v64, 1.0, v64
	v_add_f32_e32 v74, 1.0, v74
	v_rcp_f32_e32 v64, v64
	v_rcp_f32_e32 v77, v74
	v_add_u32_e32 v78, 0x1800, v126
	v_add_f32_e32 v74, 1.0, v75
	v_cvt_pk_bf16_f32 v81, v79, v82
	v_ashrrev_i32_e32 v79, 31, v78
	v_rcp_f32_e32 v82, v74
	v_add_f32_e32 v74, 1.0, v76
	v_rcp_f32_e32 v76, v74
	v_lshl_add_u64 v[74:75], v[78:79], 3, s[10:11]
	global_store_dwordx2 v[74:75], v[80:81], off
	v_cvt_pk_bf16_f32 v74, v64, v77
	v_mul_f32_e32 v64, 0xbfb8aa3b, v70
	v_mul_f32_e32 v70, 0xbfb8aa3b, v71
	v_exp_f32_e32 v64, v64
	v_exp_f32_e32 v70, v70
	v_mul_f32_e32 v71, 0xbfb8aa3b, v72
	v_exp_f32_e32 v71, v71
	v_mul_f32_e32 v72, 0xbfb8aa3b, v73
	v_exp_f32_e32 v72, v72
	v_add_f32_e32 v64, 1.0, v64
	v_add_f32_e32 v70, 1.0, v70
	v_rcp_f32_e32 v64, v64
	v_rcp_f32_e32 v73, v70
	v_cvt_pk_bf16_f32 v75, v82, v76
	v_add_u32_e32 v76, 0x1a00, v126
	v_add_f32_e32 v70, 1.0, v71
	v_ashrrev_i32_e32 v77, 31, v76
	v_rcp_f32_e32 v78, v70
	v_add_f32_e32 v70, 1.0, v72
	v_rcp_f32_e32 v72, v70
	v_lshl_add_u64 v[70:71], v[76:77], 3, s[10:11]
	global_store_dwordx2 v[70:71], v[74:75], off
	v_cvt_pk_bf16_f32 v70, v64, v73
	v_mul_f32_e32 v64, 0xbfb8aa3b, v66
	v_mul_f32_e32 v66, 0xbfb8aa3b, v67
	v_exp_f32_e32 v66, v66
	v_mul_f32_e32 v67, 0xbfb8aa3b, v68
	v_exp_f32_e32 v67, v67
	v_mul_f32_e32 v68, 0xbfb8aa3b, v69
	v_exp_f32_e32 v68, v68
	v_exp_f32_e32 v64, v64
	v_add_f32_e32 v66, 1.0, v66
	v_rcp_f32_e32 v69, v66
	v_add_f32_e32 v66, 1.0, v67
	v_rcp_f32_e32 v74, v66
	v_add_f32_e32 v66, 1.0, v68
	v_add_f32_e32 v64, 1.0, v64
	v_rcp_f32_e32 v68, v66
	v_cvt_pk_bf16_f32 v71, v78, v72
	v_add_u32_e32 v72, 0x1c00, v126
	v_rcp_f32_e32 v64, v64
	v_ashrrev_i32_e32 v73, 31, v72
	v_lshl_add_u64 v[66:67], v[72:73], 3, s[10:11]
	global_store_dwordx2 v[66:67], v[70:71], off
	v_cvt_pk_bf16_f32 v67, v74, v68
	v_add_u32_e32 v68, 0x1e00, v126
; DI unsigned pk_bf16(float lo, float hi) { f32x2_t v = {lo, hi}; return __builtin_bit_cast(unsigned, __builtin_convertvector(v, bf16x2_t)); }
; DI float fsigmoid(float x) { return __builtin_amdgcn_rcpf(1.0f + __expf(-x)); }
; #define EPI_M _Pragma("unroll") for (int m = 0; m < 8; ++m)
; #define EPI_N _Pragma("unroll") for (int n = 0; n < 4; ++n)
; DI void p5_phase(const Params& p, char* lds) {
;     ...
;     EPI_M {
;       EPI_N {
;         u32x2 o; o[0] = pk_bf16(fsigmoid(ACC(m, n)[0]), fsigmoid(ACC(m, n)[1])); o[1] = pk_bf16(fsigmoid(ACC(m, n)[2]), fsigmoid(ACC(m, n)[3]));
;         tg[(m * 4 + n) * 512 + tid] = o;
;       }
;       __builtin_amdgcn_sched_barrier(0);
;     }
	v_cvt_pk_bf16_f32 v66, v64, v69
	v_ashrrev_i32_e32 v69, 31, v68
	v_lshl_add_u64 v[68:69], v[68:69], 3, s[10:11]
	global_store_dwordx2 v[68:69], v[66:67], off
	v_mul_f32_e32 v60, 0xbfb8aa3b, v60
	v_exp_f32_e32 v60, v60
	v_mul_f32_e32 v61, 0xbfb8aa3b, v61
	v_exp_f32_e32 v61, v61
	v_mul_f32_e32 v56, 0xbfb8aa3b, v56
	v_add_f32_e32 v60, 1.0, v60
	v_rcp_f32_e32 v64, v60
	v_mul_f32_e32 v60, 0xbfb8aa3b, v62
	v_add_f32_e32 v61, 1.0, v61
	v_exp_f32_e32 v60, v60
	v_mul_f32_e32 v62, 0xbfb8aa3b, v63
	v_exp_f32_e32 v56, v56
	v_mul_f32_e32 v57, 0xbfb8aa3b, v57
	v_exp_f32_e32 v62, v62
	v_rcp_f32_e32 v61, v61
	v_exp_f32_e32 v57, v57
	v_add_f32_e32 v60, 1.0, v60
	v_add_f32_e32 v56, 1.0, v56
	v_rcp_f32_e32 v63, v60
	v_add_f32_e32 v60, 1.0, v62
	v_cvt_pk_bf16_f32 v62, v64, v61
	v_rcp_f32_e32 v64, v56
	v_add_f32_e32 v56, 1.0, v57
	v_mul_f32_e32 v57, 0xbfb8aa3b, v58
	v_exp_f32_e32 v57, v57
	v_mul_f32_e32 v58, 0xbfb8aa3b, v59
	v_mul_f32_e32 v52, 0xbfb8aa3b, v52
	v_rcp_f32_e32 v66, v60
	v_exp_f32_e32 v58, v58
	v_exp_f32_e32 v52, v52
	v_mul_f32_e32 v53, 0xbfb8aa3b, v53
	v_exp_f32_e32 v53, v53
	v_add_u32_e32 v60, 0x2000, v126
	v_rcp_f32_e32 v59, v56
	v_add_f32_e32 v56, 1.0, v57
	v_cvt_pk_bf16_f32 v63, v63, v66
	v_ashrrev_i32_e32 v61, 31, v60
	v_rcp_f32_e32 v66, v56
	v_add_f32_e32 v56, 1.0, v58
	v_add_f32_e32 v52, 1.0, v52
	v_rcp_f32_e32 v58, v56
	v_lshl_add_u64 v[56:57], v[60:61], 3, s[10:11]
	v_rcp_f32_e32 v60, v52
	v_add_f32_e32 v52, 1.0, v53
	v_mul_f32_e32 v53, 0xbfb8aa3b, v54
	v_exp_f32_e32 v53, v53
	v_mul_f32_e32 v54, 0xbfb8aa3b, v55
	v_exp_f32_e32 v54, v54
	v_mul_f32_e32 v48, 0xbfb8aa3b, v48
	v_exp_f32_e32 v48, v48
	v_mul_f32_e32 v49, 0xbfb8aa3b, v49
	v_exp_f32_e32 v49, v49
	global_store_dwordx2 v[56:57], v[62:63], off
	v_cvt_pk_bf16_f32 v57, v66, v58
	v_add_u32_e32 v58, 0x2200, v126
	v_rcp_f32_e32 v55, v52
	v_add_f32_e32 v52, 1.0, v53
	v_cvt_pk_bf16_f32 v56, v64, v59
	v_ashrrev_i32_e32 v59, 31, v58
	v_rcp_f32_e32 v61, v52
	v_add_f32_e32 v52, 1.0, v54
	v_rcp_f32_e32 v54, v52
	v_lshl_add_u64 v[52:53], v[58:59], 3, s[10:11]
	v_add_f32_e32 v48, 1.0, v48
	global_store_dwordx2 v[52:53], v[56:57], off
	v_rcp_f32_e32 v56, v48
	v_add_f32_e32 v48, 1.0, v49
	v_mul_f32_e32 v49, 0xbfb8aa3b, v50
	v_exp_f32_e32 v49, v49
	v_mul_f32_e32 v50, 0xbfb8aa3b, v51
	v_exp_f32_e32 v50, v50
	v_rcp_f32_e32 v51, v48
	v_add_f32_e32 v48, 1.0, v49
	v_rcp_f32_e32 v57, v48
	v_add_f32_e32 v48, 1.0, v50
	v_rcp_f32_e32 v50, v48
	v_cvt_pk_bf16_f32 v53, v61, v54
	v_add_u32_e32 v54, 0x2400, v126
	v_cvt_pk_bf16_f32 v52, v60, v55
	v_ashrrev_i32_e32 v55, 31, v54
	v_lshl_add_u64 v[48:49], v[54:55], 3, s[10:11]
	global_store_dwordx2 v[48:49], v[52:53], off
	v_cvt_pk_bf16_f32 v49, v57, v50
	v_add_u32_e32 v50, 0x2600, v126
	v_cvt_pk_bf16_f32 v48, v56, v51
	v_ashrrev_i32_e32 v51, 31, v50
	v_lshl_add_u64 v[50:51], v[50:51], 3, s[10:11]
	global_store_dwordx2 v[50:51], v[48:49], off
	v_mul_f32_e32 v44, 0xbfb8aa3b, v44
	v_exp_f32_e32 v44, v44
	v_mul_f32_e32 v45, 0xbfb8aa3b, v45
	v_exp_f32_e32 v45, v45
	v_mul_f32_e32 v40, 0xbfb8aa3b, v40
	v_add_f32_e32 v44, 1.0, v44
	v_rcp_f32_e32 v48, v44
	v_mul_f32_e32 v44, 0xbfb8aa3b, v46
	v_add_f32_e32 v45, 1.0, v45
	v_exp_f32_e32 v44, v44
	v_mul_f32_e32 v46, 0xbfb8aa3b, v47
	v_exp_f32_e32 v40, v40
	v_mul_f32_e32 v41, 0xbfb8aa3b, v41
	v_exp_f32_e32 v46, v46
	v_rcp_f32_e32 v45, v45
	v_exp_f32_e32 v41, v41
	v_add_f32_e32 v44, 1.0, v44
	v_add_f32_e32 v40, 1.0, v40
	v_rcp_f32_e32 v47, v44
	v_add_f32_e32 v44, 1.0, v46
	v_cvt_pk_bf16_f32 v46, v48, v45
	v_rcp_f32_e32 v48, v40
	v_add_f32_e32 v40, 1.0, v41
	v_mul_f32_e32 v41, 0xbfb8aa3b, v42
	v_exp_f32_e32 v41, v41
	v_mul_f32_e32 v42, 0xbfb8aa3b, v43
	v_mul_f32_e32 v36, 0xbfb8aa3b, v36
	v_rcp_f32_e32 v49, v44
	v_exp_f32_e32 v42, v42
	v_exp_f32_e32 v36, v36
	v_mul_f32_e32 v37, 0xbfb8aa3b, v37
	v_exp_f32_e32 v37, v37
	v_add_u32_e32 v44, 0x2800, v126
	v_rcp_f32_e32 v43, v40
	v_add_f32_e32 v40, 1.0, v41
	v_cvt_pk_bf16_f32 v47, v47, v49
	v_ashrrev_i32_e32 v45, 31, v44
	v_rcp_f32_e32 v49, v40
	v_add_f32_e32 v40, 1.0, v42
	v_add_f32_e32 v36, 1.0, v36
	v_rcp_f32_e32 v42, v40
	v_lshl_add_u64 v[40:41], v[44:45], 3, s[10:11]
	v_rcp_f32_e32 v44, v36
	v_add_f32_e32 v36, 1.0, v37
	v_mul_f32_e32 v37, 0xbfb8aa3b, v38
	v_exp_f32_e32 v37, v37
	v_mul_f32_e32 v38, 0xbfb8aa3b, v39
	v_exp_f32_e32 v38, v38
	v_mul_f32_e32 v32, 0xbfb8aa3b, v32
	v_exp_f32_e32 v32, v32
	v_mul_f32_e32 v33, 0xbfb8aa3b, v33
	v_exp_f32_e32 v33, v33
	global_store_dwordx2 v[40:41], v[46:47], off
	v_cvt_pk_bf16_f32 v41, v49, v42
	v_add_u32_e32 v42, 0x2a00, v126
	v_rcp_f32_e32 v39, v36
	v_add_f32_e32 v36, 1.0, v37
	v_cvt_pk_bf16_f32 v40, v48, v43
	v_ashrrev_i32_e32 v43, 31, v42
	v_rcp_f32_e32 v45, v36
	v_add_f32_e32 v36, 1.0, v38
	v_rcp_f32_e32 v38, v36
	v_lshl_add_u64 v[36:37], v[42:43], 3, s[10:11]
	v_add_f32_e32 v32, 1.0, v32
	global_store_dwordx2 v[36:37], v[40:41], off
	v_rcp_f32_e32 v40, v32
	v_add_f32_e32 v32, 1.0, v33
	v_mul_f32_e32 v33, 0xbfb8aa3b, v34
	v_exp_f32_e32 v33, v33
	v_mul_f32_e32 v34, 0xbfb8aa3b, v35
	v_exp_f32_e32 v34, v34
	v_rcp_f32_e32 v35, v32
	v_add_f32_e32 v32, 1.0, v33
	v_rcp_f32_e32 v41, v32
	v_add_f32_e32 v32, 1.0, v34
	v_rcp_f32_e32 v34, v32
	v_cvt_pk_bf16_f32 v37, v45, v38
	v_add_u32_e32 v38, 0x2c00, v126
	v_cvt_pk_bf16_f32 v36, v44, v39
	v_ashrrev_i32_e32 v39, 31, v38
	v_lshl_add_u64 v[32:33], v[38:39], 3, s[10:11]
	global_store_dwordx2 v[32:33], v[36:37], off
	v_cvt_pk_bf16_f32 v33, v41, v34
	v_add_u32_e32 v34, 0x2e00, v126
	v_cvt_pk_bf16_f32 v32, v40, v35
	v_ashrrev_i32_e32 v35, 31, v34
	v_lshl_add_u64 v[34:35], v[34:35], 3, s[10:11]
	global_store_dwordx2 v[34:35], v[32:33], off
	v_mul_f32_e32 v28, 0xbfb8aa3b, v28
	v_exp_f32_e32 v28, v28
; DI unsigned pk_bf16(float lo, float hi) { f32x2_t v = {lo, hi}; return __builtin_bit_cast(unsigned, __builtin_convertvector(v, bf16x2_t)); }
; DI float fsigmoid(float x) { return __builtin_amdgcn_rcpf(1.0f + __expf(-x)); }
; #define EPI_M _Pragma("unroll") for (int m = 0; m < 8; ++m)
; #define EPI_N _Pragma("unroll") for (int n = 0; n < 4; ++n)
; DI void p5_phase(const Params& p, char* lds) {
;     ...
;     EPI_M {
;       EPI_N {
;         u32x2 o; o[0] = pk_bf16(fsigmoid(ACC(m, n)[0]), fsigmoid(ACC(m, n)[1])); o[1] = pk_bf16(fsigmoid(ACC(m, n)[2]), fsigmoid(ACC(m, n)[3]));
;         tg[(m * 4 + n) * 512 + tid] = o;
;       }
;       __builtin_amdgcn_sched_barrier(0);
;     }
;     zero_acc(acc);
;     gemm256(oab + (size_t)row0 * 1024, 1024, (const u16*)(ws + OFF_WA) + (size_t)col0 * 512, (const u16*)(ws + OFF_WA) + (size_t)(col0 + 128) * 512, 512, 8, acc, lds);
	v_mul_f32_e32 v29, 0xbfb8aa3b, v29
	v_exp_f32_e32 v29, v29
	v_mul_f32_e32 v24, 0xbfb8aa3b, v24
	v_add_f32_e32 v28, 1.0, v28
	v_rcp_f32_e32 v32, v28
	v_mul_f32_e32 v28, 0xbfb8aa3b, v30
	v_add_f32_e32 v29, 1.0, v29
	v_exp_f32_e32 v28, v28
	v_mul_f32_e32 v30, 0xbfb8aa3b, v31
	v_exp_f32_e32 v24, v24
	v_mul_f32_e32 v25, 0xbfb8aa3b, v25
	v_exp_f32_e32 v30, v30
	v_rcp_f32_e32 v29, v29
	v_exp_f32_e32 v25, v25
	v_add_f32_e32 v28, 1.0, v28
	v_add_f32_e32 v24, 1.0, v24
	v_rcp_f32_e32 v31, v28
	v_add_f32_e32 v28, 1.0, v30
	v_cvt_pk_bf16_f32 v30, v32, v29
	v_rcp_f32_e32 v32, v24
	v_add_f32_e32 v24, 1.0, v25
	v_mul_f32_e32 v25, 0xbfb8aa3b, v26
	v_exp_f32_e32 v25, v25
	v_mul_f32_e32 v26, 0xbfb8aa3b, v27
	v_mul_f32_e32 v20, 0xbfb8aa3b, v20
	v_rcp_f32_e32 v33, v28
	v_exp_f32_e32 v26, v26
	v_exp_f32_e32 v20, v20
	v_mul_f32_e32 v21, 0xbfb8aa3b, v21
	v_exp_f32_e32 v21, v21
	v_add_u32_e32 v28, 0x3000, v126
	v_rcp_f32_e32 v27, v24
	v_add_f32_e32 v24, 1.0, v25
	v_cvt_pk_bf16_f32 v31, v31, v33
	v_ashrrev_i32_e32 v29, 31, v28
	v_rcp_f32_e32 v33, v24
	v_add_f32_e32 v24, 1.0, v26
	v_add_f32_e32 v20, 1.0, v20
	v_rcp_f32_e32 v26, v24
	v_lshl_add_u64 v[24:25], v[28:29], 3, s[10:11]
	v_rcp_f32_e32 v28, v20
	v_add_f32_e32 v20, 1.0, v21
	v_mul_f32_e32 v21, 0xbfb8aa3b, v22
	v_exp_f32_e32 v21, v21
	v_mul_f32_e32 v22, 0xbfb8aa3b, v23
	v_exp_f32_e32 v22, v22
	v_mul_f32_e32 v16, 0xbfb8aa3b, v16
	v_exp_f32_e32 v16, v16
	v_mul_f32_e32 v17, 0xbfb8aa3b, v17
	v_exp_f32_e32 v17, v17
	global_store_dwordx2 v[24:25], v[30:31], off
	v_cvt_pk_bf16_f32 v25, v33, v26
	v_add_u32_e32 v26, 0x3200, v126
	v_rcp_f32_e32 v23, v20
	v_add_f32_e32 v20, 1.0, v21
	v_cvt_pk_bf16_f32 v24, v32, v27
	v_ashrrev_i32_e32 v27, 31, v26
	v_rcp_f32_e32 v29, v20
	v_add_f32_e32 v20, 1.0, v22
	v_rcp_f32_e32 v22, v20
	v_lshl_add_u64 v[20:21], v[26:27], 3, s[10:11]
	v_add_f32_e32 v16, 1.0, v16
	global_store_dwordx2 v[20:21], v[24:25], off
	v_rcp_f32_e32 v24, v16
	v_add_f32_e32 v16, 1.0, v17
	v_mul_f32_e32 v17, 0xbfb8aa3b, v18
	v_exp_f32_e32 v17, v17
	v_mul_f32_e32 v18, 0xbfb8aa3b, v19
	v_exp_f32_e32 v18, v18
	v_rcp_f32_e32 v19, v16
	v_add_f32_e32 v16, 1.0, v17
	v_rcp_f32_e32 v25, v16
	v_add_f32_e32 v16, 1.0, v18
	v_rcp_f32_e32 v18, v16
	v_cvt_pk_bf16_f32 v21, v29, v22
	v_add_u32_e32 v22, 0x3400, v126
	v_cvt_pk_bf16_f32 v20, v28, v23
	v_ashrrev_i32_e32 v23, 31, v22
	v_lshl_add_u64 v[16:17], v[22:23], 3, s[10:11]
	global_store_dwordx2 v[16:17], v[20:21], off
	v_cvt_pk_bf16_f32 v17, v25, v18
	v_add_u32_e32 v18, 0x3600, v126
	v_cvt_pk_bf16_f32 v16, v24, v19
	v_ashrrev_i32_e32 v19, 31, v18
	v_lshl_add_u64 v[18:19], v[18:19], 3, s[10:11]
	global_store_dwordx2 v[18:19], v[16:17], off
	v_mul_f32_e32 v12, 0xbfb8aa3b, v12
	v_exp_f32_e32 v12, v12
	v_mul_f32_e32 v13, 0xbfb8aa3b, v13
	v_exp_f32_e32 v13, v13
	v_mul_f32_e32 v8, 0xbfb8aa3b, v8
	v_add_f32_e32 v12, 1.0, v12
	v_rcp_f32_e32 v16, v12
	v_mul_f32_e32 v12, 0xbfb8aa3b, v14
	v_add_f32_e32 v13, 1.0, v13
	v_exp_f32_e32 v12, v12
	v_mul_f32_e32 v14, 0xbfb8aa3b, v15
	v_exp_f32_e32 v8, v8
	v_mul_f32_e32 v9, 0xbfb8aa3b, v9
	v_exp_f32_e32 v14, v14
	v_rcp_f32_e32 v13, v13
	v_exp_f32_e32 v9, v9
	v_add_f32_e32 v12, 1.0, v12
	v_add_f32_e32 v8, 1.0, v8
	v_rcp_f32_e32 v15, v12
	v_add_f32_e32 v12, 1.0, v14
	v_cvt_pk_bf16_f32 v14, v16, v13
	v_rcp_f32_e32 v16, v8
	v_add_f32_e32 v8, 1.0, v9
	v_mul_f32_e32 v9, 0xbfb8aa3b, v10
	v_exp_f32_e32 v9, v9
	v_mul_f32_e32 v10, 0xbfb8aa3b, v11
	v_mul_f32_e32 v4, 0xbfb8aa3b, v4
	v_rcp_f32_e32 v17, v12
	v_exp_f32_e32 v10, v10
	v_exp_f32_e32 v4, v4
	v_mul_f32_e32 v5, 0xbfb8aa3b, v5
	v_exp_f32_e32 v5, v5
	v_add_u32_e32 v12, 0x3800, v126
	v_rcp_f32_e32 v11, v8
	v_add_f32_e32 v8, 1.0, v9
	v_cvt_pk_bf16_f32 v15, v15, v17
	v_ashrrev_i32_e32 v13, 31, v12
	v_rcp_f32_e32 v17, v8
	v_add_f32_e32 v8, 1.0, v10
	v_add_f32_e32 v4, 1.0, v4
	v_rcp_f32_e32 v10, v8
	v_lshl_add_u64 v[8:9], v[12:13], 3, s[10:11]
	v_rcp_f32_e32 v12, v4
	v_add_f32_e32 v4, 1.0, v5
	v_mul_f32_e32 v5, 0xbfb8aa3b, v6
	v_exp_f32_e32 v5, v5
	v_mul_f32_e32 v6, 0xbfb8aa3b, v7
	v_exp_f32_e32 v6, v6
	v_mul_f32_e32 v0, 0xbfb8aa3b, v0
	v_exp_f32_e32 v0, v0
	v_mul_f32_e32 v1, 0xbfb8aa3b, v1
	v_exp_f32_e32 v1, v1
	global_store_dwordx2 v[8:9], v[14:15], off
	v_cvt_pk_bf16_f32 v9, v17, v10
	v_add_u32_e32 v10, 0x3a00, v126
	v_rcp_f32_e32 v7, v4
	v_add_f32_e32 v4, 1.0, v5
	v_cvt_pk_bf16_f32 v8, v16, v11
	v_ashrrev_i32_e32 v11, 31, v10
	v_rcp_f32_e32 v13, v4
	v_add_f32_e32 v4, 1.0, v6
	v_rcp_f32_e32 v6, v4
	v_lshl_add_u64 v[4:5], v[10:11], 3, s[10:11]
	v_add_f32_e32 v0, 1.0, v0
	global_store_dwordx2 v[4:5], v[8:9], off
	v_rcp_f32_e32 v8, v0
	v_add_f32_e32 v0, 1.0, v1
	v_mul_f32_e32 v1, 0xbfb8aa3b, v2
	v_exp_f32_e32 v1, v1
	v_mul_f32_e32 v2, 0xbfb8aa3b, v3
	v_exp_f32_e32 v2, v2
	v_rcp_f32_e32 v3, v0
	v_add_f32_e32 v0, 1.0, v1
	v_rcp_f32_e32 v9, v0
	v_add_f32_e32 v0, 1.0, v2
	v_rcp_f32_e32 v2, v0
	v_cvt_pk_bf16_f32 v5, v13, v6
	v_add_u32_e32 v6, 0x3c00, v126
	v_cvt_pk_bf16_f32 v4, v12, v7
	v_ashrrev_i32_e32 v7, 31, v6
	v_lshl_add_u64 v[0:1], v[6:7], 3, s[10:11]
	global_store_dwordx2 v[0:1], v[4:5], off
	v_cvt_pk_bf16_f32 v1, v9, v2
	v_add_u32_e32 v2, 0x3e00, v126
	v_cvt_pk_bf16_f32 v0, v8, v3
	v_ashrrev_i32_e32 v3, 31, v2
	v_lshl_add_u64 v[2:3], v[2:3], 3, s[10:11]
	global_store_dwordx2 v[2:3], v[0:1], off
	s_lshl_b64 s[8:9], s[8:9], 1
	v_readlane_b32 s22, v254, 12
	v_readlane_b32 s23, v254, 13
	s_add_u32 s44, s22, s8
	s_addc_u32 s45, s23, s9
	s_lshl_b64 s[48:49], s[38:39], 10
	s_add_u32 s28, s96, s48
	s_addc_u32 s29, s97, s49
	s_or_b32 s8, s38, 0x80
	s_ashr_i32 s9, s8, 31
	s_lshl_b64 s[22:23], s[8:9], 10
	s_add_u32 s22, s96, s22
	s_getreg_b32 s7, hwreg(HW_REG_HW_ID, 0, 6)
	s_addc_u32 s23, s97, s23
	s_lshl_b32 s7, s7, 2
	s_and_b32 s7, s7, 0xfc
	s_add_i32 s7, s7, 0x20040
	v_mov_b32_e32 v0, s7
	ds_read_b32 v0, v0
	v_mov_b32_e32 v131, v65
	s_waitcnt lgkmcnt(0)
; DI int my_tid() { int t = tid_raw(); asm volatile("" : "+v"(t)); return t; }
; #define STAGE_A(b, h, kt) { const u16* ap_ = A + (size_t)((h) * ahalf + (unsigned)(kt) * 64u); glds16(ap_ + ao0, l0 + SA_(b, h)); glds16(ap_ + ao1, l0 + SA_(b, h) + 8192); }
; #define STAGE_B(b, h, kt) { const u16* bp_ = ((h) ? B1 : B0) + (unsigned)(kt) * 64u; glds16(bp_ + bo0, l0 + SB_(b, h)); glds16(bp_ + bo1, l0 + SB_(b, h) + 8192); }
; #define WAIT_V(n) asm volatile("s_waitcnt vmcnt(" #n ")" ::: "memory");
; #define BAR __builtin_amdgcn_s_barrier();
; DI void gemm256(const u16* __restrict__ A, int lda, const u16* __restrict__ B0, const u16* __restrict__ B1, int ldb, int nt, acc_t& acc, char* lds) {
;   const int tid = my_tid();
;   const int lane = tid & 63, wid = tid >> 6, wr = wid >> 2, wc = wid & 3, fr = lane & 15, fq = lane >> 4;
;   int r0, c0, r1, c1;
;   stage_rc(tid * 16, r0, c0); stage_rc(tid * 16 + 8192, r1, c1);
;   const unsigned ao0 = (unsigned)(r0 * lda + c0), ao1 = (unsigned)(r1 * lda + c1);
;   const unsigned ahalf = 128u * (unsigned)lda;
;   const int p0 = (r0 & ~31) + (((r0 & 15) >> 2) * 8) + (((r0 >> 4) & 1) * 4) + (r0 & 3), p1 = (r1 & ~31) + (((r1 & 15) >> 2) * 8) + (((r1 >> 4) & 1) * 4) + (r1 & 3);
;   const unsigned bo0 = (unsigned)(p0 * ldb + c0), bo1 = (unsigned)(p1 * ldb + c1);
;   char* l0 = lds + tid * 16;
;     ...
;   bf16x8 At[4][2], Bq0[2][2], Bq1[2][2];
;   WAIT_V(0)
;   STAGE_B(0, 0, 0) STAGE_A(0, 0, 0) STAGE_B(0, 1, 0) STAGE_A(0, 1, 0)
;   if (wr == 1) BAR
;   WAIT_V(4) BAR
;   STAGE_B(1, 0, 1) STAGE_A(1, 0, 1) STAGE_B(1, 1, 1)
;   WAIT_V(6) BAR
	v_readfirstlane_b32 s7, v0
	s_nop 1
	v_lshl_or_b32 v140, s7, 6, v214
	s_nop 0
	v_bfe_i32 v2, v140, 27, 1
	v_lshlrev_b32_e32 v0, 4, v140
	v_lshrrev_b32_e32 v2, 22, v2
	v_add_u32_e32 v2, v0, v2
	v_and_b32_e32 v2, 0xfffffc00, v2
	v_sub_u32_e32 v2, v0, v2
	v_ashrrev_i32_e32 v1, 31, v140
	v_lshrrev_b32_e32 v3, 4, v2
	v_lshrrev_b32_e32 v1, 26, v1
	v_bitop3_b32 v3, v3, v2, 32 bitop3:0x6c
	v_ashrrev_i32_e32 v2, 31, v2
	v_add_u32_e32 v1, v140, v1
	v_lshrrev_b32_e32 v2, 26, v2
	v_ashrrev_i32_e32 v1, 6, v1
	v_add_u32_e32 v2, v3, v2
	v_lshlrev_b32_e32 v4, 3, v1
	v_ashrrev_i32_e32 v2, 6, v2
	v_lshlrev_b32_e32 v1, 5, v1
	v_and_b32_e32 v15, 32, v1
	v_mul_i32_i24_e32 v1, 64, v2
	v_sub_u32_e32 v1, v3, v1
	v_add_u32_e32 v3, 0x2000, v0
	v_ashrrev_i32_e32 v5, 31, v3
	v_lshrrev_b32_e32 v5, 22, v5
	v_add_u32_e32 v5, v3, v5
	v_ashrrev_i32_e32 v13, 10, v5
	v_mul_i32_i24_e32 v5, 0x400, v13
	v_sub_u32_e32 v3, v3, v5
	v_lshrrev_b32_e32 v5, 4, v3
	v_bitop3_b32 v3, v5, v3, 32 bitop3:0x6c
	v_ashrrev_i32_e32 v6, 31, v3
	v_lshrrev_b32_e32 v6, 26, v6
	v_and_b32_e32 v4, -16, v4
	v_ashrrev_i16_sdwa v17, v215, sext(v1) dst_sel:DWORD dst_unused:UNUSED_PAD src0_sel:DWORD src1_sel:BYTE_0
	v_lshlrev_b32_e32 v5, 3, v13
	v_add_u32_e32 v6, v3, v6
	v_add_u32_e32 v4, v2, v4
	v_add_u32_sdwa v1, v15, sext(v17) dst_sel:DWORD dst_unused:UNUSED_PAD src0_sel:DWORD src1_sel:WORD_0
	v_and_b32_e32 v5, -16, v5
	v_ashrrev_i32_e32 v14, 6, v6
	v_and_b32_e32 v6, 0xc0, v6
	v_add_u32_e32 v5, v14, v5
	v_sub_u32_e32 v3, v3, v6
	v_lshl_add_u32 v8, v4, 10, v1
	v_and_b32_e32 v19, 0xffffffe0, v4
	v_lshlrev_b32_e32 v6, 1, v4
	v_lshrrev_b32_e32 v4, 2, v4
	v_and_b32_e32 v22, 4, v4
	v_and_b32_e32 v24, 3, v2
	v_lshlrev_b32_e32 v4, 1, v5
	v_lshlrev_b32_e32 v7, 5, v13
	v_and_b32_e32 v21, 24, v6
	v_or_b32_e32 v2, v19, v24
	v_and_b32_e32 v20, 0xffffffe0, v5
	v_and_b32_e32 v23, 24, v4
	v_lshrrev_b32_e32 v4, 2, v5
	v_and_b32_e32 v26, 3, v14
	v_and_b32_e32 v16, 32, v7
	v_ashrrev_i16_sdwa v18, v215, sext(v3) dst_sel:DWORD dst_unused:UNUSED_PAD src0_sel:DWORD src1_sel:BYTE_0
	v_or3_b32 v2, v2, v21, v22
	v_and_b32_e32 v25, 4, v4
	v_or_b32_e32 v4, v20, v26
	v_add_u32_e32 v149, 0, v0
	v_add_u32_sdwa v3, v16, sext(v18) dst_sel:DWORD dst_unused:UNUSED_PAD src0_sel:DWORD src1_sel:WORD_0
	v_or3_b32 v4, v4, v23, v25
	v_lshl_add_u32 v64, v2, 9, v1
	v_add_u32_e32 v150, 0x10000, v149
	v_lshl_add_u32 v130, v5, 10, v3
	v_lshl_add_u32 v2, v4, 9, v3
	v_lshlrev_b64 v[6:7], 1, v[64:65]
	v_readfirstlane_b32 s7, v150
	v_mov_b32_e32 v3, v65
	v_add_u32_e32 v152, 0x12000, v149
	v_lshl_add_u64 v[0:1], s[28:29], 0, v[6:7]
	s_mov_b32 m0, s7
	v_lshlrev_b64 v[28:29], 1, v[2:3]
	v_readfirstlane_b32 s7, v152
	v_mov_b32_e32 v64, v8
	global_load_lds_dwordx4 v[0:1], off
	v_lshl_add_u64 v[2:3], s[28:29], 0, v[28:29]
	s_mov_b32 m0, s7
	v_lshlrev_b64 v[30:31], 1, v[64:65]
	v_readfirstlane_b32 s7, v149
	v_add_u32_e32 v153, 0x2000, v149
	global_load_lds_dwordx4 v[2:3], off
	v_lshl_add_u64 v[4:5], s[44:45], 0, v[30:31]
	s_mov_b32 m0, s7
	v_lshlrev_b64 v[32:33], 1, v[130:131]
	v_readfirstlane_b32 s7, v153
	v_add_u32_e32 v154, 0x14000, v149
	global_load_lds_dwordx4 v[4:5], off
	v_lshl_add_u64 v[8:9], s[44:45], 0, v[32:33]
	s_mov_b32 m0, s7
	v_readfirstlane_b32 s7, v154
	v_add_u32_e32 v155, 0x16000, v149
	global_load_lds_dwordx4 v[8:9], off
	v_lshl_add_u64 v[10:11], s[22:23], 0, v[6:7]
	s_mov_b32 m0, s7
	v_lshl_add_u64 v[6:7], s[22:23], 0, v[28:29]
	v_readfirstlane_b32 s7, v155
	s_add_u32 s22, s44, 0x40000
	v_add_u32_e32 v157, 0x4000, v149
	global_load_lds_dwordx4 v[10:11], off
	s_mov_b32 m0, s7
	s_addc_u32 s23, s45, 0
	v_readfirstlane_b32 s7, v157
	v_add_u32_e32 v158, 0x6000, v149
	global_load_lds_dwordx4 v[6:7], off
	v_lshl_add_u64 v[28:29], s[22:23], 0, v[30:31]
	s_mov_b32 m0, s7
	v_readfirstlane_b32 s7, v158
	global_load_lds_dwordx4 v[28:29], off
	v_lshl_add_u64 v[28:29], s[22:23], 0, v[32:33]
	s_mov_b32 m0, s7
	v_ashrrev_i32_e32 v12, 8, v140
	global_load_lds_dwordx4 v[28:29], off
	v_cmp_eq_u32_e32 vcc, 1, v12
	s_and_saveexec_b64 s[22:23], vcc
	s_cbranch_execz .LBB0_978
	s_barrier

; DI unsigned pk_f16(float lo, float hi) { f32x2_t v = {lo, hi}; return __builtin_bit_cast(unsigned, __builtin_convertvector(v, f16x2_t)); }
; DI float bflo(unsigned u) { return __uint_as_float(u << 16); }
; DI float bfhi(unsigned u) { return __uint_as_float(u & 0xffff0000u); }
; #define EPI_M _Pragma("unroll") for (int m = 0; m < 8; ++m)
; #define EPI_N _Pragma("unroll") for (int n = 0; n < 4; ++n)
; DI void p5_phase(const Params& p, char* lds) {
;     ...
;     EPI_IDX_N
;     {
;       u32x2 gq[2][4];
;       EPI_N gq[0][n] = tg[(0 * 4 + n) * 512 + tid];
;       EPI_M {
;         if (m < 7) EPI_N gq[(m + 1) & 1][n] = tg[((m + 1) * 4 + n) * 512 + tid];
;         EPI_N {
;           const u32x2 g = gq[m & 1][n];
;           u32x2 o; o[0] = pk_f16(ACC(m, n)[0] * bflo(g[0]), ACC(m, n)[1] * bfhi(g[0])); o[1] = pk_f16(ACC(m, n)[2] * bflo(g[1]), ACC(m, n)[3] * bfhi(g[1]));
;           tr[(m * 4 + n) * 512 + tid] = o;
;         }
;         __builtin_amdgcn_sched_barrier(0);
;       }
;     }
.LBB0_982:
	s_or_b64 exec, exec, s[8:9]
	s_waitcnt vmcnt(0)
	s_barrier
	s_getreg_b32 s2, hwreg(HW_REG_HW_ID, 0, 6)
	s_lshl_b32 s2, s2, 2
	s_and_b32 s2, s2, 0xfc
	s_add_i32 s2, s2, 0x20040
	v_mov_b32_e32 v64, s2
	ds_read_b32 v64, v64
	s_waitcnt lgkmcnt(0)
	v_readfirstlane_b32 s2, v64
	s_nop 1
	v_lshl_or_b32 v130, s2, 6, v214
	s_nop 0
	v_ashrrev_i32_e32 v131, 31, v130
	v_lshlrev_b64 v[162:163], 3, v[130:131]
	v_lshl_add_u64 v[132:133], s[10:11], 0, v[162:163]
	global_load_dwordx2 v[142:143], v[132:133], off
	v_add_u32_e32 v132, 0x200, v130
	v_ashrrev_i32_e32 v133, 31, v132
	v_lshlrev_b64 v[156:157], 3, v[132:133]
	v_lshl_add_u64 v[132:133], s[10:11], 0, v[156:157]
	global_load_dwordx2 v[164:165], v[132:133], off
	v_add_u32_e32 v132, 0x400, v130
	v_ashrrev_i32_e32 v133, 31, v132
	v_lshlrev_b64 v[152:153], 3, v[132:133]
	v_lshl_add_u64 v[132:133], s[10:11], 0, v[152:153]
	global_load_dwordx2 v[158:159], v[132:133], off
	v_add_u32_e32 v132, 0x600, v130
	v_ashrrev_i32_e32 v133, 31, v132
	v_lshlrev_b64 v[154:155], 3, v[132:133]
	v_lshl_add_u64 v[132:133], s[10:11], 0, v[154:155]
	global_load_dwordx2 v[160:161], v[132:133], off
	v_add_u32_e32 v132, 0x800, v130
	v_ashrrev_i32_e32 v133, 31, v132
	v_lshlrev_b64 v[132:133], 3, v[132:133]
	v_lshl_add_u64 v[134:135], s[10:11], 0, v[132:133]
	global_load_dwordx2 v[138:139], v[134:135], off
	v_add_u32_e32 v134, 0xa00, v130
	v_ashrrev_i32_e32 v135, 31, v134
	v_lshlrev_b64 v[134:135], 3, v[134:135]
	v_lshl_add_u64 v[136:137], s[10:11], 0, v[134:135]
	global_load_dwordx2 v[140:141], v[136:137], off
	v_add_u32_e32 v136, 0xc00, v130
	v_ashrrev_i32_e32 v137, 31, v136
	v_lshlrev_b64 v[136:137], 3, v[136:137]
	v_lshl_add_u64 v[144:145], s[10:11], 0, v[136:137]
	global_load_dwordx2 v[146:147], v[144:145], off
	v_add_u32_e32 v144, 0xe00, v130
	v_ashrrev_i32_e32 v145, 31, v144
	v_lshlrev_b64 v[148:149], 3, v[144:145]
	v_lshl_add_u64 v[144:145], s[10:11], 0, v[148:149]
	global_load_dwordx2 v[150:151], v[144:145], off
	s_waitcnt vmcnt(7)
	v_lshlrev_b32_e32 v144, 16, v142
	v_and_b32_e32 v145, 0xffff0000, v142
	v_lshlrev_b32_e32 v142, 16, v143
	v_and_b32_e32 v143, 0xffff0000, v143
	v_pk_mul_f32 v[126:127], v[126:127], v[144:145]
	v_pk_mul_f32 v[128:129], v[128:129], v[142:143]
	v_cvt_pk_f16_f32 v126, v126, v127
	v_cvt_pk_f16_f32 v127, v128, v129
	v_lshl_add_u64 v[128:129], s[12:13], 0, v[162:163]
	global_store_dwordx2 v[128:129], v[126:127], off
	s_waitcnt vmcnt(7)
	v_lshlrev_b32_e32 v126, 16, v164
	v_and_b32_e32 v127, 0xffff0000, v164
	v_pk_mul_f32 v[122:123], v[122:123], v[126:127]
	v_lshlrev_b32_e32 v126, 16, v165
	v_and_b32_e32 v127, 0xffff0000, v165
	v_pk_mul_f32 v[124:125], v[124:125], v[126:127]
	v_cvt_pk_f16_f32 v122, v122, v123
	v_cvt_pk_f16_f32 v123, v124, v125
	v_lshl_add_u64 v[124:125], s[12:13], 0, v[156:157]
	global_store_dwordx2 v[124:125], v[122:123], off
	s_waitcnt vmcnt(7)
	v_lshlrev_b32_e32 v122, 16, v158
	v_and_b32_e32 v123, 0xffff0000, v158
	v_pk_mul_f32 v[118:119], v[118:119], v[122:123]
	v_lshlrev_b32_e32 v122, 16, v159
	v_and_b32_e32 v123, 0xffff0000, v159
	v_pk_mul_f32 v[120:121], v[120:121], v[122:123]
	v_cvt_pk_f16_f32 v118, v118, v119
	v_cvt_pk_f16_f32 v119, v120, v121
	v_lshl_add_u64 v[120:121], s[12:13], 0, v[152:153]
	global_store_dwordx2 v[120:121], v[118:119], off
	s_waitcnt vmcnt(7)
	v_lshlrev_b32_e32 v118, 16, v160
	v_and_b32_e32 v119, 0xffff0000, v160
	v_pk_mul_f32 v[114:115], v[114:115], v[118:119]
	v_lshlrev_b32_e32 v118, 16, v161
	v_and_b32_e32 v119, 0xffff0000, v161
	v_pk_mul_f32 v[116:117], v[116:117], v[118:119]
	v_cvt_pk_f16_f32 v114, v114, v115
	v_cvt_pk_f16_f32 v115, v116, v117
	v_lshl_add_u64 v[116:117], s[12:13], 0, v[154:155]
	global_store_dwordx2 v[116:117], v[114:115], off
	v_add_u32_e32 v114, 0x1000, v130
	v_add_u32_e32 v118, 0x1200, v130
	v_add_u32_e32 v122, 0x1400, v130
	v_add_u32_e32 v126, 0x1600, v130
	v_ashrrev_i32_e32 v115, 31, v114
	v_ashrrev_i32_e32 v119, 31, v118
	v_ashrrev_i32_e32 v123, 31, v122
	v_ashrrev_i32_e32 v127, 31, v126
	v_lshlrev_b64 v[114:115], 3, v[114:115]
	v_lshlrev_b64 v[118:119], 3, v[118:119]
	v_lshlrev_b64 v[122:123], 3, v[122:123]
	v_lshlrev_b64 v[126:127], 3, v[126:127]
	v_lshl_add_u64 v[116:117], s[10:11], 0, v[114:115]
	v_lshl_add_u64 v[120:121], s[10:11], 0, v[118:119]
	v_lshl_add_u64 v[124:125], s[10:11], 0, v[122:123]
	v_lshl_add_u64 v[128:129], s[10:11], 0, v[126:127]
	global_load_dwordx2 v[116:117], v[116:117], off
	s_nop 0
	global_load_dwordx2 v[120:121], v[120:121], off
	s_nop 0
	global_load_dwordx2 v[124:125], v[124:125], off
	s_nop 0
	global_load_dwordx2 v[128:129], v[128:129], off
	s_waitcnt vmcnt(11)
	v_lshlrev_b32_e32 v142, 16, v138
	v_and_b32_e32 v143, 0xffff0000, v138
	v_lshlrev_b32_e32 v138, 16, v139
	v_and_b32_e32 v139, 0xffff0000, v139
	v_pk_mul_f32 v[110:111], v[110:111], v[142:143]
	v_pk_mul_f32 v[112:113], v[112:113], v[138:139]
	v_cvt_pk_f16_f32 v110, v110, v111
	v_cvt_pk_f16_f32 v111, v112, v113
	v_lshl_add_u64 v[112:113], s[12:13], 0, v[132:133]
	global_store_dwordx2 v[112:113], v[110:111], off
	s_waitcnt vmcnt(11)
	v_lshlrev_b32_e32 v110, 16, v140
	v_and_b32_e32 v111, 0xffff0000, v140
	v_pk_mul_f32 v[102:103], v[102:103], v[110:111]
	v_lshlrev_b32_e32 v110, 16, v141
	v_and_b32_e32 v111, 0xffff0000, v141
	v_pk_mul_f32 v[104:105], v[104:105], v[110:111]
	v_cvt_pk_f16_f32 v102, v102, v103
	v_cvt_pk_f16_f32 v103, v104, v105
	v_lshl_add_u64 v[104:105], s[12:13], 0, v[134:135]
	global_store_dwordx2 v[104:105], v[102:103], off
	s_waitcnt vmcnt(11)
; DI unsigned pk_f16(float lo, float hi) { f32x2_t v = {lo, hi}; return __builtin_bit_cast(unsigned, __builtin_convertvector(v, f16x2_t)); }
; DI float bflo(unsigned u) { return __uint_as_float(u << 16); }
; DI float bfhi(unsigned u) { return __uint_as_float(u & 0xffff0000u); }
; #define EPI_M _Pragma("unroll") for (int m = 0; m < 8; ++m)
; #define EPI_N _Pragma("unroll") for (int n = 0; n < 4; ++n)
; DI void p5_phase(const Params& p, char* lds) {
;     ...
;       EPI_M {
;         if (m < 7) EPI_N gq[(m + 1) & 1][n] = tg[((m + 1) * 4 + n) * 512 + tid];
;         EPI_N {
;           const u32x2 g = gq[m & 1][n];
;           u32x2 o; o[0] = pk_f16(ACC(m, n)[0] * bflo(g[0]), ACC(m, n)[1] * bfhi(g[0])); o[1] = pk_f16(ACC(m, n)[2] * bflo(g[1]), ACC(m, n)[3] * bfhi(g[1]));
;           tr[(m * 4 + n) * 512 + tid] = o;
;         }
;         __builtin_amdgcn_sched_barrier(0);
;       }
	v_lshlrev_b32_e32 v102, 16, v146
	v_and_b32_e32 v103, 0xffff0000, v146
	v_lshlrev_b32_e32 v104, 16, v147
	v_and_b32_e32 v105, 0xffff0000, v147
	v_pk_mul_f32 v[102:103], v[106:107], v[102:103]
	v_pk_mul_f32 v[104:105], v[108:109], v[104:105]
	v_cvt_pk_f16_f32 v102, v102, v103
	v_cvt_pk_f16_f32 v103, v104, v105
	v_lshl_add_u64 v[104:105], s[12:13], 0, v[136:137]
	global_store_dwordx2 v[104:105], v[102:103], off
	s_waitcnt vmcnt(11)
	v_lshlrev_b32_e32 v102, 16, v150
	v_and_b32_e32 v103, 0xffff0000, v150
	v_pk_mul_f32 v[98:99], v[98:99], v[102:103]
	v_lshlrev_b32_e32 v102, 16, v151
	v_and_b32_e32 v103, 0xffff0000, v151
	v_pk_mul_f32 v[100:101], v[100:101], v[102:103]
	v_cvt_pk_f16_f32 v98, v98, v99
	v_cvt_pk_f16_f32 v99, v100, v101
	v_lshl_add_u64 v[100:101], s[12:13], 0, v[148:149]
	global_store_dwordx2 v[100:101], v[98:99], off
	v_add_u32_e32 v98, 0x1800, v130
	v_add_u32_e32 v102, 0x1a00, v130
	v_add_u32_e32 v106, 0x1c00, v130
	v_add_u32_e32 v110, 0x1e00, v130
	v_ashrrev_i32_e32 v99, 31, v98
	v_ashrrev_i32_e32 v103, 31, v102
	v_ashrrev_i32_e32 v107, 31, v106
	v_ashrrev_i32_e32 v111, 31, v110
	v_lshlrev_b64 v[98:99], 3, v[98:99]
	v_lshlrev_b64 v[102:103], 3, v[102:103]
	v_lshlrev_b64 v[106:107], 3, v[106:107]
	v_lshlrev_b64 v[110:111], 3, v[110:111]
	v_lshl_add_u64 v[100:101], s[10:11], 0, v[98:99]
	v_lshl_add_u64 v[104:105], s[10:11], 0, v[102:103]
	v_lshl_add_u64 v[108:109], s[10:11], 0, v[106:107]
	v_lshl_add_u64 v[112:113], s[10:11], 0, v[110:111]
	global_load_dwordx2 v[100:101], v[100:101], off
	s_nop 0
	global_load_dwordx2 v[104:105], v[104:105], off
	s_nop 0
	global_load_dwordx2 v[108:109], v[108:109], off
	s_nop 0
	global_load_dwordx2 v[112:113], v[112:113], off
	s_waitcnt vmcnt(11)
	v_lshlrev_b32_e32 v132, 16, v116
	v_and_b32_e32 v133, 0xffff0000, v116
	v_lshlrev_b32_e32 v116, 16, v117
	v_and_b32_e32 v117, 0xffff0000, v117
	v_pk_mul_f32 v[94:95], v[94:95], v[132:133]
	v_pk_mul_f32 v[96:97], v[96:97], v[116:117]
	v_cvt_pk_f16_f32 v94, v94, v95
	v_cvt_pk_f16_f32 v95, v96, v97
	v_lshl_add_u64 v[96:97], s[12:13], 0, v[114:115]
	global_store_dwordx2 v[96:97], v[94:95], off
	s_waitcnt vmcnt(11)
	v_lshlrev_b32_e32 v94, 16, v120
	v_and_b32_e32 v95, 0xffff0000, v120
	v_pk_mul_f32 v[86:87], v[86:87], v[94:95]
	v_lshlrev_b32_e32 v94, 16, v121
	v_and_b32_e32 v95, 0xffff0000, v121
	v_pk_mul_f32 v[88:89], v[88:89], v[94:95]
	v_cvt_pk_f16_f32 v86, v86, v87
	v_cvt_pk_f16_f32 v87, v88, v89
	v_lshl_add_u64 v[88:89], s[12:13], 0, v[118:119]
	global_store_dwordx2 v[88:89], v[86:87], off
	s_waitcnt vmcnt(11)
	v_lshlrev_b32_e32 v86, 16, v124
	v_and_b32_e32 v87, 0xffff0000, v124
	v_lshlrev_b32_e32 v88, 16, v125
	v_and_b32_e32 v89, 0xffff0000, v125
	v_pk_mul_f32 v[86:87], v[90:91], v[86:87]
	v_pk_mul_f32 v[88:89], v[92:93], v[88:89]
	v_cvt_pk_f16_f32 v86, v86, v87
	v_cvt_pk_f16_f32 v87, v88, v89
	v_lshl_add_u64 v[88:89], s[12:13], 0, v[122:123]
	global_store_dwordx2 v[88:89], v[86:87], off
	s_waitcnt vmcnt(11)
	v_lshlrev_b32_e32 v86, 16, v128
	v_and_b32_e32 v87, 0xffff0000, v128
	v_pk_mul_f32 v[82:83], v[82:83], v[86:87]
	v_lshlrev_b32_e32 v86, 16, v129
	v_and_b32_e32 v87, 0xffff0000, v129
	v_pk_mul_f32 v[84:85], v[84:85], v[86:87]
	v_cvt_pk_f16_f32 v82, v82, v83
	v_cvt_pk_f16_f32 v83, v84, v85
	v_lshl_add_u64 v[84:85], s[12:13], 0, v[126:127]
	global_store_dwordx2 v[84:85], v[82:83], off
	v_add_u32_e32 v82, 0x2000, v130
	v_add_u32_e32 v86, 0x2200, v130
	v_add_u32_e32 v90, 0x2400, v130
	v_add_u32_e32 v94, 0x2600, v130
	v_ashrrev_i32_e32 v83, 31, v82
	v_ashrrev_i32_e32 v87, 31, v86
	v_ashrrev_i32_e32 v91, 31, v90
	v_ashrrev_i32_e32 v95, 31, v94
	v_lshlrev_b64 v[82:83], 3, v[82:83]
	v_lshlrev_b64 v[86:87], 3, v[86:87]
	v_lshlrev_b64 v[90:91], 3, v[90:91]
	v_lshlrev_b64 v[94:95], 3, v[94:95]
	v_lshl_add_u64 v[84:85], s[10:11], 0, v[82:83]
	v_lshl_add_u64 v[88:89], s[10:11], 0, v[86:87]
	v_lshl_add_u64 v[92:93], s[10:11], 0, v[90:91]
	v_lshl_add_u64 v[96:97], s[10:11], 0, v[94:95]
	global_load_dwordx2 v[84:85], v[84:85], off
	s_nop 0
	global_load_dwordx2 v[88:89], v[88:89], off
	s_nop 0
	global_load_dwordx2 v[92:93], v[92:93], off
	s_nop 0
	global_load_dwordx2 v[96:97], v[96:97], off
	s_waitcnt vmcnt(11)
	v_lshlrev_b32_e32 v114, 16, v100
	v_and_b32_e32 v115, 0xffff0000, v100
	v_lshlrev_b32_e32 v100, 16, v101
	v_and_b32_e32 v101, 0xffff0000, v101
	v_pk_mul_f32 v[78:79], v[78:79], v[114:115]
	v_pk_mul_f32 v[80:81], v[80:81], v[100:101]
	v_cvt_pk_f16_f32 v78, v78, v79
	v_cvt_pk_f16_f32 v79, v80, v81
	v_lshl_add_u64 v[80:81], s[12:13], 0, v[98:99]
	global_store_dwordx2 v[80:81], v[78:79], off
	s_waitcnt vmcnt(11)
	v_lshlrev_b32_e32 v78, 16, v104
	v_and_b32_e32 v79, 0xffff0000, v104
	v_pk_mul_f32 v[70:71], v[70:71], v[78:79]
	v_lshlrev_b32_e32 v78, 16, v105
	v_and_b32_e32 v79, 0xffff0000, v105
	v_pk_mul_f32 v[72:73], v[72:73], v[78:79]
	v_cvt_pk_f16_f32 v70, v70, v71
	v_cvt_pk_f16_f32 v71, v72, v73
	v_lshl_add_u64 v[72:73], s[12:13], 0, v[102:103]
	global_store_dwordx2 v[72:73], v[70:71], off
	s_waitcnt vmcnt(11)
	v_lshlrev_b32_e32 v70, 16, v108
	v_and_b32_e32 v71, 0xffff0000, v108
	v_lshlrev_b32_e32 v72, 16, v109
	v_and_b32_e32 v73, 0xffff0000, v109
	v_pk_mul_f32 v[70:71], v[74:75], v[70:71]
	v_pk_mul_f32 v[72:73], v[76:77], v[72:73]
	v_cvt_pk_f16_f32 v70, v70, v71
	v_cvt_pk_f16_f32 v71, v72, v73
	v_lshl_add_u64 v[72:73], s[12:13], 0, v[106:107]
	global_store_dwordx2 v[72:73], v[70:71], off
	s_waitcnt vmcnt(11)
; DI unsigned pk_f16(float lo, float hi) { f32x2_t v = {lo, hi}; return __builtin_bit_cast(unsigned, __builtin_convertvector(v, f16x2_t)); }
; DI float bflo(unsigned u) { return __uint_as_float(u << 16); }
; DI float bfhi(unsigned u) { return __uint_as_float(u & 0xffff0000u); }
; #define EPI_M _Pragma("unroll") for (int m = 0; m < 8; ++m)
; #define EPI_N _Pragma("unroll") for (int n = 0; n < 4; ++n)
; DI void p5_phase(const Params& p, char* lds) {
;     ...
;       EPI_M {
;         if (m < 7) EPI_N gq[(m + 1) & 1][n] = tg[((m + 1) * 4 + n) * 512 + tid];
;         EPI_N {
;           const u32x2 g = gq[m & 1][n];
;           u32x2 o; o[0] = pk_f16(ACC(m, n)[0] * bflo(g[0]), ACC(m, n)[1] * bfhi(g[0])); o[1] = pk_f16(ACC(m, n)[2] * bflo(g[1]), ACC(m, n)[3] * bfhi(g[1]));
;           tr[(m * 4 + n) * 512 + tid] = o;
;         }
;         __builtin_amdgcn_sched_barrier(0);
;       }
	v_lshlrev_b32_e32 v70, 16, v112
	v_and_b32_e32 v71, 0xffff0000, v112
	v_pk_mul_f32 v[66:67], v[66:67], v[70:71]
	v_lshlrev_b32_e32 v70, 16, v113
	v_and_b32_e32 v71, 0xffff0000, v113
	v_pk_mul_f32 v[68:69], v[68:69], v[70:71]
	v_cvt_pk_f16_f32 v66, v66, v67
	v_cvt_pk_f16_f32 v67, v68, v69
	v_lshl_add_u64 v[68:69], s[12:13], 0, v[110:111]
	global_store_dwordx2 v[68:69], v[66:67], off
	v_add_u32_e32 v66, 0x2800, v130
	v_add_u32_e32 v70, 0x2a00, v130
	v_add_u32_e32 v74, 0x2c00, v130
	v_add_u32_e32 v78, 0x2e00, v130
	v_ashrrev_i32_e32 v67, 31, v66
	v_ashrrev_i32_e32 v71, 31, v70
	v_ashrrev_i32_e32 v75, 31, v74
	v_ashrrev_i32_e32 v79, 31, v78
	v_lshlrev_b64 v[66:67], 3, v[66:67]
	v_lshlrev_b64 v[70:71], 3, v[70:71]
	v_lshlrev_b64 v[74:75], 3, v[74:75]
	v_lshlrev_b64 v[78:79], 3, v[78:79]
	v_lshl_add_u64 v[68:69], s[10:11], 0, v[66:67]
	v_lshl_add_u64 v[72:73], s[10:11], 0, v[70:71]
	v_lshl_add_u64 v[76:77], s[10:11], 0, v[74:75]
	v_lshl_add_u64 v[80:81], s[10:11], 0, v[78:79]
	global_load_dwordx2 v[68:69], v[68:69], off
	s_nop 0
	global_load_dwordx2 v[72:73], v[72:73], off
	s_nop 0
	global_load_dwordx2 v[76:77], v[76:77], off
	s_nop 0
	global_load_dwordx2 v[80:81], v[80:81], off
	s_waitcnt vmcnt(11)
	v_lshlrev_b32_e32 v98, 16, v84
	v_and_b32_e32 v99, 0xffff0000, v84
	v_lshlrev_b32_e32 v84, 16, v85
	v_and_b32_e32 v85, 0xffff0000, v85
	v_pk_mul_f32 v[60:61], v[60:61], v[98:99]
	v_pk_mul_f32 v[62:63], v[62:63], v[84:85]
	v_cvt_pk_f16_f32 v60, v60, v61
	v_cvt_pk_f16_f32 v61, v62, v63
	v_lshl_add_u64 v[62:63], s[12:13], 0, v[82:83]
	global_store_dwordx2 v[62:63], v[60:61], off
	s_waitcnt vmcnt(11)
	v_lshlrev_b32_e32 v60, 16, v88
	v_and_b32_e32 v61, 0xffff0000, v88
	v_pk_mul_f32 v[56:57], v[56:57], v[60:61]
	v_lshlrev_b32_e32 v60, 16, v89
	v_and_b32_e32 v61, 0xffff0000, v89
	v_pk_mul_f32 v[58:59], v[58:59], v[60:61]
	v_cvt_pk_f16_f32 v56, v56, v57
	v_cvt_pk_f16_f32 v57, v58, v59
	v_lshl_add_u64 v[58:59], s[12:13], 0, v[86:87]
	global_store_dwordx2 v[58:59], v[56:57], off
	s_waitcnt vmcnt(11)
	v_lshlrev_b32_e32 v56, 16, v92
	v_and_b32_e32 v57, 0xffff0000, v92
	v_pk_mul_f32 v[52:53], v[52:53], v[56:57]
	v_lshlrev_b32_e32 v56, 16, v93
	v_and_b32_e32 v57, 0xffff0000, v93
	v_pk_mul_f32 v[54:55], v[54:55], v[56:57]
	v_cvt_pk_f16_f32 v52, v52, v53
	v_cvt_pk_f16_f32 v53, v54, v55
	v_lshl_add_u64 v[54:55], s[12:13], 0, v[90:91]
	global_store_dwordx2 v[54:55], v[52:53], off
	s_waitcnt vmcnt(11)
	v_lshlrev_b32_e32 v52, 16, v96
	v_and_b32_e32 v53, 0xffff0000, v96
	v_pk_mul_f32 v[48:49], v[48:49], v[52:53]
	v_lshlrev_b32_e32 v52, 16, v97
	v_and_b32_e32 v53, 0xffff0000, v97
	v_pk_mul_f32 v[50:51], v[50:51], v[52:53]
	v_cvt_pk_f16_f32 v48, v48, v49
	v_cvt_pk_f16_f32 v49, v50, v51
	v_lshl_add_u64 v[50:51], s[12:13], 0, v[94:95]
	global_store_dwordx2 v[50:51], v[48:49], off
	v_add_u32_e32 v48, 0x3000, v130
	v_add_u32_e32 v52, 0x3200, v130
	v_add_u32_e32 v56, 0x3400, v130
	v_add_u32_e32 v60, 0x3600, v130
	v_ashrrev_i32_e32 v49, 31, v48
	v_ashrrev_i32_e32 v53, 31, v52
	v_ashrrev_i32_e32 v57, 31, v56
	v_ashrrev_i32_e32 v61, 31, v60
	v_lshlrev_b64 v[48:49], 3, v[48:49]
	v_lshlrev_b64 v[52:53], 3, v[52:53]
	v_lshlrev_b64 v[56:57], 3, v[56:57]
	v_lshlrev_b64 v[60:61], 3, v[60:61]
	v_lshl_add_u64 v[50:51], s[10:11], 0, v[48:49]
	v_lshl_add_u64 v[54:55], s[10:11], 0, v[52:53]
	v_lshl_add_u64 v[58:59], s[10:11], 0, v[56:57]
	v_lshl_add_u64 v[62:63], s[10:11], 0, v[60:61]
	global_load_dwordx2 v[50:51], v[50:51], off
	s_nop 0
	global_load_dwordx2 v[54:55], v[54:55], off
	s_nop 0
	global_load_dwordx2 v[58:59], v[58:59], off
	s_nop 0
	global_load_dwordx2 v[62:63], v[62:63], off
	s_waitcnt vmcnt(11)
	v_lshlrev_b32_e32 v82, 16, v68
	v_and_b32_e32 v83, 0xffff0000, v68
	v_lshlrev_b32_e32 v68, 16, v69
	v_and_b32_e32 v69, 0xffff0000, v69
	v_pk_mul_f32 v[44:45], v[44:45], v[82:83]
	v_pk_mul_f32 v[46:47], v[46:47], v[68:69]
	v_cvt_pk_f16_f32 v44, v44, v45
	v_cvt_pk_f16_f32 v45, v46, v47
	v_lshl_add_u64 v[46:47], s[12:13], 0, v[66:67]
	global_store_dwordx2 v[46:47], v[44:45], off
	s_waitcnt vmcnt(11)
	v_lshlrev_b32_e32 v44, 16, v72
	v_and_b32_e32 v45, 0xffff0000, v72
	v_pk_mul_f32 v[40:41], v[40:41], v[44:45]
	v_lshlrev_b32_e32 v44, 16, v73
	v_and_b32_e32 v45, 0xffff0000, v73
	v_pk_mul_f32 v[42:43], v[42:43], v[44:45]
	v_cvt_pk_f16_f32 v40, v40, v41
	v_cvt_pk_f16_f32 v41, v42, v43
	v_lshl_add_u64 v[42:43], s[12:13], 0, v[70:71]
	global_store_dwordx2 v[42:43], v[40:41], off
	s_waitcnt vmcnt(11)
	v_lshlrev_b32_e32 v40, 16, v76
	v_and_b32_e32 v41, 0xffff0000, v76
	v_pk_mul_f32 v[36:37], v[36:37], v[40:41]
	v_lshlrev_b32_e32 v40, 16, v77
	v_and_b32_e32 v41, 0xffff0000, v77
	v_pk_mul_f32 v[38:39], v[38:39], v[40:41]
	v_cvt_pk_f16_f32 v36, v36, v37
	v_cvt_pk_f16_f32 v37, v38, v39
	v_lshl_add_u64 v[38:39], s[12:13], 0, v[74:75]
	global_store_dwordx2 v[38:39], v[36:37], off
	s_waitcnt vmcnt(11)
	v_lshlrev_b32_e32 v36, 16, v80
	v_and_b32_e32 v37, 0xffff0000, v80
	v_pk_mul_f32 v[32:33], v[32:33], v[36:37]
	v_lshlrev_b32_e32 v36, 16, v81
	v_and_b32_e32 v37, 0xffff0000, v81
	v_pk_mul_f32 v[34:35], v[34:35], v[36:37]
	v_cvt_pk_f16_f32 v32, v32, v33
	v_cvt_pk_f16_f32 v33, v34, v35
	v_lshl_add_u64 v[34:35], s[12:13], 0, v[78:79]
	global_store_dwordx2 v[34:35], v[32:33], off
	v_add_u32_e32 v32, 0x3800, v130
	v_add_u32_e32 v36, 0x3a00, v130
	v_add_u32_e32 v40, 0x3c00, v130
	v_add_u32_e32 v44, 0x3e00, v130
	v_ashrrev_i32_e32 v33, 31, v32
	v_ashrrev_i32_e32 v37, 31, v36
	v_ashrrev_i32_e32 v41, 31, v40
	v_ashrrev_i32_e32 v45, 31, v44
	v_lshlrev_b64 v[32:33], 3, v[32:33]
	v_lshlrev_b64 v[36:37], 3, v[36:37]
	v_lshlrev_b64 v[40:41], 3, v[40:41]
	v_lshlrev_b64 v[44:45], 3, v[44:45]
	v_lshl_add_u64 v[34:35], s[10:11], 0, v[32:33]
	v_lshl_add_u64 v[38:39], s[10:11], 0, v[36:37]
	v_lshl_add_u64 v[42:43], s[10:11], 0, v[40:41]
	v_lshl_add_u64 v[46:47], s[10:11], 0, v[44:45]
	global_load_dwordx2 v[34:35], v[34:35], off
	s_nop 0
	global_load_dwordx2 v[38:39], v[38:39], off
	s_nop 0
	global_load_dwordx2 v[42:43], v[42:43], off
	s_nop 0
	global_load_dwordx2 v[46:47], v[46:47], off
	s_waitcnt vmcnt(11)
; DI unsigned pk_f16(float lo, float hi) { f32x2_t v = {lo, hi}; return __builtin_bit_cast(unsigned, __builtin_convertvector(v, f16x2_t)); }
; DI float bflo(unsigned u) { return __uint_as_float(u << 16); }
; DI float bfhi(unsigned u) { return __uint_as_float(u & 0xffff0000u); }
; #define EPI_M _Pragma("unroll") for (int m = 0; m < 8; ++m)
; #define EPI_N _Pragma("unroll") for (int n = 0; n < 4; ++n)
; DI void p5_phase(const Params& p, char* lds) {
;     ...
;       EPI_M {
;         if (m < 7) EPI_N gq[(m + 1) & 1][n] = tg[((m + 1) * 4 + n) * 512 + tid];
;         EPI_N {
;           const u32x2 g = gq[m & 1][n];
;           u32x2 o; o[0] = pk_f16(ACC(m, n)[0] * bflo(g[0]), ACC(m, n)[1] * bfhi(g[0])); o[1] = pk_f16(ACC(m, n)[2] * bflo(g[1]), ACC(m, n)[3] * bfhi(g[1]));
;           tr[(m * 4 + n) * 512 + tid] = o;
;         }
;         __builtin_amdgcn_sched_barrier(0);
;       }
;     }
;     zero_acc(acc);
;     gemm256(xb + (size_t)row0 * D, D, win + (size_t)(4608 + col0) * D, win + (size_t)(4608 + col0 + 128) * D, D, 16, acc, lds);
	v_lshlrev_b32_e32 v66, 16, v50
	v_and_b32_e32 v67, 0xffff0000, v50
	v_lshlrev_b32_e32 v50, 16, v51
	v_and_b32_e32 v51, 0xffff0000, v51
	v_pk_mul_f32 v[28:29], v[28:29], v[66:67]
	v_pk_mul_f32 v[30:31], v[30:31], v[50:51]
	v_cvt_pk_f16_f32 v28, v28, v29
	v_cvt_pk_f16_f32 v29, v30, v31
	v_lshl_add_u64 v[30:31], s[12:13], 0, v[48:49]
	global_store_dwordx2 v[30:31], v[28:29], off
	s_waitcnt vmcnt(11)
	v_lshlrev_b32_e32 v28, 16, v54
	v_and_b32_e32 v29, 0xffff0000, v54
	v_pk_mul_f32 v[24:25], v[24:25], v[28:29]
	v_lshlrev_b32_e32 v28, 16, v55
	v_and_b32_e32 v29, 0xffff0000, v55
	v_pk_mul_f32 v[26:27], v[26:27], v[28:29]
	v_cvt_pk_f16_f32 v24, v24, v25
	v_cvt_pk_f16_f32 v25, v26, v27
	v_lshl_add_u64 v[26:27], s[12:13], 0, v[52:53]
	global_store_dwordx2 v[26:27], v[24:25], off
	s_waitcnt vmcnt(11)
	v_lshlrev_b32_e32 v24, 16, v58
	v_and_b32_e32 v25, 0xffff0000, v58
	v_pk_mul_f32 v[20:21], v[20:21], v[24:25]
	v_lshlrev_b32_e32 v24, 16, v59
	v_and_b32_e32 v25, 0xffff0000, v59
	v_pk_mul_f32 v[22:23], v[22:23], v[24:25]
	v_cvt_pk_f16_f32 v20, v20, v21
	v_cvt_pk_f16_f32 v21, v22, v23
	v_lshl_add_u64 v[22:23], s[12:13], 0, v[56:57]
	global_store_dwordx2 v[22:23], v[20:21], off
	s_waitcnt vmcnt(11)
	v_lshlrev_b32_e32 v20, 16, v62
	v_and_b32_e32 v21, 0xffff0000, v62
	v_pk_mul_f32 v[16:17], v[16:17], v[20:21]
	v_lshlrev_b32_e32 v20, 16, v63
	v_and_b32_e32 v21, 0xffff0000, v63
	v_pk_mul_f32 v[18:19], v[18:19], v[20:21]
	v_cvt_pk_f16_f32 v16, v16, v17
	v_cvt_pk_f16_f32 v17, v18, v19
	v_lshl_add_u64 v[18:19], s[12:13], 0, v[60:61]
	global_store_dwordx2 v[18:19], v[16:17], off
	s_waitcnt vmcnt(7)
	v_lshlrev_b32_e32 v16, 16, v34
	v_and_b32_e32 v17, 0xffff0000, v34
	v_pk_mul_f32 v[12:13], v[12:13], v[16:17]
	v_lshlrev_b32_e32 v16, 16, v35
	v_and_b32_e32 v17, 0xffff0000, v35
	v_pk_mul_f32 v[14:15], v[14:15], v[16:17]
	v_cvt_pk_f16_f32 v12, v12, v13
	v_cvt_pk_f16_f32 v13, v14, v15
	v_lshl_add_u64 v[14:15], s[12:13], 0, v[32:33]
	global_store_dwordx2 v[14:15], v[12:13], off
	s_waitcnt vmcnt(7)
	v_lshlrev_b32_e32 v12, 16, v38
	v_and_b32_e32 v13, 0xffff0000, v38
	v_pk_mul_f32 v[8:9], v[8:9], v[12:13]
	v_lshlrev_b32_e32 v12, 16, v39
	v_and_b32_e32 v13, 0xffff0000, v39
	v_pk_mul_f32 v[10:11], v[10:11], v[12:13]
	v_cvt_pk_f16_f32 v8, v8, v9
	v_cvt_pk_f16_f32 v9, v10, v11
	v_lshl_add_u64 v[10:11], s[12:13], 0, v[36:37]
	global_store_dwordx2 v[10:11], v[8:9], off
	s_waitcnt vmcnt(7)
	v_lshlrev_b32_e32 v8, 16, v42
	v_and_b32_e32 v9, 0xffff0000, v42
	v_pk_mul_f32 v[4:5], v[4:5], v[8:9]
	v_lshlrev_b32_e32 v8, 16, v43
	v_and_b32_e32 v9, 0xffff0000, v43
	v_pk_mul_f32 v[6:7], v[6:7], v[8:9]
	v_cvt_pk_f16_f32 v4, v4, v5
	v_cvt_pk_f16_f32 v5, v6, v7
	v_lshl_add_u64 v[6:7], s[12:13], 0, v[40:41]
	global_store_dwordx2 v[6:7], v[4:5], off
	s_waitcnt vmcnt(7)
	v_lshlrev_b32_e32 v4, 16, v46
	v_and_b32_e32 v5, 0xffff0000, v46
	v_pk_mul_f32 v[0:1], v[0:1], v[4:5]
	v_lshlrev_b32_e32 v4, 16, v47
	v_and_b32_e32 v5, 0xffff0000, v47
	v_pk_mul_f32 v[2:3], v[2:3], v[4:5]
	v_cvt_pk_f16_f32 v0, v0, v1
	v_cvt_pk_f16_f32 v1, v2, v3
	v_lshl_add_u64 v[2:3], s[12:13], 0, v[44:45]
	global_store_dwordx2 v[2:3], v[0:1], off
	s_lshl_b64 s[2:3], s[38:39], 11
	s_add_u32 s2, s90, s2
	s_addc_u32 s3, s91, s3
	s_add_u32 s22, s2, 0x900000
	s_addc_u32 s23, s3, 0
	s_add_u32 s8, s2, 0x940000
	s_getreg_b32 s2, hwreg(HW_REG_HW_ID, 0, 6)
	s_addc_u32 s9, s3, 0
	s_lshl_b32 s2, s2, 2
	s_and_b32 s2, s2, 0xfc
	s_add_i32 s2, s2, 0x20040
	v_mov_b32_e32 v0, s2
	ds_read_b32 v0, v0
	v_mov_b32_e32 v131, v65
	s_waitcnt lgkmcnt(0)
; DI int my_tid() { int t = tid_raw(); asm volatile("" : "+v"(t)); return t; }
; #define STAGE_A(b, h, kt) { const u16* ap_ = A + (size_t)((h) * ahalf + (unsigned)(kt) * 64u); glds16(ap_ + ao0, l0 + SA_(b, h)); glds16(ap_ + ao1, l0 + SA_(b, h) + 8192); }
; #define STAGE_B(b, h, kt) { const u16* bp_ = ((h) ? B1 : B0) + (unsigned)(kt) * 64u; glds16(bp_ + bo0, l0 + SB_(b, h)); glds16(bp_ + bo1, l0 + SB_(b, h) + 8192); }
; #define WAIT_V(n) asm volatile("s_waitcnt vmcnt(" #n ")" ::: "memory");
; #define BAR __builtin_amdgcn_s_barrier();
; DI void gemm256(const u16* __restrict__ A, int lda, const u16* __restrict__ B0, const u16* __restrict__ B1, int ldb, int nt, acc_t& acc, char* lds) {
;   const int tid = my_tid();
;   const int lane = tid & 63, wid = tid >> 6, wr = wid >> 2, wc = wid & 3, fr = lane & 15, fq = lane >> 4;
;   int r0, c0, r1, c1;
;   stage_rc(tid * 16, r0, c0); stage_rc(tid * 16 + 8192, r1, c1);
;   const unsigned ao0 = (unsigned)(r0 * lda + c0), ao1 = (unsigned)(r1 * lda + c1);
;   const unsigned ahalf = 128u * (unsigned)lda;
;   const int p0 = (r0 & ~31) + (((r0 & 15) >> 2) * 8) + (((r0 >> 4) & 1) * 4) + (r0 & 3), p1 = (r1 & ~31) + (((r1 & 15) >> 2) * 8) + (((r1 >> 4) & 1) * 4) + (r1 & 3);
;   const unsigned bo0 = (unsigned)(p0 * ldb + c0), bo1 = (unsigned)(p1 * ldb + c1);
;   char* l0 = lds + tid * 16;
;     ...
;   bf16x8 At[4][2], Bq0[2][2], Bq1[2][2];
;   WAIT_V(0)
;   STAGE_B(0, 0, 0) STAGE_A(0, 0, 0) STAGE_B(0, 1, 0) STAGE_A(0, 1, 0)
;   if (wr == 1) BAR
;   WAIT_V(4) BAR
;   STAGE_B(1, 0, 1) STAGE_A(1, 0, 1) STAGE_B(1, 1, 1)
;   WAIT_V(6) BAR
	v_readfirstlane_b32 s2, v0
	s_nop 1
	v_lshl_or_b32 v140, s2, 6, v214
	s_nop 0
	v_bfe_i32 v2, v140, 27, 1
	v_lshlrev_b32_e32 v0, 4, v140
	v_lshrrev_b32_e32 v2, 22, v2
	v_add_u32_e32 v2, v0, v2
	v_and_b32_e32 v2, 0xfffffc00, v2
	v_sub_u32_e32 v2, v0, v2
	v_ashrrev_i32_e32 v1, 31, v140
	v_lshrrev_b32_e32 v3, 4, v2
	v_lshrrev_b32_e32 v1, 26, v1
	v_bitop3_b32 v3, v3, v2, 32 bitop3:0x6c
	v_ashrrev_i32_e32 v2, 31, v2
	v_add_u32_e32 v1, v140, v1
	v_lshrrev_b32_e32 v2, 26, v2
	v_ashrrev_i32_e32 v1, 6, v1
	v_add_u32_e32 v2, v3, v2
	v_lshlrev_b32_e32 v4, 3, v1
	v_ashrrev_i32_e32 v2, 6, v2
	v_lshlrev_b32_e32 v1, 5, v1
	v_and_b32_e32 v14, 32, v1
	v_mul_i32_i24_e32 v1, 64, v2
	v_sub_u32_e32 v1, v3, v1
	v_add_u32_e32 v3, 0x2000, v0
	v_ashrrev_i32_e32 v5, 31, v3
	v_lshrrev_b32_e32 v5, 22, v5
	v_add_u32_e32 v5, v3, v5
	v_ashrrev_i32_e32 v13, 10, v5
	v_mul_i32_i24_e32 v5, 0x400, v13
	v_sub_u32_e32 v3, v3, v5
	v_lshrrev_b32_e32 v5, 4, v3
	v_bitop3_b32 v3, v5, v3, 32 bitop3:0x6c
	v_ashrrev_i32_e32 v6, 31, v3
	v_lshrrev_b32_e32 v6, 26, v6
	v_and_b32_e32 v4, -16, v4
	v_ashrrev_i16_sdwa v15, v215, sext(v1) dst_sel:DWORD dst_unused:UNUSED_PAD src0_sel:DWORD src1_sel:BYTE_0
	v_lshlrev_b32_e32 v5, 3, v13
	v_add_u32_e32 v6, v3, v6
	v_add_u32_e32 v4, v2, v4
	v_add_u32_sdwa v1, v14, sext(v15) dst_sel:DWORD dst_unused:UNUSED_PAD src0_sel:DWORD src1_sel:WORD_0
	v_and_b32_e32 v5, -16, v5
	v_ashrrev_i32_e32 v16, 6, v6
	v_and_b32_e32 v6, 0xc0, v6
	v_add_u32_e32 v5, v16, v5
	v_sub_u32_e32 v3, v3, v6
	v_lshl_add_u32 v8, v4, 10, v1
	v_and_b32_e32 v19, 0xffffffe0, v4
	v_lshlrev_b32_e32 v6, 1, v4
	v_lshrrev_b32_e32 v4, 2, v4
	v_and_b32_e32 v22, 4, v4
	v_and_b32_e32 v24, 3, v2
	v_lshlrev_b32_e32 v4, 1, v5
	v_lshlrev_b32_e32 v7, 5, v13
	v_and_b32_e32 v21, 24, v6
	v_or_b32_e32 v2, v19, v24
	v_and_b32_e32 v20, 0xffffffe0, v5
	v_and_b32_e32 v23, 24, v4
	v_lshrrev_b32_e32 v4, 2, v5
	v_and_b32_e32 v26, 3, v16
	v_and_b32_e32 v17, 32, v7
	v_ashrrev_i16_sdwa v18, v215, sext(v3) dst_sel:DWORD dst_unused:UNUSED_PAD src0_sel:DWORD src1_sel:BYTE_0
	v_or3_b32 v2, v2, v21, v22
	v_and_b32_e32 v25, 4, v4
	v_or_b32_e32 v4, v20, v26
	v_add_u32_e32 v150, 0, v0
	v_add_u32_sdwa v3, v17, sext(v18) dst_sel:DWORD dst_unused:UNUSED_PAD src0_sel:DWORD src1_sel:WORD_0
	v_or3_b32 v4, v4, v23, v25
	v_lshl_add_u32 v64, v2, 10, v1
	v_add_u32_e32 v151, 0x10000, v150
	v_lshl_add_u32 v130, v5, 10, v3
	v_lshl_add_u32 v2, v4, 10, v3
	v_lshlrev_b64 v[6:7], 1, v[64:65]
	v_readfirstlane_b32 s2, v151
	v_mov_b32_e32 v3, v65
	v_add_u32_e32 v152, 0x12000, v150
	v_lshl_add_u64 v[0:1], s[22:23], 0, v[6:7]
	s_mov_b32 m0, s2
	v_lshlrev_b64 v[28:29], 1, v[2:3]
	v_readfirstlane_b32 s2, v152
	v_mov_b32_e32 v64, v8
	global_load_lds_dwordx4 v[0:1], off
	v_lshl_add_u64 v[2:3], s[22:23], 0, v[28:29]
	s_mov_b32 m0, s2
	v_lshlrev_b64 v[30:31], 1, v[64:65]
	v_readfirstlane_b32 s2, v150
	v_add_u32_e32 v153, 0x2000, v150
	global_load_lds_dwordx4 v[2:3], off
	v_lshl_add_u64 v[4:5], s[50:51], 0, v[30:31]
	s_mov_b32 m0, s2
	v_lshlrev_b64 v[32:33], 1, v[130:131]
	v_readfirstlane_b32 s2, v153
	v_add_u32_e32 v155, 0x14000, v150
	global_load_lds_dwordx4 v[4:5], off
	v_lshl_add_u64 v[8:9], s[50:51], 0, v[32:33]
	s_mov_b32 m0, s2
	v_readfirstlane_b32 s2, v155
	v_add_u32_e32 v156, 0x16000, v150
	global_load_lds_dwordx4 v[8:9], off
	v_lshl_add_u64 v[10:11], s[8:9], 0, v[6:7]
	s_mov_b32 m0, s2
	v_readfirstlane_b32 s2, v156
	v_add_u32_e32 v157, 0x4000, v150
	global_load_lds_dwordx4 v[10:11], off
	v_lshl_add_u64 v[6:7], s[8:9], 0, v[28:29]
	s_mov_b32 m0, s2
	v_readfirstlane_b32 s2, v157
	v_add_u32_e32 v158, 0x6000, v150
	global_load_lds_dwordx4 v[6:7], off
	v_lshl_add_u64 v[28:29], s[52:53], 0, v[30:31]
	s_mov_b32 m0, s2
	v_readfirstlane_b32 s2, v158
	global_load_lds_dwordx4 v[28:29], off
	v_lshl_add_u64 v[28:29], s[52:53], 0, v[32:33]
	s_mov_b32 m0, s2
	v_ashrrev_i32_e32 v12, 8, v140
	global_load_lds_dwordx4 v[28:29], off
	v_cmp_eq_u32_e32 vcc, 1, v12
	s_and_saveexec_b64 s[8:9], vcc
	s_cbranch_execz .LBB0_984
	s_barrier

; DI unsigned pk_bf16(float lo, float hi) { f32x2_t v = {lo, hi}; return __builtin_bit_cast(unsigned, __builtin_convertvector(v, bf16x2_t)); }
; DI float fsigmoid(float x) { return __builtin_amdgcn_rcpf(1.0f + __expf(-x)); }
; #define EPI_M _Pragma("unroll") for (int m = 0; m < 8; ++m)
; #define EPI_N _Pragma("unroll") for (int n = 0; n < 4; ++n)
; DI void p5_phase(const Params& p, char* lds) {
;     ...
;     EPI_M {
;       EPI_N {
;         u32x2 o; o[0] = pk_bf16(fsigmoid(ACC(m, n)[0]), fsigmoid(ACC(m, n)[1])); o[1] = pk_bf16(fsigmoid(ACC(m, n)[2]), fsigmoid(ACC(m, n)[3]));
;         tg[(m * 4 + n) * 512 + tid] = o;
;       }
;       __builtin_amdgcn_sched_barrier(0);
;     }
.LBB0_988:
	s_or_b64 exec, exec, s[8:9]
	s_waitcnt vmcnt(0)
	s_barrier
	s_getreg_b32 s2, hwreg(HW_REG_HW_ID, 0, 6)
	s_lshl_b32 s2, s2, 2
	s_and_b32 s2, s2, 0xfc
	s_add_i32 s2, s2, 0x20040
	v_mov_b32_e32 v64, s2
	ds_read_b32 v64, v64
	v_mul_f32_e32 v126, 0xbfb8aa3b, v126
	v_mul_f32_e32 v127, 0xbfb8aa3b, v127
	v_exp_f32_e32 v126, v126
	v_exp_f32_e32 v127, v127
	s_waitcnt lgkmcnt(0)
	v_readfirstlane_b32 s2, v64
	v_add_f32_e32 v64, 1.0, v126
	v_add_f32_e32 v126, 1.0, v127
	v_mul_f32_e32 v127, 0xbfb8aa3b, v128
	v_exp_f32_e32 v127, v127
	v_mul_f32_e32 v128, 0xbfb8aa3b, v129
	v_rcp_f32_e32 v64, v64
	v_exp_f32_e32 v128, v128
	v_rcp_f32_e32 v129, v126
	v_add_f32_e32 v126, 1.0, v127
	v_rcp_f32_e32 v127, v126
	v_add_f32_e32 v126, 1.0, v128
	v_cvt_pk_bf16_f32 v128, v64, v129
	v_mul_f32_e32 v64, 0xbfb8aa3b, v122
	v_mul_f32_e32 v122, 0xbfb8aa3b, v123
	v_exp_f32_e32 v64, v64
	v_exp_f32_e32 v122, v122
	v_mul_f32_e32 v123, 0xbfb8aa3b, v124
	v_exp_f32_e32 v123, v123
	v_mul_f32_e32 v124, 0xbfb8aa3b, v125
	v_rcp_f32_e32 v130, v126
	v_exp_f32_e32 v124, v124
	v_add_f32_e32 v64, 1.0, v64
	v_add_f32_e32 v122, 1.0, v122
	v_rcp_f32_e32 v64, v64
	v_rcp_f32_e32 v125, v122
	v_lshl_or_b32 v126, s2, 6, v214
	v_add_f32_e32 v122, 1.0, v123
	v_cvt_pk_bf16_f32 v129, v127, v130
	v_ashrrev_i32_e32 v127, 31, v126
	v_rcp_f32_e32 v130, v122
	v_add_f32_e32 v122, 1.0, v124
	v_rcp_f32_e32 v124, v122
	v_lshl_add_u64 v[122:123], v[126:127], 3, s[10:11]
	global_store_dwordx2 v[122:123], v[128:129], off
	v_cvt_pk_bf16_f32 v122, v64, v125
	v_mul_f32_e32 v64, 0xbfb8aa3b, v118
	v_mul_f32_e32 v118, 0xbfb8aa3b, v119
	v_exp_f32_e32 v64, v64
	v_exp_f32_e32 v118, v118
	v_mul_f32_e32 v119, 0xbfb8aa3b, v120
	v_exp_f32_e32 v119, v119
	v_mul_f32_e32 v120, 0xbfb8aa3b, v121
	v_exp_f32_e32 v120, v120
	v_add_f32_e32 v64, 1.0, v64
	v_add_f32_e32 v118, 1.0, v118
	v_rcp_f32_e32 v64, v64
	v_rcp_f32_e32 v121, v118
	v_cvt_pk_bf16_f32 v123, v130, v124
	v_add_u32_e32 v124, 0x200, v126
	v_add_f32_e32 v118, 1.0, v119
	v_ashrrev_i32_e32 v125, 31, v124
	v_rcp_f32_e32 v127, v118
	v_add_f32_e32 v118, 1.0, v120
	v_rcp_f32_e32 v120, v118
	v_lshl_add_u64 v[118:119], v[124:125], 3, s[10:11]
	global_store_dwordx2 v[118:119], v[122:123], off
	v_cvt_pk_bf16_f32 v118, v64, v121
	v_mul_f32_e32 v64, 0xbfb8aa3b, v114
	v_mul_f32_e32 v114, 0xbfb8aa3b, v115
	v_exp_f32_e32 v114, v114
	v_mul_f32_e32 v115, 0xbfb8aa3b, v116
	v_exp_f32_e32 v115, v115
	v_mul_f32_e32 v116, 0xbfb8aa3b, v117
	v_exp_f32_e32 v116, v116
	v_exp_f32_e32 v64, v64
	v_add_f32_e32 v114, 1.0, v114
	v_rcp_f32_e32 v117, v114
	v_add_f32_e32 v114, 1.0, v115
	v_rcp_f32_e32 v122, v114
	v_add_f32_e32 v114, 1.0, v116
	v_add_f32_e32 v64, 1.0, v64
	v_rcp_f32_e32 v116, v114
	v_cvt_pk_bf16_f32 v119, v127, v120
	v_add_u32_e32 v120, 0x400, v126
	v_rcp_f32_e32 v64, v64
	v_ashrrev_i32_e32 v121, 31, v120
	v_lshl_add_u64 v[114:115], v[120:121], 3, s[10:11]
	global_store_dwordx2 v[114:115], v[118:119], off
	v_cvt_pk_bf16_f32 v115, v122, v116
	v_add_u32_e32 v116, 0x600, v126
	v_cvt_pk_bf16_f32 v114, v64, v117
	v_ashrrev_i32_e32 v117, 31, v116
	v_lshl_add_u64 v[116:117], v[116:117], 3, s[10:11]
	global_store_dwordx2 v[116:117], v[114:115], off
	v_mul_f32_e32 v64, 0xbfb8aa3b, v110
	v_mul_f32_e32 v110, 0xbfb8aa3b, v111
	v_exp_f32_e32 v64, v64
	v_exp_f32_e32 v110, v110
	v_mul_f32_e32 v111, 0xbfb8aa3b, v112
	v_exp_f32_e32 v111, v111
	v_add_f32_e32 v64, 1.0, v64
	v_add_f32_e32 v110, 1.0, v110
	v_mul_f32_e32 v112, 0xbfb8aa3b, v113
	v_rcp_f32_e32 v64, v64
	v_exp_f32_e32 v112, v112
	v_rcp_f32_e32 v113, v110
	v_add_f32_e32 v110, 1.0, v111
	v_rcp_f32_e32 v111, v110
	v_add_f32_e32 v110, 1.0, v112
	v_cvt_pk_bf16_f32 v112, v64, v113
	v_mul_f32_e32 v64, 0xbfb8aa3b, v106
	v_mul_f32_e32 v106, 0xbfb8aa3b, v107
	v_exp_f32_e32 v64, v64
	v_exp_f32_e32 v106, v106
	v_mul_f32_e32 v107, 0xbfb8aa3b, v108
	v_exp_f32_e32 v107, v107
	v_mul_f32_e32 v108, 0xbfb8aa3b, v109
	v_rcp_f32_e32 v114, v110
	v_exp_f32_e32 v108, v108
	v_add_f32_e32 v64, 1.0, v64
	v_add_f32_e32 v106, 1.0, v106
	v_rcp_f32_e32 v64, v64
	v_rcp_f32_e32 v109, v106
	v_add_u32_e32 v110, 0x800, v126
	v_add_f32_e32 v106, 1.0, v107
	v_cvt_pk_bf16_f32 v113, v111, v114
	v_ashrrev_i32_e32 v111, 31, v110
	v_rcp_f32_e32 v114, v106
	v_add_f32_e32 v106, 1.0, v108
	v_rcp_f32_e32 v108, v106
	v_lshl_add_u64 v[106:107], v[110:111], 3, s[10:11]
	global_store_dwordx2 v[106:107], v[112:113], off
	v_cvt_pk_bf16_f32 v106, v64, v109
	v_mul_f32_e32 v64, 0xbfb8aa3b, v102
	v_mul_f32_e32 v102, 0xbfb8aa3b, v103
	v_exp_f32_e32 v64, v64
	v_exp_f32_e32 v102, v102
	v_mul_f32_e32 v103, 0xbfb8aa3b, v104
	v_exp_f32_e32 v103, v103
	v_mul_f32_e32 v104, 0xbfb8aa3b, v105
	v_exp_f32_e32 v104, v104
	v_add_f32_e32 v64, 1.0, v64
	v_add_f32_e32 v102, 1.0, v102
	v_rcp_f32_e32 v64, v64
	v_rcp_f32_e32 v105, v102
	v_cvt_pk_bf16_f32 v107, v114, v108
	v_add_u32_e32 v108, 0xa00, v126
	v_add_f32_e32 v102, 1.0, v103
	v_ashrrev_i32_e32 v109, 31, v108
	v_rcp_f32_e32 v110, v102
	v_add_f32_e32 v102, 1.0, v104
	v_rcp_f32_e32 v104, v102
	v_lshl_add_u64 v[102:103], v[108:109], 3, s[10:11]
	global_store_dwordx2 v[102:103], v[106:107], off
	v_cvt_pk_bf16_f32 v102, v64, v105
	v_mul_f32_e32 v64, 0xbfb8aa3b, v98
	v_mul_f32_e32 v98, 0xbfb8aa3b, v99
	v_exp_f32_e32 v98, v98
	v_mul_f32_e32 v99, 0xbfb8aa3b, v100
	v_exp_f32_e32 v99, v99
	v_mul_f32_e32 v100, 0xbfb8aa3b, v101
	v_exp_f32_e32 v100, v100
	v_exp_f32_e32 v64, v64
	v_add_f32_e32 v98, 1.0, v98
	v_rcp_f32_e32 v101, v98
	v_add_f32_e32 v98, 1.0, v99
	v_rcp_f32_e32 v106, v98
	v_add_f32_e32 v98, 1.0, v100
	v_add_f32_e32 v64, 1.0, v64
	v_rcp_f32_e32 v100, v98
	v_cvt_pk_bf16_f32 v103, v110, v104
	v_add_u32_e32 v104, 0xc00, v126
	v_rcp_f32_e32 v64, v64
; DI unsigned pk_bf16(float lo, float hi) { f32x2_t v = {lo, hi}; return __builtin_bit_cast(unsigned, __builtin_convertvector(v, bf16x2_t)); }
; DI float fsigmoid(float x) { return __builtin_amdgcn_rcpf(1.0f + __expf(-x)); }
; #define EPI_M _Pragma("unroll") for (int m = 0; m < 8; ++m)
; #define EPI_N _Pragma("unroll") for (int n = 0; n < 4; ++n)
; DI void p5_phase(const Params& p, char* lds) {
;     ...
;     EPI_M {
;       EPI_N {
;         u32x2 o; o[0] = pk_bf16(fsigmoid(ACC(m, n)[0]), fsigmoid(ACC(m, n)[1])); o[1] = pk_bf16(fsigmoid(ACC(m, n)[2]), fsigmoid(ACC(m, n)[3]));
;         tg[(m * 4 + n) * 512 + tid] = o;
;       }
;       __builtin_amdgcn_sched_barrier(0);
;     }
	v_ashrrev_i32_e32 v105, 31, v104
	v_lshl_add_u64 v[98:99], v[104:105], 3, s[10:11]
	global_store_dwordx2 v[98:99], v[102:103], off
	v_cvt_pk_bf16_f32 v99, v106, v100
	v_add_u32_e32 v100, 0xe00, v126
	v_cvt_pk_bf16_f32 v98, v64, v101
	v_ashrrev_i32_e32 v101, 31, v100
	v_lshl_add_u64 v[100:101], v[100:101], 3, s[10:11]
	global_store_dwordx2 v[100:101], v[98:99], off
	v_mul_f32_e32 v64, 0xbfb8aa3b, v94
	v_mul_f32_e32 v94, 0xbfb8aa3b, v95
	v_exp_f32_e32 v64, v64
	v_exp_f32_e32 v94, v94
	v_mul_f32_e32 v95, 0xbfb8aa3b, v96
	v_exp_f32_e32 v95, v95
	v_add_f32_e32 v64, 1.0, v64
	v_add_f32_e32 v94, 1.0, v94
	v_mul_f32_e32 v96, 0xbfb8aa3b, v97
	v_rcp_f32_e32 v64, v64
	v_exp_f32_e32 v96, v96
	v_rcp_f32_e32 v97, v94
	v_add_f32_e32 v94, 1.0, v95
	v_rcp_f32_e32 v95, v94
	v_add_f32_e32 v94, 1.0, v96
	v_cvt_pk_bf16_f32 v96, v64, v97
	v_mul_f32_e32 v64, 0xbfb8aa3b, v90
	v_mul_f32_e32 v90, 0xbfb8aa3b, v91
	v_exp_f32_e32 v64, v64
	v_exp_f32_e32 v90, v90
	v_mul_f32_e32 v91, 0xbfb8aa3b, v92
	v_exp_f32_e32 v91, v91
	v_mul_f32_e32 v92, 0xbfb8aa3b, v93
	v_rcp_f32_e32 v98, v94
	v_exp_f32_e32 v92, v92
	v_add_f32_e32 v64, 1.0, v64
	v_add_f32_e32 v90, 1.0, v90
	v_rcp_f32_e32 v64, v64
	v_rcp_f32_e32 v93, v90
	v_add_u32_e32 v94, 0x1000, v126
	v_add_f32_e32 v90, 1.0, v91
	v_cvt_pk_bf16_f32 v97, v95, v98
	v_ashrrev_i32_e32 v95, 31, v94
	v_rcp_f32_e32 v98, v90
	v_add_f32_e32 v90, 1.0, v92
	v_rcp_f32_e32 v92, v90
	v_lshl_add_u64 v[90:91], v[94:95], 3, s[10:11]
	global_store_dwordx2 v[90:91], v[96:97], off
	v_cvt_pk_bf16_f32 v90, v64, v93
	v_mul_f32_e32 v64, 0xbfb8aa3b, v86
	v_mul_f32_e32 v86, 0xbfb8aa3b, v87
	v_exp_f32_e32 v64, v64
	v_exp_f32_e32 v86, v86
	v_mul_f32_e32 v87, 0xbfb8aa3b, v88
	v_exp_f32_e32 v87, v87
	v_mul_f32_e32 v88, 0xbfb8aa3b, v89
	v_exp_f32_e32 v88, v88
	v_add_f32_e32 v64, 1.0, v64
	v_add_f32_e32 v86, 1.0, v86
	v_rcp_f32_e32 v64, v64
	v_rcp_f32_e32 v89, v86
	v_cvt_pk_bf16_f32 v91, v98, v92
	v_add_u32_e32 v92, 0x1200, v126
	v_add_f32_e32 v86, 1.0, v87
	v_ashrrev_i32_e32 v93, 31, v92
	v_rcp_f32_e32 v94, v86
	v_add_f32_e32 v86, 1.0, v88
	v_rcp_f32_e32 v88, v86
	v_lshl_add_u64 v[86:87], v[92:93], 3, s[10:11]
	global_store_dwordx2 v[86:87], v[90:91], off
	v_cvt_pk_bf16_f32 v86, v64, v89
	v_mul_f32_e32 v64, 0xbfb8aa3b, v82
	v_mul_f32_e32 v82, 0xbfb8aa3b, v83
	v_exp_f32_e32 v82, v82
	v_mul_f32_e32 v83, 0xbfb8aa3b, v84
	v_exp_f32_e32 v83, v83
	v_mul_f32_e32 v84, 0xbfb8aa3b, v85
	v_exp_f32_e32 v84, v84
	v_exp_f32_e32 v64, v64
	v_add_f32_e32 v82, 1.0, v82
	v_rcp_f32_e32 v85, v82
	v_add_f32_e32 v82, 1.0, v83
	v_rcp_f32_e32 v90, v82
	v_add_f32_e32 v82, 1.0, v84
	v_add_f32_e32 v64, 1.0, v64
	v_rcp_f32_e32 v84, v82
	v_cvt_pk_bf16_f32 v87, v94, v88
	v_add_u32_e32 v88, 0x1400, v126
	v_rcp_f32_e32 v64, v64
	v_ashrrev_i32_e32 v89, 31, v88
	v_lshl_add_u64 v[82:83], v[88:89], 3, s[10:11]
	global_store_dwordx2 v[82:83], v[86:87], off
	v_cvt_pk_bf16_f32 v83, v90, v84
	v_add_u32_e32 v84, 0x1600, v126
	v_cvt_pk_bf16_f32 v82, v64, v85
	v_ashrrev_i32_e32 v85, 31, v84
	v_lshl_add_u64 v[84:85], v[84:85], 3, s[10:11]
	global_store_dwordx2 v[84:85], v[82:83], off
	v_mul_f32_e32 v64, 0xbfb8aa3b, v78
	v_mul_f32_e32 v78, 0xbfb8aa3b, v79
	v_exp_f32_e32 v64, v64
	v_exp_f32_e32 v78, v78
	v_mul_f32_e32 v79, 0xbfb8aa3b, v80
	v_exp_f32_e32 v79, v79
	v_add_f32_e32 v64, 1.0, v64
	v_add_f32_e32 v78, 1.0, v78
	v_mul_f32_e32 v80, 0xbfb8aa3b, v81
	v_rcp_f32_e32 v64, v64
	v_exp_f32_e32 v80, v80
	v_rcp_f32_e32 v81, v78
	v_add_f32_e32 v78, 1.0, v79
	v_rcp_f32_e32 v79, v78
	v_add_f32_e32 v78, 1.0, v80
	v_cvt_pk_bf16_f32 v80, v64, v81
	v_mul_f32_e32 v64, 0xbfb8aa3b, v74
	v_mul_f32_e32 v74, 0xbfb8aa3b, v75
	v_exp_f32_e32 v64, v64
	v_exp_f32_e32 v74, v74
	v_mul_f32_e32 v75, 0xbfb8aa3b, v76
	v_exp_f32_e32 v75, v75
	v_mul_f32_e32 v76, 0xbfb8aa3b, v77
	v_rcp_f32_e32 v82, v78
	v_exp_f32_e32 v76, v76
	v_add_f32_e32 v64, 1.0, v64
	v_add_f32_e32 v74, 1.0, v74
	v_rcp_f32_e32 v64, v64
	v_rcp_f32_e32 v77, v74
	v_add_u32_e32 v78, 0x1800, v126
	v_add_f32_e32 v74, 1.0, v75
	v_cvt_pk_bf16_f32 v81, v79, v82
	v_ashrrev_i32_e32 v79, 31, v78
	v_rcp_f32_e32 v82, v74
	v_add_f32_e32 v74, 1.0, v76
	v_rcp_f32_e32 v76, v74
	v_lshl_add_u64 v[74:75], v[78:79], 3, s[10:11]
	global_store_dwordx2 v[74:75], v[80:81], off
	v_cvt_pk_bf16_f32 v74, v64, v77
	v_mul_f32_e32 v64, 0xbfb8aa3b, v70
	v_mul_f32_e32 v70, 0xbfb8aa3b, v71
	v_exp_f32_e32 v64, v64
	v_exp_f32_e32 v70, v70
	v_mul_f32_e32 v71, 0xbfb8aa3b, v72
	v_exp_f32_e32 v71, v71
	v_mul_f32_e32 v72, 0xbfb8aa3b, v73
	v_exp_f32_e32 v72, v72
	v_add_f32_e32 v64, 1.0, v64
	v_add_f32_e32 v70, 1.0, v70
	v_rcp_f32_e32 v64, v64
	v_rcp_f32_e32 v73, v70
	v_cvt_pk_bf16_f32 v75, v82, v76
	v_add_u32_e32 v76, 0x1a00, v126
	v_add_f32_e32 v70, 1.0, v71
	v_ashrrev_i32_e32 v77, 31, v76
	v_rcp_f32_e32 v78, v70
	v_add_f32_e32 v70, 1.0, v72
	v_rcp_f32_e32 v72, v70
	v_lshl_add_u64 v[70:71], v[76:77], 3, s[10:11]
	global_store_dwordx2 v[70:71], v[74:75], off
	v_cvt_pk_bf16_f32 v70, v64, v73
	v_mul_f32_e32 v64, 0xbfb8aa3b, v66
	v_mul_f32_e32 v66, 0xbfb8aa3b, v67
	v_exp_f32_e32 v66, v66
	v_mul_f32_e32 v67, 0xbfb8aa3b, v68
	v_exp_f32_e32 v67, v67
	v_mul_f32_e32 v68, 0xbfb8aa3b, v69
	v_exp_f32_e32 v68, v68
	v_exp_f32_e32 v64, v64
	v_add_f32_e32 v66, 1.0, v66
	v_rcp_f32_e32 v69, v66
	v_add_f32_e32 v66, 1.0, v67
	v_rcp_f32_e32 v74, v66
	v_add_f32_e32 v66, 1.0, v68
	v_add_f32_e32 v64, 1.0, v64
	v_rcp_f32_e32 v68, v66
	v_cvt_pk_bf16_f32 v71, v78, v72
	v_add_u32_e32 v72, 0x1c00, v126
	v_rcp_f32_e32 v64, v64
	v_ashrrev_i32_e32 v73, 31, v72
	v_lshl_add_u64 v[66:67], v[72:73], 3, s[10:11]
	global_store_dwordx2 v[66:67], v[70:71], off
	v_cvt_pk_bf16_f32 v67, v74, v68
	v_add_u32_e32 v68, 0x1e00, v126
; DI unsigned pk_bf16(float lo, float hi) { f32x2_t v = {lo, hi}; return __builtin_bit_cast(unsigned, __builtin_convertvector(v, bf16x2_t)); }
; DI float fsigmoid(float x) { return __builtin_amdgcn_rcpf(1.0f + __expf(-x)); }
; #define EPI_M _Pragma("unroll") for (int m = 0; m < 8; ++m)
; #define EPI_N _Pragma("unroll") for (int n = 0; n < 4; ++n)
; DI void p5_phase(const Params& p, char* lds) {
;     ...
;     EPI_M {
;       EPI_N {
;         u32x2 o; o[0] = pk_bf16(fsigmoid(ACC(m, n)[0]), fsigmoid(ACC(m, n)[1])); o[1] = pk_bf16(fsigmoid(ACC(m, n)[2]), fsigmoid(ACC(m, n)[3]));
;         tg[(m * 4 + n) * 512 + tid] = o;
;       }
;       __builtin_amdgcn_sched_barrier(0);
;     }
	v_cvt_pk_bf16_f32 v66, v64, v69
	v_ashrrev_i32_e32 v69, 31, v68
	v_lshl_add_u64 v[68:69], v[68:69], 3, s[10:11]
	global_store_dwordx2 v[68:69], v[66:67], off
	v_mul_f32_e32 v60, 0xbfb8aa3b, v60
	v_exp_f32_e32 v60, v60
	v_mul_f32_e32 v61, 0xbfb8aa3b, v61
	v_exp_f32_e32 v61, v61
	v_mul_f32_e32 v56, 0xbfb8aa3b, v56
	v_add_f32_e32 v60, 1.0, v60
	v_rcp_f32_e32 v64, v60
	v_mul_f32_e32 v60, 0xbfb8aa3b, v62
	v_add_f32_e32 v61, 1.0, v61
	v_exp_f32_e32 v60, v60
	v_mul_f32_e32 v62, 0xbfb8aa3b, v63
	v_exp_f32_e32 v56, v56
	v_mul_f32_e32 v57, 0xbfb8aa3b, v57
	v_exp_f32_e32 v62, v62
	v_rcp_f32_e32 v61, v61
	v_exp_f32_e32 v57, v57
	v_add_f32_e32 v60, 1.0, v60
	v_add_f32_e32 v56, 1.0, v56
	v_rcp_f32_e32 v63, v60
	v_add_f32_e32 v60, 1.0, v62
	v_cvt_pk_bf16_f32 v62, v64, v61
	v_rcp_f32_e32 v64, v56
	v_add_f32_e32 v56, 1.0, v57
	v_mul_f32_e32 v57, 0xbfb8aa3b, v58
	v_exp_f32_e32 v57, v57
	v_mul_f32_e32 v58, 0xbfb8aa3b, v59
	v_mul_f32_e32 v52, 0xbfb8aa3b, v52
	v_rcp_f32_e32 v66, v60
	v_exp_f32_e32 v58, v58
	v_exp_f32_e32 v52, v52
	v_mul_f32_e32 v53, 0xbfb8aa3b, v53
	v_exp_f32_e32 v53, v53
	v_add_u32_e32 v60, 0x2000, v126
	v_rcp_f32_e32 v59, v56
	v_add_f32_e32 v56, 1.0, v57
	v_cvt_pk_bf16_f32 v63, v63, v66
	v_ashrrev_i32_e32 v61, 31, v60
	v_rcp_f32_e32 v66, v56
	v_add_f32_e32 v56, 1.0, v58
	v_add_f32_e32 v52, 1.0, v52
	v_rcp_f32_e32 v58, v56
	v_lshl_add_u64 v[56:57], v[60:61], 3, s[10:11]
	v_rcp_f32_e32 v60, v52
	v_add_f32_e32 v52, 1.0, v53
	v_mul_f32_e32 v53, 0xbfb8aa3b, v54
	v_exp_f32_e32 v53, v53
	v_mul_f32_e32 v54, 0xbfb8aa3b, v55
	v_exp_f32_e32 v54, v54
	v_mul_f32_e32 v48, 0xbfb8aa3b, v48
	v_exp_f32_e32 v48, v48
	v_mul_f32_e32 v49, 0xbfb8aa3b, v49
	v_exp_f32_e32 v49, v49
	global_store_dwordx2 v[56:57], v[62:63], off
	v_cvt_pk_bf16_f32 v57, v66, v58
	v_add_u32_e32 v58, 0x2200, v126
	v_rcp_f32_e32 v55, v52
	v_add_f32_e32 v52, 1.0, v53
	v_cvt_pk_bf16_f32 v56, v64, v59
	v_ashrrev_i32_e32 v59, 31, v58
	v_rcp_f32_e32 v61, v52
	v_add_f32_e32 v52, 1.0, v54
	v_rcp_f32_e32 v54, v52
	v_lshl_add_u64 v[52:53], v[58:59], 3, s[10:11]
	v_add_f32_e32 v48, 1.0, v48
	global_store_dwordx2 v[52:53], v[56:57], off
	v_rcp_f32_e32 v56, v48
	v_add_f32_e32 v48, 1.0, v49
	v_mul_f32_e32 v49, 0xbfb8aa3b, v50
	v_exp_f32_e32 v49, v49
	v_mul_f32_e32 v50, 0xbfb8aa3b, v51
	v_exp_f32_e32 v50, v50
	v_rcp_f32_e32 v51, v48
	v_add_f32_e32 v48, 1.0, v49
	v_rcp_f32_e32 v57, v48
	v_add_f32_e32 v48, 1.0, v50
	v_rcp_f32_e32 v50, v48
	v_cvt_pk_bf16_f32 v53, v61, v54
	v_add_u32_e32 v54, 0x2400, v126
	v_cvt_pk_bf16_f32 v52, v60, v55
	v_ashrrev_i32_e32 v55, 31, v54
	v_lshl_add_u64 v[48:49], v[54:55], 3, s[10:11]
	global_store_dwordx2 v[48:49], v[52:53], off
	v_cvt_pk_bf16_f32 v49, v57, v50
	v_add_u32_e32 v50, 0x2600, v126
	v_cvt_pk_bf16_f32 v48, v56, v51
	v_ashrrev_i32_e32 v51, 31, v50
	v_lshl_add_u64 v[50:51], v[50:51], 3, s[10:11]
	global_store_dwordx2 v[50:51], v[48:49], off
	v_mul_f32_e32 v44, 0xbfb8aa3b, v44
	v_exp_f32_e32 v44, v44
	v_mul_f32_e32 v45, 0xbfb8aa3b, v45
	v_exp_f32_e32 v45, v45
	v_mul_f32_e32 v40, 0xbfb8aa3b, v40
	v_add_f32_e32 v44, 1.0, v44
	v_rcp_f32_e32 v48, v44
	v_mul_f32_e32 v44, 0xbfb8aa3b, v46
	v_add_f32_e32 v45, 1.0, v45
	v_exp_f32_e32 v44, v44
	v_mul_f32_e32 v46, 0xbfb8aa3b, v47
	v_exp_f32_e32 v40, v40
	v_mul_f32_e32 v41, 0xbfb8aa3b, v41
	v_exp_f32_e32 v46, v46
	v_rcp_f32_e32 v45, v45
	v_exp_f32_e32 v41, v41
	v_add_f32_e32 v44, 1.0, v44
	v_add_f32_e32 v40, 1.0, v40
	v_rcp_f32_e32 v47, v44
	v_add_f32_e32 v44, 1.0, v46
	v_cvt_pk_bf16_f32 v46, v48, v45
	v_rcp_f32_e32 v48, v40
	v_add_f32_e32 v40, 1.0, v41
	v_mul_f32_e32 v41, 0xbfb8aa3b, v42
	v_exp_f32_e32 v41, v41
	v_mul_f32_e32 v42, 0xbfb8aa3b, v43
	v_mul_f32_e32 v36, 0xbfb8aa3b, v36
	v_rcp_f32_e32 v49, v44
	v_exp_f32_e32 v42, v42
	v_exp_f32_e32 v36, v36
	v_mul_f32_e32 v37, 0xbfb8aa3b, v37
	v_exp_f32_e32 v37, v37
	v_add_u32_e32 v44, 0x2800, v126
	v_rcp_f32_e32 v43, v40
	v_add_f32_e32 v40, 1.0, v41
	v_cvt_pk_bf16_f32 v47, v47, v49
	v_ashrrev_i32_e32 v45, 31, v44
	v_rcp_f32_e32 v49, v40
	v_add_f32_e32 v40, 1.0, v42
	v_add_f32_e32 v36, 1.0, v36
	v_rcp_f32_e32 v42, v40
	v_lshl_add_u64 v[40:41], v[44:45], 3, s[10:11]
	v_rcp_f32_e32 v44, v36
	v_add_f32_e32 v36, 1.0, v37
	v_mul_f32_e32 v37, 0xbfb8aa3b, v38
	v_exp_f32_e32 v37, v37
	v_mul_f32_e32 v38, 0xbfb8aa3b, v39
	v_exp_f32_e32 v38, v38
	v_mul_f32_e32 v32, 0xbfb8aa3b, v32
	v_exp_f32_e32 v32, v32
	v_mul_f32_e32 v33, 0xbfb8aa3b, v33
	v_exp_f32_e32 v33, v33
	global_store_dwordx2 v[40:41], v[46:47], off
	v_cvt_pk_bf16_f32 v41, v49, v42
	v_add_u32_e32 v42, 0x2a00, v126
	v_rcp_f32_e32 v39, v36
	v_add_f32_e32 v36, 1.0, v37
	v_cvt_pk_bf16_f32 v40, v48, v43
	v_ashrrev_i32_e32 v43, 31, v42
	v_rcp_f32_e32 v45, v36
	v_add_f32_e32 v36, 1.0, v38
	v_rcp_f32_e32 v38, v36
	v_lshl_add_u64 v[36:37], v[42:43], 3, s[10:11]
	v_add_f32_e32 v32, 1.0, v32
	global_store_dwordx2 v[36:37], v[40:41], off
	v_rcp_f32_e32 v40, v32
	v_add_f32_e32 v32, 1.0, v33
	v_mul_f32_e32 v33, 0xbfb8aa3b, v34
	v_exp_f32_e32 v33, v33
	v_mul_f32_e32 v34, 0xbfb8aa3b, v35
	v_exp_f32_e32 v34, v34
	v_rcp_f32_e32 v35, v32
	v_add_f32_e32 v32, 1.0, v33
	v_rcp_f32_e32 v41, v32
	v_add_f32_e32 v32, 1.0, v34
	v_rcp_f32_e32 v34, v32
	v_cvt_pk_bf16_f32 v37, v45, v38
	v_add_u32_e32 v38, 0x2c00, v126
	v_cvt_pk_bf16_f32 v36, v44, v39
	v_ashrrev_i32_e32 v39, 31, v38
	v_lshl_add_u64 v[32:33], v[38:39], 3, s[10:11]
	global_store_dwordx2 v[32:33], v[36:37], off
	v_cvt_pk_bf16_f32 v33, v41, v34
	v_add_u32_e32 v34, 0x2e00, v126
	v_cvt_pk_bf16_f32 v32, v40, v35
	v_ashrrev_i32_e32 v35, 31, v34
	v_lshl_add_u64 v[34:35], v[34:35], 3, s[10:11]
	global_store_dwordx2 v[34:35], v[32:33], off
	v_mul_f32_e32 v28, 0xbfb8aa3b, v28
	v_exp_f32_e32 v28, v28
; DI unsigned pk_bf16(float lo, float hi) { f32x2_t v = {lo, hi}; return __builtin_bit_cast(unsigned, __builtin_convertvector(v, bf16x2_t)); }
; DI float fsigmoid(float x) { return __builtin_amdgcn_rcpf(1.0f + __expf(-x)); }
; #define EPI_M _Pragma("unroll") for (int m = 0; m < 8; ++m)
; #define EPI_N _Pragma("unroll") for (int n = 0; n < 4; ++n)
; DI void p5_phase(const Params& p, char* lds) {
;     ...
;     EPI_M {
;       EPI_N {
;         u32x2 o; o[0] = pk_bf16(fsigmoid(ACC(m, n)[0]), fsigmoid(ACC(m, n)[1])); o[1] = pk_bf16(fsigmoid(ACC(m, n)[2]), fsigmoid(ACC(m, n)[3]));
;         tg[(m * 4 + n) * 512 + tid] = o;
;       }
;       __builtin_amdgcn_sched_barrier(0);
;     }
;     zero_acc(acc);
;     gemm256(oab + (size_t)row0 * 1024 + 512, 1024, (const u16*)(ws + OFF_WB) + (size_t)col0 * 512, (const u16*)(ws + OFF_WB) + (size_t)(col0 + 128) * 512, 512, 8, acc, lds);
	v_mul_f32_e32 v29, 0xbfb8aa3b, v29
	v_exp_f32_e32 v29, v29
	v_mul_f32_e32 v24, 0xbfb8aa3b, v24
	v_add_f32_e32 v28, 1.0, v28
	v_rcp_f32_e32 v32, v28
	v_mul_f32_e32 v28, 0xbfb8aa3b, v30
	v_add_f32_e32 v29, 1.0, v29
	v_exp_f32_e32 v28, v28
	v_mul_f32_e32 v30, 0xbfb8aa3b, v31
	v_exp_f32_e32 v24, v24
	v_mul_f32_e32 v25, 0xbfb8aa3b, v25
	v_exp_f32_e32 v30, v30
	v_rcp_f32_e32 v29, v29
	v_exp_f32_e32 v25, v25
	v_add_f32_e32 v28, 1.0, v28
	v_add_f32_e32 v24, 1.0, v24
	v_rcp_f32_e32 v31, v28
	v_add_f32_e32 v28, 1.0, v30
	v_cvt_pk_bf16_f32 v30, v32, v29
	v_rcp_f32_e32 v32, v24
	v_add_f32_e32 v24, 1.0, v25
	v_mul_f32_e32 v25, 0xbfb8aa3b, v26
	v_exp_f32_e32 v25, v25
	v_mul_f32_e32 v26, 0xbfb8aa3b, v27
	v_mul_f32_e32 v20, 0xbfb8aa3b, v20
	v_rcp_f32_e32 v33, v28
	v_exp_f32_e32 v26, v26
	v_exp_f32_e32 v20, v20
	v_mul_f32_e32 v21, 0xbfb8aa3b, v21
	v_exp_f32_e32 v21, v21
	v_add_u32_e32 v28, 0x3000, v126
	v_rcp_f32_e32 v27, v24
	v_add_f32_e32 v24, 1.0, v25
	v_cvt_pk_bf16_f32 v31, v31, v33
	v_ashrrev_i32_e32 v29, 31, v28
	v_rcp_f32_e32 v33, v24
	v_add_f32_e32 v24, 1.0, v26
	v_add_f32_e32 v20, 1.0, v20
	v_rcp_f32_e32 v26, v24
	v_lshl_add_u64 v[24:25], v[28:29], 3, s[10:11]
	v_rcp_f32_e32 v28, v20
	v_add_f32_e32 v20, 1.0, v21
	v_mul_f32_e32 v21, 0xbfb8aa3b, v22
	v_exp_f32_e32 v21, v21
	v_mul_f32_e32 v22, 0xbfb8aa3b, v23
	v_exp_f32_e32 v22, v22
	v_mul_f32_e32 v16, 0xbfb8aa3b, v16
	v_exp_f32_e32 v16, v16
	v_mul_f32_e32 v17, 0xbfb8aa3b, v17
	v_exp_f32_e32 v17, v17
	global_store_dwordx2 v[24:25], v[30:31], off
	v_cvt_pk_bf16_f32 v25, v33, v26
	v_add_u32_e32 v26, 0x3200, v126
	v_rcp_f32_e32 v23, v20
	v_add_f32_e32 v20, 1.0, v21
	v_cvt_pk_bf16_f32 v24, v32, v27
	v_ashrrev_i32_e32 v27, 31, v26
	v_rcp_f32_e32 v29, v20
	v_add_f32_e32 v20, 1.0, v22
	v_rcp_f32_e32 v22, v20
	v_lshl_add_u64 v[20:21], v[26:27], 3, s[10:11]
	v_add_f32_e32 v16, 1.0, v16
	global_store_dwordx2 v[20:21], v[24:25], off
	v_rcp_f32_e32 v24, v16
	v_add_f32_e32 v16, 1.0, v17
	v_mul_f32_e32 v17, 0xbfb8aa3b, v18
	v_exp_f32_e32 v17, v17
	v_mul_f32_e32 v18, 0xbfb8aa3b, v19
	v_exp_f32_e32 v18, v18
	v_rcp_f32_e32 v19, v16
	v_add_f32_e32 v16, 1.0, v17
	v_rcp_f32_e32 v25, v16
	v_add_f32_e32 v16, 1.0, v18
	v_rcp_f32_e32 v18, v16
	v_cvt_pk_bf16_f32 v21, v29, v22
	v_add_u32_e32 v22, 0x3400, v126
	v_cvt_pk_bf16_f32 v20, v28, v23
	v_ashrrev_i32_e32 v23, 31, v22
	v_lshl_add_u64 v[16:17], v[22:23], 3, s[10:11]
	global_store_dwordx2 v[16:17], v[20:21], off
	v_cvt_pk_bf16_f32 v17, v25, v18
	v_add_u32_e32 v18, 0x3600, v126
	v_cvt_pk_bf16_f32 v16, v24, v19
	v_ashrrev_i32_e32 v19, 31, v18
	v_lshl_add_u64 v[18:19], v[18:19], 3, s[10:11]
	global_store_dwordx2 v[18:19], v[16:17], off
	v_mul_f32_e32 v12, 0xbfb8aa3b, v12
	v_exp_f32_e32 v12, v12
	v_mul_f32_e32 v13, 0xbfb8aa3b, v13
	v_exp_f32_e32 v13, v13
	v_mul_f32_e32 v8, 0xbfb8aa3b, v8
	v_add_f32_e32 v12, 1.0, v12
	v_rcp_f32_e32 v16, v12
	v_mul_f32_e32 v12, 0xbfb8aa3b, v14
	v_add_f32_e32 v13, 1.0, v13
	v_exp_f32_e32 v12, v12
	v_mul_f32_e32 v14, 0xbfb8aa3b, v15
	v_exp_f32_e32 v8, v8
	v_mul_f32_e32 v9, 0xbfb8aa3b, v9
	v_exp_f32_e32 v14, v14
	v_rcp_f32_e32 v13, v13
	v_exp_f32_e32 v9, v9
	v_add_f32_e32 v12, 1.0, v12
	v_add_f32_e32 v8, 1.0, v8
	v_rcp_f32_e32 v15, v12
	v_add_f32_e32 v12, 1.0, v14
	v_cvt_pk_bf16_f32 v14, v16, v13
	v_rcp_f32_e32 v16, v8
	v_add_f32_e32 v8, 1.0, v9
	v_mul_f32_e32 v9, 0xbfb8aa3b, v10
	v_exp_f32_e32 v9, v9
	v_mul_f32_e32 v10, 0xbfb8aa3b, v11
	v_mul_f32_e32 v4, 0xbfb8aa3b, v4
	v_rcp_f32_e32 v17, v12
	v_exp_f32_e32 v10, v10
	v_exp_f32_e32 v4, v4
	v_mul_f32_e32 v5, 0xbfb8aa3b, v5
	v_exp_f32_e32 v5, v5
	v_add_u32_e32 v12, 0x3800, v126
	v_rcp_f32_e32 v11, v8
	v_add_f32_e32 v8, 1.0, v9
	v_cvt_pk_bf16_f32 v15, v15, v17
	v_ashrrev_i32_e32 v13, 31, v12
	v_rcp_f32_e32 v17, v8
	v_add_f32_e32 v8, 1.0, v10
	v_add_f32_e32 v4, 1.0, v4
	v_rcp_f32_e32 v10, v8
	v_lshl_add_u64 v[8:9], v[12:13], 3, s[10:11]
	v_rcp_f32_e32 v12, v4
	v_add_f32_e32 v4, 1.0, v5
	v_mul_f32_e32 v5, 0xbfb8aa3b, v6
	v_exp_f32_e32 v5, v5
	v_mul_f32_e32 v6, 0xbfb8aa3b, v7
	v_exp_f32_e32 v6, v6
	v_mul_f32_e32 v0, 0xbfb8aa3b, v0
	v_exp_f32_e32 v0, v0
	v_mul_f32_e32 v1, 0xbfb8aa3b, v1
	v_exp_f32_e32 v1, v1
	global_store_dwordx2 v[8:9], v[14:15], off
	v_cvt_pk_bf16_f32 v9, v17, v10
	v_add_u32_e32 v10, 0x3a00, v126
	v_rcp_f32_e32 v7, v4
	v_add_f32_e32 v4, 1.0, v5
	v_cvt_pk_bf16_f32 v8, v16, v11
	v_ashrrev_i32_e32 v11, 31, v10
	v_rcp_f32_e32 v13, v4
	v_add_f32_e32 v4, 1.0, v6
	v_rcp_f32_e32 v6, v4
	v_lshl_add_u64 v[4:5], v[10:11], 3, s[10:11]
	v_add_f32_e32 v0, 1.0, v0
	global_store_dwordx2 v[4:5], v[8:9], off
	v_rcp_f32_e32 v8, v0
	v_add_f32_e32 v0, 1.0, v1
	v_mul_f32_e32 v1, 0xbfb8aa3b, v2
	v_exp_f32_e32 v1, v1
	v_mul_f32_e32 v2, 0xbfb8aa3b, v3
	v_exp_f32_e32 v2, v2
	v_rcp_f32_e32 v3, v0
	v_add_f32_e32 v0, 1.0, v1
	v_rcp_f32_e32 v9, v0
	v_add_f32_e32 v0, 1.0, v2
	v_rcp_f32_e32 v2, v0
	v_cvt_pk_bf16_f32 v5, v13, v6
	v_add_u32_e32 v6, 0x3c00, v126
	v_cvt_pk_bf16_f32 v4, v12, v7
	v_ashrrev_i32_e32 v7, 31, v6
	v_lshl_add_u64 v[0:1], v[6:7], 3, s[10:11]
	global_store_dwordx2 v[0:1], v[4:5], off
	v_cvt_pk_bf16_f32 v1, v9, v2
	v_add_u32_e32 v2, 0x3e00, v126
	v_cvt_pk_bf16_f32 v0, v8, v3
	v_ashrrev_i32_e32 v3, 31, v2
	v_lshl_add_u64 v[2:3], v[2:3], 3, s[10:11]
	global_store_dwordx2 v[2:3], v[0:1], off
	s_lshl_b64 s[2:3], s[58:59], 1
	s_add_u32 s22, s94, s2
	s_addc_u32 s23, s95, s3
	s_lshl_b64 s[2:3], s[56:57], 1
	s_add_u32 s8, s94, s2
	s_getreg_b32 s2, hwreg(HW_REG_HW_ID, 0, 6)
	s_addc_u32 s9, s95, s3
	s_lshl_b32 s2, s2, 2
	s_and_b32 s2, s2, 0xfc
	s_add_i32 s2, s2, 0x20040
	v_mov_b32_e32 v0, s2
	ds_read_b32 v0, v0
	v_mov_b32_e32 v131, v65
	s_waitcnt lgkmcnt(0)
; DI int my_tid() { int t = tid_raw(); asm volatile("" : "+v"(t)); return t; }
; #define STAGE_A(b, h, kt) { const u16* ap_ = A + (size_t)((h) * ahalf + (unsigned)(kt) * 64u); glds16(ap_ + ao0, l0 + SA_(b, h)); glds16(ap_ + ao1, l0 + SA_(b, h) + 8192); }
; #define STAGE_B(b, h, kt) { const u16* bp_ = ((h) ? B1 : B0) + (unsigned)(kt) * 64u; glds16(bp_ + bo0, l0 + SB_(b, h)); glds16(bp_ + bo1, l0 + SB_(b, h) + 8192); }
; #define WAIT_V(n) asm volatile("s_waitcnt vmcnt(" #n ")" ::: "memory");
; #define BAR __builtin_amdgcn_s_barrier();
; DI void gemm256(const u16* __restrict__ A, int lda, const u16* __restrict__ B0, const u16* __restrict__ B1, int ldb, int nt, acc_t& acc, char* lds) {
;   const int tid = my_tid();
;   const int lane = tid & 63, wid = tid >> 6, wr = wid >> 2, wc = wid & 3, fr = lane & 15, fq = lane >> 4;
;   int r0, c0, r1, c1;
;   stage_rc(tid * 16, r0, c0); stage_rc(tid * 16 + 8192, r1, c1);
;   const unsigned ao0 = (unsigned)(r0 * lda + c0), ao1 = (unsigned)(r1 * lda + c1);
;   const unsigned ahalf = 128u * (unsigned)lda;
;   const int p0 = (r0 & ~31) + (((r0 & 15) >> 2) * 8) + (((r0 >> 4) & 1) * 4) + (r0 & 3), p1 = (r1 & ~31) + (((r1 & 15) >> 2) * 8) + (((r1 >> 4) & 1) * 4) + (r1 & 3);
;   const unsigned bo0 = (unsigned)(p0 * ldb + c0), bo1 = (unsigned)(p1 * ldb + c1);
;   char* l0 = lds + tid * 16;
;     ...
;   bf16x8 At[4][2], Bq0[2][2], Bq1[2][2];
;   WAIT_V(0)
;   STAGE_B(0, 0, 0) STAGE_A(0, 0, 0) STAGE_B(0, 1, 0) STAGE_A(0, 1, 0)
;   if (wr == 1) BAR
;   WAIT_V(4) BAR
;   STAGE_B(1, 0, 1) STAGE_A(1, 0, 1) STAGE_B(1, 1, 1)
;   WAIT_V(6) BAR
	v_readfirstlane_b32 s2, v0
	s_nop 1
	v_lshl_or_b32 v140, s2, 6, v214
	s_nop 0
	v_ashrrev_i32_e32 v1, 31, v140
	v_lshrrev_b32_e32 v1, 26, v1
	v_add_u32_e32 v1, v140, v1
	v_ashrrev_i32_e32 v12, 6, v1
	v_bfe_i32 v1, v140, 27, 1
	v_lshlrev_b32_e32 v0, 4, v140
	v_lshrrev_b32_e32 v1, 22, v1
	v_add_u32_e32 v1, v0, v1
	v_and_b32_e32 v1, 0xfffffc00, v1
	v_sub_u32_e32 v1, v0, v1
	v_lshrrev_b32_e32 v2, 4, v1
	v_bitop3_b32 v2, v2, v1, 32 bitop3:0x6c
	v_ashrrev_i32_e32 v1, 31, v1
	v_lshrrev_b32_e32 v1, 26, v1
	v_lshlrev_b32_e32 v3, 3, v12
	v_add_u32_e32 v1, v2, v1
	v_and_b32_e32 v3, -16, v3
	v_ashrrev_i32_e32 v16, 6, v1
	v_add_u32_e32 v1, v16, v3
	v_lshlrev_b32_e32 v3, 5, v12
	v_and_b32_e32 v14, 32, v3
	v_mul_i32_i24_e32 v3, 64, v16
	v_sub_u32_e32 v2, v2, v3
	v_add_u32_e32 v3, 0x2000, v0
	v_ashrrev_i32_e32 v4, 31, v3
	v_lshrrev_b32_e32 v4, 22, v4
	v_add_u32_e32 v4, v3, v4
	v_ashrrev_i32_e32 v19, 10, v4
	v_mul_i32_i24_e32 v4, 0x400, v19
	v_sub_u32_e32 v3, v3, v4
	v_lshrrev_b32_e32 v4, 4, v3
	v_bitop3_b32 v3, v4, v3, 32 bitop3:0x6c
	v_ashrrev_i32_e32 v5, 31, v3
	v_lshrrev_b32_e32 v5, 26, v5
	v_add_u32_e32 v5, v3, v5
	v_ashrrev_i32_e32 v25, 6, v5
	v_and_b32_e32 v5, 0xc0, v5
	v_ashrrev_i16_sdwa v15, v215, sext(v2) dst_sel:DWORD dst_unused:UNUSED_PAD src0_sel:DWORD src1_sel:BYTE_0
	v_lshlrev_b32_e32 v4, 3, v19
	v_lshlrev_b32_e32 v6, 5, v19
	v_sub_u32_e32 v3, v3, v5
	v_add_u32_sdwa v2, v14, sext(v15) dst_sel:DWORD dst_unused:UNUSED_PAD src0_sel:DWORD src1_sel:WORD_0
	v_and_b32_e32 v4, -16, v4
	v_and_b32_e32 v17, 32, v6
	v_ashrrev_i16_sdwa v18, v215, sext(v3) dst_sel:DWORD dst_unused:UNUSED_PAD src0_sel:DWORD src1_sel:BYTE_0
	v_add_u32_e32 v4, v25, v4
	v_add_u32_sdwa v3, v17, sext(v18) dst_sel:DWORD dst_unused:UNUSED_PAD src0_sel:DWORD src1_sel:WORD_0
	v_lshl_add_u32 v5, v1, 10, v2
	v_and_b32_e32 v20, 0xffffffe0, v1
	v_lshlrev_b32_e32 v6, 1, v1
	v_lshrrev_b32_e32 v1, 2, v1
	v_and_b32_e32 v26, 3, v16
	v_lshl_add_u32 v130, v4, 10, v3
	v_and_b32_e32 v22, 24, v6
	v_and_b32_e32 v23, 4, v1
	v_or_b32_e32 v1, v20, v26
	v_and_b32_e32 v21, 0xffffffe0, v4
	v_lshlrev_b32_e32 v6, 1, v4
	v_lshrrev_b32_e32 v4, 2, v4
	v_and_b32_e32 v28, 3, v25
	v_or3_b32 v1, v1, v22, v23
	v_and_b32_e32 v24, 24, v6
	v_and_b32_e32 v27, 4, v4
	v_or_b32_e32 v4, v21, v28
	v_add_u32_e32 v149, 0, v0
	v_or3_b32 v4, v4, v24, v27
	v_lshl_add_u32 v64, v1, 9, v2
	v_add_u32_e32 v150, 0x10000, v149
	v_lshl_add_u32 v2, v4, 9, v3
	v_lshlrev_b64 v[8:9], 1, v[64:65]
	v_readfirstlane_b32 s2, v150
	v_mov_b32_e32 v3, v65
	v_add_u32_e32 v152, 0x12000, v149
	v_mov_b32_e32 v64, v5
	v_lshl_add_u64 v[0:1], s[22:23], 0, v[8:9]
	s_mov_b32 m0, s2
	v_lshlrev_b64 v[30:31], 1, v[2:3]
	v_readfirstlane_b32 s2, v152
	v_lshlrev_b64 v[32:33], 1, v[64:65]
	global_load_lds_dwordx4 v[0:1], off
	v_lshl_add_u64 v[2:3], s[22:23], 0, v[30:31]
	s_mov_b32 m0, s2
	v_lshl_add_u64 v[4:5], s[44:45], 0, v[32:33]
	s_mov_b64 s[22:23], 0x400
	v_readfirstlane_b32 s2, v149
	global_load_lds_dwordx4 v[2:3], off
	v_lshl_add_u64 v[6:7], v[4:5], 0, s[22:23]
	s_mov_b32 m0, s2
	v_lshlrev_b64 v[34:35], 1, v[130:131]
	v_add_u32_e32 v153, 0x2000, v149
	global_load_lds_dwordx4 v[6:7], off
	v_lshl_add_u64 v[6:7], s[44:45], 0, v[34:35]
	v_readfirstlane_b32 s2, v153
	v_add_u32_e32 v154, 0x14000, v149
	v_lshl_add_u64 v[10:11], v[6:7], 0, s[22:23]
	s_mov_b32 m0, s2
	v_readfirstlane_b32 s2, v154
	v_add_u32_e32 v156, 0x16000, v149
	global_load_lds_dwordx4 v[10:11], off
	v_lshl_add_u64 v[10:11], s[8:9], 0, v[8:9]
	s_mov_b32 m0, s2
	v_readfirstlane_b32 s2, v156
	global_load_lds_dwordx4 v[10:11], off
	s_mov_b32 m0, s2
	s_add_u32 s2, s44, 0x40400
	v_add_u32_e32 v157, 0x4000, v149
	v_lshl_add_u64 v[8:9], s[8:9], 0, v[30:31]
	s_addc_u32 s3, s45, 0
	v_readfirstlane_b32 s7, v157
	global_load_lds_dwordx4 v[8:9], off
	v_lshl_add_u64 v[30:31], s[2:3], 0, v[32:33]
	s_mov_b32 m0, s7
	v_add_u32_e32 v158, 0x6000, v149
	global_load_lds_dwordx4 v[30:31], off
	v_lshl_add_u64 v[30:31], s[2:3], 0, v[34:35]
	v_readfirstlane_b32 s2, v158
	s_mov_b32 m0, s2
	v_ashrrev_i32_e32 v13, 8, v140
	global_load_lds_dwordx4 v[30:31], off
	v_cmp_eq_u32_e32 vcc, 1, v13
	s_and_saveexec_b64 s[8:9], vcc
	s_cbranch_execz .LBB0_990
	s_barrier

; DI int my_tid() { int t = tid_raw(); asm volatile("" : "+v"(t)); return t; }
; #define STAGE_A(b, h, kt) { const u16* ap_ = A + (size_t)((h) * ahalf + (unsigned)(kt) * 64u); glds16(ap_ + ao0, l0 + SA_(b, h)); glds16(ap_ + ao1, l0 + SA_(b, h) + 8192); }
; #define STAGE_B(b, h, kt) { const u16* bp_ = ((h) ? B1 : B0) + (unsigned)(kt) * 64u; glds16(bp_ + bo0, l0 + SB_(b, h)); glds16(bp_ + bo1, l0 + SB_(b, h) + 8192); }
; #define WAIT_V(n) asm volatile("s_waitcnt vmcnt(" #n ")" ::: "memory");
; #define BAR __builtin_amdgcn_s_barrier();
; DI void gemm256(const u16* __restrict__ A, int lda, const u16* __restrict__ B0, const u16* __restrict__ B1, int ldb, int nt, acc_t& acc, char* lds) {
;   const int tid = my_tid();
;   const int lane = tid & 63, wid = tid >> 6, wr = wid >> 2, wc = wid & 3, fr = lane & 15, fq = lane >> 4;
;   int r0, c0, r1, c1;
;   stage_rc(tid * 16, r0, c0); stage_rc(tid * 16 + 8192, r1, c1);
;   const unsigned ao0 = (unsigned)(r0 * lda + c0), ao1 = (unsigned)(r1 * lda + c1);
;   const unsigned ahalf = 128u * (unsigned)lda;
;   const int p0 = (r0 & ~31) + (((r0 & 15) >> 2) * 8) + (((r0 >> 4) & 1) * 4) + (r0 & 3), p1 = (r1 & ~31) + (((r1 & 15) >> 2) * 8) + (((r1 >> 4) & 1) * 4) + (r1 & 3);
;   const unsigned bo0 = (unsigned)(p0 * ldb + c0), bo1 = (unsigned)(p1 * ldb + c1);
;   char* l0 = lds + tid * 16;
;     ...
;   bf16x8 At[4][2], Bq0[2][2], Bq1[2][2];
;   WAIT_V(0)
;   STAGE_B(0, 0, 0) STAGE_A(0, 0, 0) STAGE_B(0, 1, 0) STAGE_A(0, 1, 0)
;   if (wr == 1) BAR
;   WAIT_V(4) BAR
;   STAGE_B(1, 0, 1) STAGE_A(1, 0, 1) STAGE_B(1, 1, 1)
;   WAIT_V(6) BAR
.LBB0_1050:
	s_ashr_i32 s3, s2, 31
	s_lshr_b32 s3, s3, 29
	s_add_i32 s3, s2, s3
	s_ashr_i32 s7, s3, 3
	s_and_b32 s3, s3, -8
	s_sub_i32 s3, s2, s3
	s_lshr_b32 s8, s3, 31
	s_or_b32 s8, s8, 32
	s_mul_i32 s3, s8, s3
	s_add_i32 s3, s3, s7
	s_ashr_i32 s7, s3, 31
	s_lshr_b32 s7, s7, 27
	s_add_i32 s8, s3, s7
	s_ashr_i32 s7, s8, 5
	s_lshl_b32 s22, s7, 3
	s_sub_i32 s9, 64, s22
	s_min_u32 s19, s9, 8
	s_andn2_b32 s8, s8, 31
	s_sub_i32 s23, s3, s8
	v_cvt_f32_ubyte0_e32 v1, s19
	v_cvt_f32_i32_e32 v0, s23
	v_rcp_iflag_f32_e32 v2, v1
	s_ashr_i32 s8, s23, 30
	s_or_b32 s28, s8, 1
	v_readlane_b32 s36, v253, 62
	v_mul_f32_e32 v2, v0, v2
	v_trunc_f32_e32 v2, v2
	v_fma_f32 v0, -v2, v1, v0
	v_cvt_i32_f32_e32 v2, v2
	v_cmp_ge_f32_e64 s[8:9], |v0|, v1
	s_and_b64 s[8:9], s[8:9], exec
	s_cselect_b32 s8, s28, 0
	v_readfirstlane_b32 s9, v2
	s_add_i32 s8, s9, s8
	s_mul_i32 s19, s8, s19
	s_sext_i32_i8 s9, s8
	s_sub_i32 s8, s23, s19
	s_sext_i32_i8 s8, s8
	s_add_i32 s22, s22, s8
	s_lshl_b32 s8, s22, 8
	s_lshl_b32 s22, s9, 8
	s_ashr_i32 s9, s8, 31
	s_lshl_b64 s[28:29], s[8:9], 11
	v_readlane_b32 s37, v253, 63
	s_add_u32 s28, s36, s28
	s_addc_u32 s29, s37, s29
	s_ashr_i32 s23, s22, 31
	s_lshl_b64 s[36:37], s[22:23], 11
	v_readlane_b32 s42, v252, 36
	v_readlane_b32 s43, v252, 37
	s_add_u32 s40, s42, s36
	s_addc_u32 s41, s43, s37
	s_or_b32 s38, s22, 0x80
	s_ashr_i32 s39, s38, 31
	s_lshl_b64 s[38:39], s[38:39], 11
	s_add_u32 s38, s42, s38
	s_getreg_b32 s9, hwreg(HW_REG_HW_ID, 0, 6)
	s_addc_u32 s39, s43, s39
	s_lshl_b32 s9, s9, 2
	s_and_b32 s9, s9, 0xfc
	s_add_i32 s9, s9, 0x20040
	v_mov_b32_e32 v0, s9
	ds_read_b32 v0, v0
	v_mov_b32_e32 v131, v65
	s_waitcnt lgkmcnt(0)
	v_readfirstlane_b32 s9, v0
	s_nop 1
	v_lshl_or_b32 v140, s9, 6, v214
	s_nop 0
	v_bfe_i32 v2, v140, 27, 1
	v_lshlrev_b32_e32 v0, 4, v140
	v_lshrrev_b32_e32 v2, 22, v2
	v_add_u32_e32 v2, v0, v2
	v_and_b32_e32 v2, 0xfffffc00, v2
	v_sub_u32_e32 v2, v0, v2
	v_ashrrev_i32_e32 v1, 31, v140
	v_lshrrev_b32_e32 v3, 4, v2
	v_lshrrev_b32_e32 v1, 26, v1
	v_bitop3_b32 v3, v3, v2, 32 bitop3:0x6c
	v_ashrrev_i32_e32 v2, 31, v2
	v_add_u32_e32 v1, v140, v1
	v_lshrrev_b32_e32 v2, 26, v2
	v_ashrrev_i32_e32 v1, 6, v1
	v_add_u32_e32 v2, v3, v2
	v_lshlrev_b32_e32 v4, 3, v1
	v_ashrrev_i32_e32 v2, 6, v2
	v_lshlrev_b32_e32 v1, 5, v1
	v_and_b32_e32 v17, 32, v1
	v_mul_i32_i24_e32 v1, 64, v2
	v_sub_u32_e32 v1, v3, v1
	v_add_u32_e32 v3, 0x2000, v0
	v_ashrrev_i32_e32 v5, 31, v3
	v_lshrrev_b32_e32 v5, 22, v5
	v_add_u32_e32 v5, v3, v5
	v_ashrrev_i32_e32 v13, 10, v5
	v_mul_i32_i24_e32 v5, 0x400, v13
	v_sub_u32_e32 v3, v3, v5
	v_lshrrev_b32_e32 v5, 4, v3
	v_bitop3_b32 v3, v5, v3, 32 bitop3:0x6c
	v_ashrrev_i32_e32 v6, 31, v3
	v_lshrrev_b32_e32 v6, 26, v6
	v_and_b32_e32 v4, -16, v4
	v_ashrrev_i16_sdwa v18, v215, sext(v1) dst_sel:DWORD dst_unused:UNUSED_PAD src0_sel:DWORD src1_sel:BYTE_0
	v_lshlrev_b32_e32 v5, 3, v13
	v_add_u32_e32 v6, v3, v6
	v_add_u32_e32 v4, v2, v4
	v_add_u32_sdwa v1, v17, sext(v18) dst_sel:DWORD dst_unused:UNUSED_PAD src0_sel:DWORD src1_sel:WORD_0
	v_and_b32_e32 v5, -16, v5
	v_ashrrev_i32_e32 v14, 6, v6
	v_and_b32_e32 v6, 0xc0, v6
	v_add_u32_e32 v5, v14, v5
	v_sub_u32_e32 v3, v3, v6
	v_lshl_add_u32 v8, v4, 10, v1
	v_and_b32_e32 v19, 0xffffffe0, v4
	v_lshlrev_b32_e32 v6, 1, v4
	v_lshrrev_b32_e32 v4, 2, v4
	v_and_b32_e32 v22, 4, v4
	v_and_b32_e32 v24, 3, v2
	v_lshlrev_b32_e32 v4, 1, v5
	v_lshlrev_b32_e32 v7, 5, v13
	v_and_b32_e32 v21, 24, v6
	v_or_b32_e32 v2, v19, v24
	v_and_b32_e32 v20, 0xffffffe0, v5
	v_and_b32_e32 v23, 24, v4
	v_lshrrev_b32_e32 v4, 2, v5
	v_and_b32_e32 v26, 3, v14
	v_and_b32_e32 v15, 32, v7
	v_ashrrev_i16_sdwa v16, v215, sext(v3) dst_sel:DWORD dst_unused:UNUSED_PAD src0_sel:DWORD src1_sel:BYTE_0
	v_or3_b32 v2, v2, v21, v22
	v_and_b32_e32 v25, 4, v4
	v_or_b32_e32 v4, v20, v26
	v_add_u32_e32 v149, 0, v0
	v_add_u32_sdwa v3, v15, sext(v16) dst_sel:DWORD dst_unused:UNUSED_PAD src0_sel:DWORD src1_sel:WORD_0
	v_or3_b32 v4, v4, v23, v25
	v_lshl_add_u32 v64, v2, 10, v1
	v_add_u32_e32 v150, 0x10000, v149
	v_lshl_add_u32 v130, v5, 10, v3
	v_lshl_add_u32 v2, v4, 10, v3
	v_lshlrev_b64 v[6:7], 1, v[64:65]
	v_readfirstlane_b32 s9, v150
	v_mov_b32_e32 v3, v65
	v_add_u32_e32 v152, 0x12000, v149
	v_lshl_add_u64 v[0:1], s[40:41], 0, v[6:7]
	s_mov_b32 m0, s9
	v_lshlrev_b64 v[28:29], 1, v[2:3]
	v_readfirstlane_b32 s9, v152
	v_mov_b32_e32 v64, v8
	global_load_lds_dwordx4 v[0:1], off
	v_lshl_add_u64 v[2:3], s[40:41], 0, v[28:29]
	s_mov_b32 m0, s9
	v_lshlrev_b64 v[30:31], 1, v[64:65]
	v_readfirstlane_b32 s9, v149
	v_add_u32_e32 v153, 0x2000, v149
	global_load_lds_dwordx4 v[2:3], off
	v_lshl_add_u64 v[4:5], s[28:29], 0, v[30:31]
	s_mov_b32 m0, s9
	v_lshlrev_b64 v[32:33], 1, v[130:131]
	v_readfirstlane_b32 s9, v153
	v_add_u32_e32 v154, 0x14000, v149
	global_load_lds_dwordx4 v[4:5], off
	v_lshl_add_u64 v[8:9], s[28:29], 0, v[32:33]
	s_mov_b32 m0, s9
	v_readfirstlane_b32 s9, v154
	v_add_u32_e32 v155, 0x16000, v149
	global_load_lds_dwordx4 v[8:9], off
	v_lshl_add_u64 v[10:11], s[38:39], 0, v[6:7]
	s_mov_b32 m0, s9
	v_lshl_add_u64 v[6:7], s[38:39], 0, v[28:29]
	v_readfirstlane_b32 s9, v155
	s_add_u32 s38, s28, 0x40000
	v_add_u32_e32 v157, 0x4000, v149
	global_load_lds_dwordx4 v[10:11], off
	s_mov_b32 m0, s9
	s_addc_u32 s39, s29, 0
	v_readfirstlane_b32 s9, v157
	v_add_u32_e32 v158, 0x6000, v149
	global_load_lds_dwordx4 v[6:7], off
	v_lshl_add_u64 v[28:29], s[38:39], 0, v[30:31]
	s_mov_b32 m0, s9
	v_readfirstlane_b32 s9, v158
	global_load_lds_dwordx4 v[28:29], off
	v_lshl_add_u64 v[28:29], s[38:39], 0, v[32:33]
	s_mov_b32 m0, s9
	v_ashrrev_i32_e32 v12, 8, v140
	global_load_lds_dwordx4 v[28:29], off
	v_cmp_eq_u32_e32 vcc, 1, v12
	s_and_saveexec_b64 s[38:39], vcc
	s_cbranch_execz .LBB0_1052
	s_barrier

; DI int my_tid() { int t = tid_raw(); asm volatile("" : "+v"(t)); return t; }
; #define STAGE_A(b, h, kt) { const u16* ap_ = A + (size_t)((h) * ahalf + (unsigned)(kt) * 64u); glds16(ap_ + ao0, l0 + SA_(b, h)); glds16(ap_ + ao1, l0 + SA_(b, h) + 8192); }
; #define STAGE_B(b, h, kt) { const u16* bp_ = ((h) ? B1 : B0) + (unsigned)(kt) * 64u; glds16(bp_ + bo0, l0 + SB_(b, h)); glds16(bp_ + bo1, l0 + SB_(b, h) + 8192); }
; #define WAIT_V(n) asm volatile("s_waitcnt vmcnt(" #n ")" ::: "memory");
; #define BAR __builtin_amdgcn_s_barrier();
; DI void gemm256(const u16* __restrict__ A, int lda, const u16* __restrict__ B0, const u16* __restrict__ B1, int ldb, int nt, acc_t& acc, char* lds) {
;   const int tid = my_tid();
;   const int lane = tid & 63, wid = tid >> 6, wr = wid >> 2, wc = wid & 3, fr = lane & 15, fq = lane >> 4;
;   int r0, c0, r1, c1;
;   stage_rc(tid * 16, r0, c0); stage_rc(tid * 16 + 8192, r1, c1);
;   const unsigned ao0 = (unsigned)(r0 * lda + c0), ao1 = (unsigned)(r1 * lda + c1);
;   const unsigned ahalf = 128u * (unsigned)lda;
;   const int p0 = (r0 & ~31) + (((r0 & 15) >> 2) * 8) + (((r0 >> 4) & 1) * 4) + (r0 & 3), p1 = (r1 & ~31) + (((r1 & 15) >> 2) * 8) + (((r1 >> 4) & 1) * 4) + (r1 & 3);
;   const unsigned bo0 = (unsigned)(p0 * ldb + c0), bo1 = (unsigned)(p1 * ldb + c1);
;   char* l0 = lds + tid * 16;
;     ...
;   bf16x8 At[4][2], Bq0[2][2], Bq1[2][2];
;   WAIT_V(0)
;   STAGE_B(0, 0, 0) STAGE_A(0, 0, 0) STAGE_B(0, 1, 0) STAGE_A(0, 1, 0)
;   if (wr == 1) BAR
;   WAIT_V(4) BAR
;   STAGE_B(1, 0, 1) STAGE_A(1, 0, 1) STAGE_B(1, 1, 1)
;   WAIT_V(6) BAR
; DI void p8_phase(const Params& p, int layer, char* lds) {
;     ...
;   for (int task = blockIdx.x; task < 1408; task += gridDim.x) {
;     acc_t acc; zero_acc(acc);
;     if (task < 1408) {
;       int rt, ct; tile_map(task, 64, 22, rt, ct);
;       const int row0 = rt * 256, ch0 = ct * 128;
;       gemm256(x1b + (size_t)row0 * D, D, wup + (size_t)ch0 * D, wup + (size_t)(DFF + ch0) * D, D, 16, acc, lds);
.LBB0_1169:
	s_ashr_i32 s3, s2, 31
	s_lshr_b32 s3, s3, 29
	s_add_i32 s3, s2, s3
	s_ashr_i32 s7, s3, 3
	s_and_b32 s3, s3, -8
	s_sub_i32 s3, s2, s3
	s_lshr_b32 s8, s3, 31
	s_or_b32 s8, s8, 0xb0
	s_mul_i32 s3, s8, s3
	s_add_i32 s7, s3, s7
	s_mul_hi_i32 s3, s7, 0x2e8ba2e9
	s_lshr_b32 s8, s3, 31
	s_ashr_i32 s19, s3, 5
	s_add_i32 s19, s19, s8
	s_lshl_b32 s3, s19, 3
	s_sub_i32 s8, 64, s3
	s_min_u32 s22, s8, 8
	s_mul_i32 s46, s19, 0xb0
	s_sub_i32 s23, s7, s46
	v_cvt_f32_ubyte0_e32 v1, s22
	v_cvt_f32_i32_e32 v0, s23
	v_rcp_iflag_f32_e32 v2, v1
	s_ashr_i32 s8, s23, 30
	s_or_b32 s28, s8, 1
	v_readlane_b32 s36, v254, 12
	v_mul_f32_e32 v2, v0, v2
	v_trunc_f32_e32 v2, v2
	v_fma_f32 v0, -v2, v1, v0
	v_cvt_i32_f32_e32 v2, v2
	v_cmp_ge_f32_e64 s[8:9], |v0|, v1
	s_and_b64 s[8:9], s[8:9], exec
	s_cselect_b32 s8, s28, 0
	v_readfirstlane_b32 s9, v2
	s_add_i32 s47, s9, s8
	s_sext_i32_i16 s9, s47
	s_mul_i32 s47, s47, s22
	s_sub_i32 s8, s23, s47
	s_sext_i32_i16 s8, s8
	s_add_i32 s3, s3, s8
	s_lshl_b32 s8, s3, 8
	s_lshl_b32 s22, s9, 7
	s_ashr_i32 s9, s8, 31
	s_lshl_b64 s[28:29], s[8:9], 11
	v_readlane_b32 s37, v254, 13
	s_add_u32 s28, s36, s28
	s_addc_u32 s29, s37, s29
	s_ashr_i32 s23, s22, 31
	s_lshl_b64 s[36:37], s[22:23], 11
	v_readlane_b32 s42, v252, 40
	v_readlane_b32 s43, v252, 41
	s_add_u32 s44, s42, s36
	s_addc_u32 s45, s43, s37
	s_add_u32 s42, s44, 0x580000
	s_getreg_b32 s9, hwreg(HW_REG_HW_ID, 0, 6)
	s_addc_u32 s43, s45, 0
	s_lshl_b32 s9, s9, 2
	s_and_b32 s9, s9, 0xfc
	s_add_i32 s9, s9, 0x20040
	v_mov_b32_e32 v0, s9
	ds_read_b32 v0, v0
	v_mov_b32_e32 v131, v65
	s_waitcnt lgkmcnt(0)
	v_readfirstlane_b32 s9, v0
	s_nop 1
	v_lshl_or_b32 v140, s9, 6, v214
	s_nop 0
	v_bfe_i32 v2, v140, 27, 1
	v_lshlrev_b32_e32 v0, 4, v140
	v_lshrrev_b32_e32 v2, 22, v2
	v_add_u32_e32 v2, v0, v2
	v_and_b32_e32 v2, 0xfffffc00, v2
	v_sub_u32_e32 v2, v0, v2
	v_ashrrev_i32_e32 v1, 31, v140
	v_lshrrev_b32_e32 v3, 4, v2
	v_lshrrev_b32_e32 v1, 26, v1
	v_bitop3_b32 v3, v3, v2, 32 bitop3:0x6c
	v_ashrrev_i32_e32 v2, 31, v2
	v_add_u32_e32 v1, v140, v1
	v_lshrrev_b32_e32 v2, 26, v2
	v_ashrrev_i32_e32 v1, 6, v1
	v_add_u32_e32 v2, v3, v2
	v_lshlrev_b32_e32 v4, 3, v1
	v_ashrrev_i32_e32 v2, 6, v2
	v_lshlrev_b32_e32 v1, 5, v1
	v_and_b32_e32 v17, 32, v1
	v_mul_i32_i24_e32 v1, 64, v2
	v_sub_u32_e32 v1, v3, v1
	v_add_u32_e32 v3, 0x2000, v0
	v_ashrrev_i32_e32 v5, 31, v3
	v_lshrrev_b32_e32 v5, 22, v5
	v_add_u32_e32 v5, v3, v5
	v_ashrrev_i32_e32 v13, 10, v5
	v_mul_i32_i24_e32 v5, 0x400, v13
	v_sub_u32_e32 v3, v3, v5
	v_lshrrev_b32_e32 v5, 4, v3
	v_bitop3_b32 v3, v5, v3, 32 bitop3:0x6c
	v_ashrrev_i32_e32 v6, 31, v3
	v_lshrrev_b32_e32 v6, 26, v6
	v_and_b32_e32 v4, -16, v4
	v_ashrrev_i16_sdwa v18, v215, sext(v1) dst_sel:DWORD dst_unused:UNUSED_PAD src0_sel:DWORD src1_sel:BYTE_0
	v_lshlrev_b32_e32 v5, 3, v13
	v_add_u32_e32 v6, v3, v6
	v_add_u32_e32 v4, v2, v4
	v_add_u32_sdwa v1, v17, sext(v18) dst_sel:DWORD dst_unused:UNUSED_PAD src0_sel:DWORD src1_sel:WORD_0
	v_and_b32_e32 v5, -16, v5
	v_ashrrev_i32_e32 v14, 6, v6
	v_and_b32_e32 v6, 0xc0, v6
	v_add_u32_e32 v5, v14, v5
	v_sub_u32_e32 v3, v3, v6
	v_lshl_add_u32 v8, v4, 10, v1
	v_and_b32_e32 v19, 0xffffffe0, v4
	v_lshlrev_b32_e32 v6, 1, v4
	v_lshrrev_b32_e32 v4, 2, v4
	v_and_b32_e32 v22, 4, v4
	v_and_b32_e32 v24, 3, v2
	v_lshlrev_b32_e32 v4, 1, v5
	v_lshlrev_b32_e32 v7, 5, v13
	v_and_b32_e32 v21, 24, v6
	v_or_b32_e32 v2, v19, v24
	v_and_b32_e32 v20, 0xffffffe0, v5
	v_and_b32_e32 v23, 24, v4
	v_lshrrev_b32_e32 v4, 2, v5
	v_and_b32_e32 v26, 3, v14
	v_and_b32_e32 v15, 32, v7
	v_ashrrev_i16_sdwa v16, v215, sext(v3) dst_sel:DWORD dst_unused:UNUSED_PAD src0_sel:DWORD src1_sel:BYTE_0
	v_or3_b32 v2, v2, v21, v22
	v_and_b32_e32 v25, 4, v4
	v_or_b32_e32 v4, v20, v26
	v_add_u32_e32 v149, 0, v0
	v_add_u32_sdwa v3, v15, sext(v16) dst_sel:DWORD dst_unused:UNUSED_PAD src0_sel:DWORD src1_sel:WORD_0
	v_or3_b32 v4, v4, v23, v25
	v_lshl_add_u32 v64, v2, 10, v1
	v_add_u32_e32 v150, 0x10000, v149
	v_lshl_add_u32 v130, v5, 10, v3
	v_lshl_add_u32 v2, v4, 10, v3
	v_lshlrev_b64 v[6:7], 1, v[64:65]
	v_readfirstlane_b32 s9, v150
	v_mov_b32_e32 v3, v65
	v_add_u32_e32 v152, 0x12000, v149
	v_lshl_add_u64 v[0:1], s[44:45], 0, v[6:7]
	s_mov_b32 m0, s9
	v_lshlrev_b64 v[28:29], 1, v[2:3]
	v_readfirstlane_b32 s9, v152
	v_mov_b32_e32 v64, v8
	global_load_lds_dwordx4 v[0:1], off
	v_lshl_add_u64 v[2:3], s[44:45], 0, v[28:29]
	s_mov_b32 m0, s9
	v_lshlrev_b64 v[30:31], 1, v[64:65]
	v_readfirstlane_b32 s9, v149
	v_add_u32_e32 v153, 0x2000, v149
	global_load_lds_dwordx4 v[2:3], off
	v_lshl_add_u64 v[4:5], s[28:29], 0, v[30:31]
	s_mov_b32 m0, s9
	v_lshlrev_b64 v[32:33], 1, v[130:131]
	v_readfirstlane_b32 s9, v153
	v_add_u32_e32 v154, 0x14000, v149
	global_load_lds_dwordx4 v[4:5], off
	v_lshl_add_u64 v[8:9], s[28:29], 0, v[32:33]
	s_mov_b32 m0, s9
	v_readfirstlane_b32 s9, v154
	v_add_u32_e32 v155, 0x16000, v149
	global_load_lds_dwordx4 v[8:9], off
	v_lshl_add_u64 v[10:11], s[42:43], 0, v[6:7]
	s_mov_b32 m0, s9
	v_lshl_add_u64 v[6:7], s[42:43], 0, v[28:29]
	v_readfirstlane_b32 s9, v155
	s_add_u32 s42, s28, 0x40000
	v_add_u32_e32 v157, 0x4000, v149
	global_load_lds_dwordx4 v[10:11], off
	s_mov_b32 m0, s9
	s_addc_u32 s43, s29, 0
	v_readfirstlane_b32 s9, v157
	v_add_u32_e32 v158, 0x6000, v149
	global_load_lds_dwordx4 v[6:7], off
	v_lshl_add_u64 v[28:29], s[42:43], 0, v[30:31]
	s_mov_b32 m0, s9
	v_readfirstlane_b32 s9, v158
	global_load_lds_dwordx4 v[28:29], off
	v_lshl_add_u64 v[28:29], s[42:43], 0, v[32:33]
	s_mov_b32 m0, s9
	v_ashrrev_i32_e32 v12, 8, v140
	global_load_lds_dwordx4 v[28:29], off
	v_cmp_eq_u32_e32 vcc, 1, v12
	s_and_saveexec_b64 s[42:43], vcc
	s_cbranch_execz .LBB0_1171
	s_barrier

; DI int my_tid() { int t = tid_raw(); asm volatile("" : "+v"(t)); return t; }
; #define STAGE_A(b, h, kt) { const u16* ap_ = A + (size_t)((h) * ahalf + (unsigned)(kt) * 64u); glds16(ap_ + ao0, l0 + SA_(b, h)); glds16(ap_ + ao1, l0 + SA_(b, h) + 8192); }
; #define STAGE_B(b, h, kt) { const u16* bp_ = ((h) ? B1 : B0) + (unsigned)(kt) * 64u; glds16(bp_ + bo0, l0 + SB_(b, h)); glds16(bp_ + bo1, l0 + SB_(b, h) + 8192); }
; #define WAIT_V(n) asm volatile("s_waitcnt vmcnt(" #n ")" ::: "memory");
; #define BAR __builtin_amdgcn_s_barrier();
; DI void gemm256(const u16* __restrict__ A, int lda, const u16* __restrict__ B0, const u16* __restrict__ B1, int ldb, int nt, acc_t& acc, char* lds) {
;   const int tid = my_tid();
;   const int lane = tid & 63, wid = tid >> 6, wr = wid >> 2, wc = wid & 3, fr = lane & 15, fq = lane >> 4;
;   int r0, c0, r1, c1;
;   stage_rc(tid * 16, r0, c0); stage_rc(tid * 16 + 8192, r1, c1);
;   const unsigned ao0 = (unsigned)(r0 * lda + c0), ao1 = (unsigned)(r1 * lda + c1);
;   const unsigned ahalf = 128u * (unsigned)lda;
;   const int p0 = (r0 & ~31) + (((r0 & 15) >> 2) * 8) + (((r0 >> 4) & 1) * 4) + (r0 & 3), p1 = (r1 & ~31) + (((r1 & 15) >> 2) * 8) + (((r1 >> 4) & 1) * 4) + (r1 & 3);
;   const unsigned bo0 = (unsigned)(p0 * ldb + c0), bo1 = (unsigned)(p1 * ldb + c1);
;   char* l0 = lds + tid * 16;
;     ...
;   bf16x8 At[4][2], Bq0[2][2], Bq1[2][2];
;   WAIT_V(0)
;   STAGE_B(0, 0, 0) STAGE_A(0, 0, 0) STAGE_B(0, 1, 0) STAGE_A(0, 1, 0)
;   if (wr == 1) BAR
;   WAIT_V(4) BAR
;   STAGE_B(1, 0, 1) STAGE_A(1, 0, 1) STAGE_B(1, 1, 1)
;   WAIT_V(6) BAR
; DI void p10_phase(const Params& p, int layer, u16* dst, char* lds) {
;     ...
;     gemm256((const u16*)(ws + OFF_PB) + (size_t)row0 * PLE, PLE, (const u16*)(ws + OFF_WPE) + (size_t)col0 * PLE, (const u16*)(ws + OFF_WPE) + (size_t)(col0 + 128) * PLE, PLE, 4, acc, lds);
.LBB0_1253:
	s_or_b64 exec, exec, s[8:9]
	s_lshl_b32 s36, s52, 8
	s_sext_i32_i8 s2, s2
	s_ashr_i32 s37, s36, 31
	s_lshl_b32 s42, s2, 8
	s_lshl_b64 s[8:9], s[36:37], 9
	v_readlane_b32 s22, v252, 42
	v_readlane_b32 s23, v252, 43
	s_add_u32 s22, s22, s8
	s_addc_u32 s23, s23, s9
	s_ashr_i32 s43, s42, 31
	s_lshl_b64 s[8:9], s[42:43], 9
	s_add_u32 s44, s82, s8
	s_addc_u32 s45, s83, s9
	s_or_b32 s8, s42, 0x80
	s_ashr_i32 s9, s8, 31
	s_lshl_b64 s[28:29], s[8:9], 9
	s_waitcnt vmcnt(0)
	s_barrier
	s_add_u32 s28, s82, s28
	s_getreg_b32 s2, hwreg(HW_REG_HW_ID, 0, 6)
	s_addc_u32 s29, s83, s29
	s_lshl_b32 s2, s2, 2
	s_and_b32 s2, s2, 0xfc
	s_add_i32 s2, s2, 0x20040
	v_mov_b32_e32 v0, s2
	ds_read_b32 v0, v0
	s_waitcnt lgkmcnt(0)
	v_readfirstlane_b32 s2, v0
	s_nop 1
	v_lshl_or_b32 v130, s2, 6, v214
	s_nop 0
	v_bfe_i32 v2, v130, 27, 1
	v_lshlrev_b32_e32 v1, 4, v130
	v_lshrrev_b32_e32 v2, 22, v2
	v_add_u32_e32 v2, v1, v2
	v_and_b32_e32 v2, 0xfffffc00, v2
	v_sub_u32_e32 v2, v1, v2
	v_lshrrev_b32_e32 v3, 4, v2
	v_bitop3_b32 v3, v3, v2, 32 bitop3:0x6c
	v_ashrrev_i32_e32 v2, 31, v2
	v_ashrrev_i32_e32 v0, 31, v130
	v_lshrrev_b32_e32 v2, 26, v2
	v_lshrrev_b32_e32 v0, 26, v0
	v_add_u32_e32 v2, v3, v2
	v_add_u32_e32 v0, v130, v0
	v_ashrrev_i32_e32 v5, 6, v2
	v_ashrrev_i32_e32 v0, 6, v0
	v_mul_i32_i24_e32 v2, 64, v5
	v_lshlrev_b32_e32 v4, 3, v0
	v_lshlrev_b32_e32 v0, 5, v0
	v_sub_u32_e32 v2, v3, v2
	v_and_b32_e32 v0, 32, v0
	v_ashrrev_i16_sdwa v2, v215, sext(v2) dst_sel:DWORD dst_unused:UNUSED_PAD src0_sel:DWORD src1_sel:BYTE_0
	v_add_u32_sdwa v3, v0, sext(v2) dst_sel:DWORD dst_unused:UNUSED_PAD src0_sel:DWORD src1_sel:WORD_0
	v_add_u32_e32 v0, 0x2000, v1
	v_ashrrev_i32_e32 v2, 31, v0
	v_lshrrev_b32_e32 v2, 22, v2
	v_add_u32_e32 v2, v0, v2
	v_ashrrev_i32_e32 v2, 10, v2
	v_mul_i32_i24_e32 v6, 0x400, v2
	v_sub_u32_e32 v0, v0, v6
	v_lshrrev_b32_e32 v6, 4, v0
	v_bitop3_b32 v0, v6, v0, 32 bitop3:0x6c
	v_ashrrev_i32_e32 v7, 31, v0
	v_lshrrev_b32_e32 v7, 26, v7
	v_add_u32_e32 v7, v0, v7
	v_and_b32_e32 v4, -16, v4
	v_ashrrev_i32_e32 v8, 6, v7
	v_and_b32_e32 v7, 0xc0, v7
	v_add_u32_e32 v4, v5, v4
	v_lshlrev_b32_e32 v6, 3, v2
	v_lshlrev_b32_e32 v2, 5, v2
	v_sub_u32_e32 v0, v0, v7
	v_and_b32_e32 v6, -16, v6
	v_and_b32_e32 v2, 32, v2
	v_ashrrev_i16_sdwa v0, v215, sext(v0) dst_sel:DWORD dst_unused:UNUSED_PAD src0_sel:DWORD src1_sel:BYTE_0
	v_lshlrev_b32_e32 v9, 1, v4
	v_lshrrev_b32_e32 v10, 2, v4
	v_and_b32_e32 v5, 3, v5
	v_add_u32_e32 v6, v8, v6
	v_add_u32_sdwa v7, v2, sext(v0) dst_sel:DWORD dst_unused:UNUSED_PAD src0_sel:DWORD src1_sel:WORD_0
	v_lshl_add_u32 v0, v4, 8, v3
	v_and_b32_e32 v9, 24, v9
	v_and_b32_e32 v10, 4, v10
	v_and_or_b32 v4, v4, s68, v5
	v_or3_b32 v4, v4, v9, v10
	v_lshlrev_b32_e32 v5, 1, v6
	v_lshrrev_b32_e32 v9, 2, v6
	v_and_b32_e32 v8, 3, v8
	v_lshl_add_u32 v2, v6, 8, v7
	v_and_b32_e32 v5, 24, v5
	v_and_b32_e32 v9, 4, v9
	v_and_or_b32 v6, v6, s68, v8
	v_add_u32_e32 v20, 0, v1
	v_or3_b32 v5, v6, v5, v9
	v_lshl_add_u32 v64, v4, 8, v3
	v_add_u32_e32 v24, 0x10000, v20
	v_lshl_add_u32 v4, v5, 8, v7
	v_lshlrev_b64 v[6:7], 1, v[64:65]
	v_readfirstlane_b32 s2, v24
	v_mov_b32_e32 v5, v65
	v_add_u32_e32 v25, 0x12000, v20
	v_lshl_add_u64 v[12:13], s[44:45], 0, v[6:7]
	s_mov_b32 m0, s2
	v_lshlrev_b64 v[18:19], 1, v[4:5]
	v_readfirstlane_b32 s2, v25
	v_mov_b32_e32 v1, v65
	global_load_lds_dwordx4 v[12:13], off
	v_lshl_add_u64 v[14:15], s[44:45], 0, v[18:19]
	s_mov_b32 m0, s2
	v_lshlrev_b64 v[0:1], 1, v[0:1]
	v_readfirstlane_b32 s2, v20
	v_mov_b32_e32 v3, v65
	v_add_u32_e32 v23, 0x2000, v20
	global_load_lds_dwordx4 v[14:15], off
	v_lshl_add_u64 v[8:9], s[22:23], 0, v[0:1]
	s_mov_b32 m0, s2
	v_lshlrev_b64 v[2:3], 1, v[2:3]
	v_readfirstlane_b32 s2, v23
	v_add_u32_e32 v21, 0x14000, v20
	global_load_lds_dwordx4 v[8:9], off
	v_lshl_add_u64 v[10:11], s[22:23], 0, v[2:3]
	s_mov_b32 m0, s2
	v_readfirstlane_b32 s2, v21
	v_add_u32_e32 v22, 0x16000, v20
	global_load_lds_dwordx4 v[10:11], off
	v_lshl_add_u64 v[4:5], s[28:29], 0, v[6:7]
	s_mov_b32 m0, s2
	v_lshl_add_u64 v[6:7], s[28:29], 0, v[18:19]
	v_readfirstlane_b32 s2, v22
	s_add_u32 s28, s22, 0x10000
	v_add_u32_e32 v18, 0x4000, v20
	global_load_lds_dwordx4 v[4:5], off
	s_mov_b32 m0, s2
	s_addc_u32 s29, s23, 0
	v_readfirstlane_b32 s2, v18
	v_add_u32_e32 v19, 0x6000, v20
	global_load_lds_dwordx4 v[6:7], off
	v_lshl_add_u64 v[26:27], s[28:29], 0, v[0:1]
	s_mov_b32 m0, s2
	v_readfirstlane_b32 s2, v19
	global_load_lds_dwordx4 v[26:27], off
	v_lshl_add_u64 v[26:27], s[28:29], 0, v[2:3]
	s_mov_b32 m0, s2
	v_ashrrev_i32_e32 v16, 8, v130
	global_load_lds_dwordx4 v[26:27], off
	v_cmp_eq_u32_e32 vcc, 1, v16
	s_and_saveexec_b64 s[28:29], vcc
	s_cbranch_execz .LBB0_1255
	s_barrier

; DI unsigned pk_f16(float lo, float hi) { f32x2_t v = {lo, hi}; return __builtin_bit_cast(unsigned, __builtin_convertvector(v, f16x2_t)); }
; #define EPI_FOR _Pragma("unroll") for (int m = 0; m < 8; ++m) _Pragma("unroll") for (int n = 0; n < 4; ++n)
; DI void p10_phase(const Params& p, int layer, u16* dst, char* lds) {
;     ...
;     EPI_FOR {
;       u32x2 o; o[0] = pk_f16(ACC(m, n)[0], ACC(m, n)[1]); o[1] = pk_f16(ACC(m, n)[2], ACC(m, n)[3]);
;       tp[(m * 4 + n) * 512 + tid] = o;
;     }
.LBB0_1257:
	s_or_b64 exec, exec, s[22:23]
	s_waitcnt vmcnt(0)
	s_barrier
	s_getreg_b32 s2, hwreg(HW_REG_HW_ID, 0, 6)
	s_lshl_b32 s2, s2, 2
	s_and_b32 s2, s2, 0xfc
	s_add_i32 s2, s2, 0x20040
	v_mov_b32_e32 v64, s2
	ds_read_b32 v64, v64
	v_cvt_pk_f16_f32 v130, v122, v123
	v_cvt_pk_f16_f32 v48, v48, v49
	v_cvt_pk_f16_f32 v49, v50, v51
	v_cvt_pk_f16_f32 v114, v114, v115
	s_waitcnt lgkmcnt(0)
	v_readfirstlane_b32 s2, v64
	v_cvt_pk_f16_f32 v115, v116, v117
	v_cvt_pk_f16_f32 v98, v98, v99
	v_lshl_or_b32 v122, s2, 6, v214
	v_cvt_pk_f16_f32 v99, v100, v101
	v_add_u32_e32 v50, 0x1a00, v122
	v_ashrrev_i32_e32 v51, 31, v50
	v_lshl_add_u64 v[50:51], v[50:51], 3, s[16:17]
	global_store_dwordx2 v[50:51], v[48:49], off
	v_add_u32_e32 v50, 0x1c00, v122
	v_ashrrev_i32_e32 v51, 31, v50
	v_cvt_pk_f16_f32 v48, v78, v79
	v_cvt_pk_f16_f32 v49, v80, v81
	v_lshl_add_u64 v[50:51], v[50:51], 3, s[16:17]
	global_store_dwordx2 v[50:51], v[48:49], off
	v_add_u32_e32 v50, 0x1e00, v122
	v_ashrrev_i32_e32 v51, 31, v50
	v_cvt_pk_f16_f32 v48, v60, v61
	v_cvt_pk_f16_f32 v49, v62, v63
	v_lshl_add_u64 v[50:51], v[50:51], 3, s[16:17]
	global_store_dwordx2 v[50:51], v[48:49], off
	v_add_u32_e32 v48, 0x2000, v122
	v_ashrrev_i32_e32 v49, 31, v48
	v_cvt_pk_f16_f32 v50, v74, v75
	v_cvt_pk_f16_f32 v51, v76, v77
	v_lshl_add_u64 v[48:49], v[48:49], 3, s[16:17]
	v_add_u32_e32 v116, 0x200, v122
	v_add_u32_e32 v100, 0xa00, v122
	v_cvt_pk_f16_f32 v82, v82, v83
	v_cvt_pk_f16_f32 v83, v84, v85
	v_add_u32_e32 v84, 0x1200, v122
	global_store_dwordx2 v[48:49], v[50:51], off
	v_add_u32_e32 v50, 0x2200, v122
	v_ashrrev_i32_e32 v117, 31, v116
	v_ashrrev_i32_e32 v101, 31, v100
	v_ashrrev_i32_e32 v85, 31, v84
	v_ashrrev_i32_e32 v51, 31, v50
	v_lshl_add_u64 v[116:117], v[116:117], 3, s[16:17]
	v_lshl_add_u64 v[100:101], v[100:101], 3, s[16:17]
	v_lshl_add_u64 v[84:85], v[84:85], 3, s[16:17]
	v_cvt_pk_f16_f32 v48, v56, v57
	v_cvt_pk_f16_f32 v49, v58, v59
	v_lshl_add_u64 v[50:51], v[50:51], 3, s[16:17]
	global_store_dwordx2 v[116:117], v[114:115], off
	v_add_u32_e32 v116, 0x400, v122
	global_store_dwordx2 v[100:101], v[98:99], off
	v_add_u32_e32 v100, 0xc00, v122
	global_store_dwordx2 v[84:85], v[82:83], off
	v_add_u32_e32 v84, 0x1400, v122
	global_store_dwordx2 v[50:51], v[48:49], off
	v_add_u32_e32 v50, 0x2400, v122
	v_ashrrev_i32_e32 v117, 31, v116
	v_ashrrev_i32_e32 v101, 31, v100
	v_ashrrev_i32_e32 v85, 31, v84
	v_ashrrev_i32_e32 v51, 31, v50
	v_cvt_pk_f16_f32 v114, v126, v127
	v_cvt_pk_f16_f32 v115, v128, v129
	v_lshl_add_u64 v[116:117], v[116:117], 3, s[16:17]
	v_cvt_pk_f16_f32 v98, v110, v111
	v_cvt_pk_f16_f32 v99, v112, v113
	v_lshl_add_u64 v[100:101], v[100:101], 3, s[16:17]
	v_cvt_pk_f16_f32 v82, v94, v95
	v_cvt_pk_f16_f32 v83, v96, v97
	v_lshl_add_u64 v[84:85], v[84:85], 3, s[16:17]
	v_cvt_pk_f16_f32 v48, v70, v71
	v_cvt_pk_f16_f32 v49, v72, v73
	v_lshl_add_u64 v[50:51], v[50:51], 3, s[16:17]
	global_store_dwordx2 v[116:117], v[114:115], off
	v_add_u32_e32 v116, 0x600, v122
	global_store_dwordx2 v[100:101], v[98:99], off
	v_add_u32_e32 v100, 0xe00, v122
	global_store_dwordx2 v[84:85], v[82:83], off
	v_add_u32_e32 v84, 0x1600, v122
	global_store_dwordx2 v[50:51], v[48:49], off
	v_add_u32_e32 v50, 0x2600, v122
	v_cvt_pk_f16_f32 v36, v36, v37
	v_cvt_pk_f16_f32 v37, v38, v39
	v_add_u32_e32 v38, 0x2a00, v122
	v_cvt_pk_f16_f32 v32, v32, v33
	v_cvt_pk_f16_f32 v33, v34, v35
	v_add_u32_e32 v34, 0x2e00, v122
	v_cvt_pk_f16_f32 v20, v20, v21
	v_cvt_pk_f16_f32 v21, v22, v23
	v_add_u32_e32 v22, 0x3200, v122
	v_cvt_pk_f16_f32 v16, v16, v17
	v_cvt_pk_f16_f32 v17, v18, v19
	v_add_u32_e32 v18, 0x3600, v122
	v_cvt_pk_f16_f32 v4, v4, v5
	v_cvt_pk_f16_f32 v5, v6, v7
	v_add_u32_e32 v6, 0x3a00, v122
	v_ashrrev_i32_e32 v117, 31, v116
	v_ashrrev_i32_e32 v101, 31, v100
	v_ashrrev_i32_e32 v85, 31, v84
	v_ashrrev_i32_e32 v51, 31, v50
	v_ashrrev_i32_e32 v39, 31, v38
	v_ashrrev_i32_e32 v35, 31, v34
	v_ashrrev_i32_e32 v23, 31, v22
	v_ashrrev_i32_e32 v19, 31, v18
	v_ashrrev_i32_e32 v7, 31, v6
	s_lshl_b64 s[22:23], s[36:37], 11
	v_readlane_b32 s28, v254, 12
	v_cvt_pk_f16_f32 v114, v118, v119
	v_cvt_pk_f16_f32 v115, v120, v121
	v_lshl_add_u64 v[116:117], v[116:117], 3, s[16:17]
	v_cvt_pk_f16_f32 v98, v102, v103
	v_cvt_pk_f16_f32 v99, v104, v105
	v_lshl_add_u64 v[100:101], v[100:101], 3, s[16:17]
	v_cvt_pk_f16_f32 v82, v86, v87
	v_cvt_pk_f16_f32 v83, v88, v89
	v_lshl_add_u64 v[84:85], v[84:85], 3, s[16:17]
	v_cvt_pk_f16_f32 v48, v52, v53
	v_cvt_pk_f16_f32 v49, v54, v55
	v_lshl_add_u64 v[50:51], v[50:51], 3, s[16:17]
	v_lshl_add_u64 v[38:39], v[38:39], 3, s[16:17]
	v_lshl_add_u64 v[34:35], v[34:35], 3, s[16:17]
	v_lshl_add_u64 v[22:23], v[22:23], 3, s[16:17]
	v_lshl_add_u64 v[18:19], v[18:19], 3, s[16:17]
	v_lshl_add_u64 v[6:7], v[6:7], 3, s[16:17]
	v_readlane_b32 s29, v254, 13
	s_add_u32 s22, s28, s22
	global_store_dwordx2 v[116:117], v[114:115], off
	v_add_u32_e32 v114, 0x800, v122
	global_store_dwordx2 v[100:101], v[98:99], off
	v_add_u32_e32 v98, 0x1000, v122
	global_store_dwordx2 v[84:85], v[82:83], off
	v_add_u32_e32 v82, 0x1800, v122
	global_store_dwordx2 v[50:51], v[48:49], off
	v_add_u32_e32 v48, 0x2800, v122
	global_store_dwordx2 v[38:39], v[36:37], off
	v_add_u32_e32 v38, 0x2c00, v122
	global_store_dwordx2 v[34:35], v[32:33], off
	v_add_u32_e32 v32, 0x3000, v122
	global_store_dwordx2 v[22:23], v[20:21], off
	v_add_u32_e32 v22, 0x3400, v122
	global_store_dwordx2 v[18:19], v[16:17], off
	v_add_u32_e32 v16, 0x3800, v122
	global_store_dwordx2 v[6:7], v[4:5], off
	v_add_u32_e32 v6, 0x3c00, v122
	v_cvt_pk_f16_f32 v0, v0, v1
	v_cvt_pk_f16_f32 v1, v2, v3
	v_add_u32_e32 v2, 0x3e00, v122
	s_addc_u32 s23, s29, s23
; DI unsigned pk_f16(float lo, float hi) { f32x2_t v = {lo, hi}; return __builtin_bit_cast(unsigned, __builtin_convertvector(v, f16x2_t)); }
; DI int my_tid() { int t = tid_raw(); asm volatile("" : "+v"(t)); return t; }
; #define STAGE_A(b, h, kt) { const u16* ap_ = A + (size_t)((h) * ahalf + (unsigned)(kt) * 64u); glds16(ap_ + ao0, l0 + SA_(b, h)); glds16(ap_ + ao1, l0 + SA_(b, h) + 8192); }
; #define STAGE_B(b, h, kt) { const u16* bp_ = ((h) ? B1 : B0) + (unsigned)(kt) * 64u; glds16(bp_ + bo0, l0 + SB_(b, h)); glds16(bp_ + bo1, l0 + SB_(b, h) + 8192); }
; #define WAIT_V(n) asm volatile("s_waitcnt vmcnt(" #n ")" ::: "memory");
; #define BAR __builtin_amdgcn_s_barrier();
; #define EPI_FOR _Pragma("unroll") for (int m = 0; m < 8; ++m) _Pragma("unroll") for (int n = 0; n < 4; ++n)
; DI void gemm256(const u16* __restrict__ A, int lda, const u16* __restrict__ B0, const u16* __restrict__ B1, int ldb, int nt, acc_t& acc, char* lds) {
;   const int tid = my_tid();
;   const int lane = tid & 63, wid = tid >> 6, wr = wid >> 2, wc = wid & 3, fr = lane & 15, fq = lane >> 4;
;   int r0, c0, r1, c1;
;   stage_rc(tid * 16, r0, c0); stage_rc(tid * 16 + 8192, r1, c1);
;   const unsigned ao0 = (unsigned)(r0 * lda + c0), ao1 = (unsigned)(r1 * lda + c1);
;   const unsigned ahalf = 128u * (unsigned)lda;
;   const int p0 = (r0 & ~31) + (((r0 & 15) >> 2) * 8) + (((r0 >> 4) & 1) * 4) + (r0 & 3), p1 = (r1 & ~31) + (((r1 & 15) >> 2) * 8) + (((r1 >> 4) & 1) * 4) + (r1 & 3);
;   const unsigned bo0 = (unsigned)(p0 * ldb + c0), bo1 = (unsigned)(p1 * ldb + c1);
;   char* l0 = lds + tid * 16;
;     ...
;   bf16x8 At[4][2], Bq0[2][2], Bq1[2][2];
;   WAIT_V(0)
;   STAGE_B(0, 0, 0) STAGE_A(0, 0, 0) STAGE_B(0, 1, 0) STAGE_A(0, 1, 0)
;   if (wr == 1) BAR
;   WAIT_V(4) BAR
;   STAGE_B(1, 0, 1) STAGE_A(1, 0, 1) STAGE_B(1, 1, 1)
;   WAIT_V(6) BAR
; DI void p10_phase(const Params& p, int layer, u16* dst, char* lds) {
;     ...
;     EPI_FOR {
;       u32x2 o; o[0] = pk_f16(ACC(m, n)[0], ACC(m, n)[1]); o[1] = pk_f16(ACC(m, n)[2], ACC(m, n)[3]);
;       tp[(m * 4 + n) * 512 + tid] = o;
;     }
	s_lshl_b64 s[28:29], s[42:43], 11
	v_readlane_b32 s54, v252, 34
	v_ashrrev_i32_e32 v123, 31, v122
	v_ashrrev_i32_e32 v115, 31, v114
	v_ashrrev_i32_e32 v99, 31, v98
	v_ashrrev_i32_e32 v83, 31, v82
	v_ashrrev_i32_e32 v49, 31, v48
	v_ashrrev_i32_e32 v39, 31, v38
	v_ashrrev_i32_e32 v33, 31, v32
	v_ashrrev_i32_e32 v23, 31, v22
	v_ashrrev_i32_e32 v17, 31, v16
	v_ashrrev_i32_e32 v7, 31, v6
	v_ashrrev_i32_e32 v3, 31, v2
	v_readlane_b32 s55, v252, 35
	s_add_u32 s46, s54, s28
	v_cvt_pk_f16_f32 v131, v124, v125
	v_lshl_add_u64 v[124:125], v[122:123], 3, s[16:17]
	v_cvt_pk_f16_f32 v106, v106, v107
	v_cvt_pk_f16_f32 v107, v108, v109
	v_lshl_add_u64 v[108:109], v[114:115], 3, s[16:17]
	v_cvt_pk_f16_f32 v90, v90, v91
	v_cvt_pk_f16_f32 v91, v92, v93
	v_lshl_add_u64 v[92:93], v[98:99], 3, s[16:17]
	v_cvt_pk_f16_f32 v66, v66, v67
	v_cvt_pk_f16_f32 v67, v68, v69
	v_lshl_add_u64 v[68:69], v[82:83], 3, s[16:17]
	v_cvt_pk_f16_f32 v44, v44, v45
	v_cvt_pk_f16_f32 v45, v46, v47
	v_lshl_add_u64 v[46:47], v[48:49], 3, s[16:17]
	v_cvt_pk_f16_f32 v36, v40, v41
	v_cvt_pk_f16_f32 v37, v42, v43
	v_lshl_add_u64 v[38:39], v[38:39], 3, s[16:17]
	v_cvt_pk_f16_f32 v28, v28, v29
	v_cvt_pk_f16_f32 v29, v30, v31
	v_lshl_add_u64 v[30:31], v[32:33], 3, s[16:17]
	v_cvt_pk_f16_f32 v20, v24, v25
	v_cvt_pk_f16_f32 v21, v26, v27
	v_lshl_add_u64 v[22:23], v[22:23], 3, s[16:17]
	v_cvt_pk_f16_f32 v12, v12, v13
	v_cvt_pk_f16_f32 v13, v14, v15
	v_lshl_add_u64 v[14:15], v[16:17], 3, s[16:17]
	v_cvt_pk_f16_f32 v4, v8, v9
	v_cvt_pk_f16_f32 v5, v10, v11
	v_lshl_add_u64 v[6:7], v[6:7], 3, s[16:17]
	v_lshl_add_u64 v[2:3], v[2:3], 3, s[16:17]
	s_addc_u32 s47, s55, s29
	s_lshl_b64 s[44:45], s[8:9], 11
	global_store_dwordx2 v[124:125], v[130:131], off
	global_store_dwordx2 v[108:109], v[106:107], off
	global_store_dwordx2 v[92:93], v[90:91], off
	global_store_dwordx2 v[68:69], v[66:67], off
	global_store_dwordx2 v[46:47], v[44:45], off
	global_store_dwordx2 v[38:39], v[36:37], off
	global_store_dwordx2 v[30:31], v[28:29], off
	global_store_dwordx2 v[22:23], v[20:21], off
	global_store_dwordx2 v[14:15], v[12:13], off
	global_store_dwordx2 v[6:7], v[4:5], off
	global_store_dwordx2 v[2:3], v[0:1], off
	s_add_u32 s44, s54, s44
	s_getreg_b32 s2, hwreg(HW_REG_HW_ID, 0, 6)
	s_addc_u32 s45, s55, s45
	s_lshl_b32 s2, s2, 2
	s_and_b32 s2, s2, 0xfc
	s_add_i32 s2, s2, 0x20040
	v_mov_b32_e32 v0, s2
	ds_read_b32 v0, v0
	v_mov_b32_e32 v131, v65
	s_waitcnt lgkmcnt(0)
	v_readfirstlane_b32 s2, v0
	s_nop 1
	v_lshl_or_b32 v146, s2, 6, v214
	s_nop 0
	v_bfe_i32 v2, v146, 27, 1
	v_lshlrev_b32_e32 v0, 4, v146
	v_lshrrev_b32_e32 v2, 22, v2
	v_add_u32_e32 v2, v0, v2
	v_and_b32_e32 v2, 0xfffffc00, v2
	v_sub_u32_e32 v2, v0, v2
	v_ashrrev_i32_e32 v1, 31, v146
	v_lshrrev_b32_e32 v3, 4, v2
	v_lshrrev_b32_e32 v1, 26, v1
	v_bitop3_b32 v3, v3, v2, 32 bitop3:0x6c
	v_ashrrev_i32_e32 v2, 31, v2
	v_add_u32_e32 v1, v146, v1
	v_lshrrev_b32_e32 v2, 26, v2
	v_ashrrev_i32_e32 v1, 6, v1
	v_add_u32_e32 v2, v3, v2
	v_lshlrev_b32_e32 v4, 3, v1
	v_ashrrev_i32_e32 v2, 6, v2
	v_lshlrev_b32_e32 v1, 5, v1
	v_and_b32_e32 v16, 32, v1
	v_mul_i32_i24_e32 v1, 64, v2
	v_sub_u32_e32 v1, v3, v1
	v_add_u32_e32 v3, 0x2000, v0
	v_ashrrev_i32_e32 v5, 31, v3
	v_lshrrev_b32_e32 v5, 22, v5
	v_add_u32_e32 v5, v3, v5
	v_ashrrev_i32_e32 v12, 10, v5
	v_mul_i32_i24_e32 v5, 0x400, v12
	v_sub_u32_e32 v3, v3, v5
	v_lshrrev_b32_e32 v5, 4, v3
	v_bitop3_b32 v3, v5, v3, 32 bitop3:0x6c
	v_ashrrev_i32_e32 v6, 31, v3
	v_lshrrev_b32_e32 v6, 26, v6
	v_and_b32_e32 v4, -16, v4
	v_ashrrev_i16_sdwa v17, v215, sext(v1) dst_sel:DWORD dst_unused:UNUSED_PAD src0_sel:DWORD src1_sel:BYTE_0
	v_lshlrev_b32_e32 v5, 3, v12
	v_add_u32_e32 v6, v3, v6
	v_add_u32_e32 v4, v2, v4
	v_add_u32_sdwa v1, v16, sext(v17) dst_sel:DWORD dst_unused:UNUSED_PAD src0_sel:DWORD src1_sel:WORD_0
	v_and_b32_e32 v5, -16, v5
	v_ashrrev_i32_e32 v13, 6, v6
	v_and_b32_e32 v6, 0xc0, v6
	v_add_u32_e32 v5, v13, v5
	v_sub_u32_e32 v3, v3, v6
	v_lshl_add_u32 v8, v4, 10, v1
	v_and_b32_e32 v18, 0xffffffe0, v4
	v_lshlrev_b32_e32 v6, 1, v4
	v_lshrrev_b32_e32 v4, 2, v4
	v_and_b32_e32 v21, 4, v4
	v_and_b32_e32 v23, 3, v2
	v_lshlrev_b32_e32 v4, 1, v5
	v_lshlrev_b32_e32 v7, 5, v12
	v_and_b32_e32 v20, 24, v6
	v_or_b32_e32 v2, v18, v23
	v_and_b32_e32 v19, 0xffffffe0, v5
	v_and_b32_e32 v22, 24, v4
	v_lshrrev_b32_e32 v4, 2, v5
	v_and_b32_e32 v25, 3, v13
	v_and_b32_e32 v14, 32, v7
	v_ashrrev_i16_sdwa v15, v215, sext(v3) dst_sel:DWORD dst_unused:UNUSED_PAD src0_sel:DWORD src1_sel:BYTE_0
	v_or3_b32 v2, v2, v20, v21
	v_and_b32_e32 v24, 4, v4
	v_or_b32_e32 v4, v19, v25
	v_add_u32_e32 v140, 0, v0
	v_add_u32_sdwa v3, v14, sext(v15) dst_sel:DWORD dst_unused:UNUSED_PAD src0_sel:DWORD src1_sel:WORD_0
	v_or3_b32 v4, v4, v22, v24
	v_lshl_add_u32 v64, v2, 10, v1
	v_add_u32_e32 v141, 0x10000, v140
	v_lshl_add_u32 v130, v5, 10, v3
	v_lshl_add_u32 v2, v4, 10, v3
	v_lshlrev_b64 v[6:7], 1, v[64:65]
	v_readfirstlane_b32 s2, v141
	v_mov_b32_e32 v3, v65
	v_add_u32_e32 v152, 0x12000, v140
	v_lshl_add_u64 v[0:1], s[46:47], 0, v[6:7]
	s_mov_b32 m0, s2
	v_lshlrev_b64 v[26:27], 1, v[2:3]
	v_readfirstlane_b32 s2, v152
	v_mov_b32_e32 v64, v8
	global_load_lds_dwordx4 v[0:1], off
	v_lshl_add_u64 v[2:3], s[46:47], 0, v[26:27]
	s_mov_b32 m0, s2
	v_lshlrev_b64 v[28:29], 1, v[64:65]
	v_readfirstlane_b32 s2, v140
	v_add_u32_e32 v153, 0x2000, v140
	global_load_lds_dwordx4 v[2:3], off
	v_lshl_add_u64 v[4:5], s[22:23], 0, v[28:29]
	s_mov_b32 m0, s2
	v_lshlrev_b64 v[30:31], 1, v[130:131]
	v_readfirstlane_b32 s2, v153
	v_add_u32_e32 v154, 0x14000, v140
	global_load_lds_dwordx4 v[4:5], off
	v_lshl_add_u64 v[8:9], s[22:23], 0, v[30:31]
	s_mov_b32 m0, s2
	v_readfirstlane_b32 s2, v154
	v_add_u32_e32 v155, 0x16000, v140
	global_load_lds_dwordx4 v[8:9], off
	v_lshl_add_u64 v[10:11], s[44:45], 0, v[6:7]
	s_mov_b32 m0, s2
	v_lshl_add_u64 v[6:7], s[44:45], 0, v[26:27]
	v_readfirstlane_b32 s2, v155
	s_add_u32 s44, s22, 0x40000
	v_add_u32_e32 v157, 0x4000, v140
	global_load_lds_dwordx4 v[10:11], off
	s_mov_b32 m0, s2
	s_addc_u32 s45, s23, 0
	v_readfirstlane_b32 s2, v157
	v_add_u32_e32 v158, 0x6000, v140
	global_load_lds_dwordx4 v[6:7], off
	v_lshl_add_u64 v[26:27], s[44:45], 0, v[28:29]
	s_mov_b32 m0, s2
	v_readfirstlane_b32 s2, v158
	global_load_lds_dwordx4 v[26:27], off
	v_lshl_add_u64 v[26:27], s[44:45], 0, v[30:31]
	s_mov_b32 m0, s2
	s_nop 0
	global_load_lds_dwordx4 v[26:27], off
	v_ashrrev_i32_e32 v26, 8, v146
	v_cmp_eq_u32_e32 vcc, 1, v26
	s_and_saveexec_b64 s[44:45], vcc
	s_cbranch_execz .LBB0_1259
	s_barrier

; DI float h2lo(unsigned u) { return (float)__builtin_bit_cast(f16x2_t, u)[0]; }
; DI float h2hi(unsigned u) { return (float)__builtin_bit_cast(f16x2_t, u)[1]; }
; DI float fsigmoid(float x) { return __builtin_amdgcn_rcpf(1.0f + __expf(-x)); }
; #define EPI_M _Pragma("unroll") for (int m = 0; m < 8; ++m)
; #define EPI_N _Pragma("unroll") for (int n = 0; n < 4; ++n)
; DI void p10_phase(const Params& p, int layer, u16* dst, char* lds) {
;     ...
;     {
;       u32x2 rq[2][4];
;       EPI_N rq[0][n] = tp[(0 * 4 + n) * 512 + tid];
;       EPI_M {
;         if (m < 7) EPI_N rq[(m + 1) & 1][n] = tp[((m + 1) * 4 + n) * 512 + tid];
;         EPI_N {
;           const u32x2 r = rq[m & 1][n];
;           f32x4 v = ACC(m, n);
;           v[0] = h2lo(r[0]) * fsigmoid(v[0]); v[1] = h2hi(r[0]) * fsigmoid(v[1]); v[2] = h2lo(r[1]) * fsigmoid(v[2]); v[3] = h2hi(r[1]) * fsigmoid(v[3]);
;           ACC(m, n) = v;
;         }
;         __builtin_amdgcn_sched_barrier(0);
;       }
;     }
;     const u16* wd = (const u16*)(ws + OFF_WDOWN);
;     gemm256((const u16*)(ws + OFF_HB) + (size_t)row0 * DFF, DFF, wd + (size_t)col0 * DFF, wd + (size_t)(col0 + 128) * DFF, DFF, 44, acc, lds);
.LBB0_1263:
	s_or_b64 exec, exec, s[22:23]
	s_waitcnt vmcnt(0)
	s_barrier
	s_getreg_b32 s3, hwreg(HW_REG_HW_ID, 0, 6)
	s_lshl_b32 s3, s3, 2
	s_and_b32 s3, s3, 0xfc
	s_add_i32 s3, s3, 0x20040
	v_mov_b32_e32 v0, s3
	ds_read_b32 v0, v0
	s_waitcnt lgkmcnt(0)
	v_readfirstlane_b32 s3, v0
	s_nop 1
	v_lshl_or_b32 v98, s3, 6, v214
	s_movk_i32 s3, 0x2000
	v_ashrrev_i32_e32 v99, 31, v98
	v_lshl_add_u64 v[0:1], v[98:99], 3, s[16:17]
	v_add_co_u32_e32 v62, vcc, s3, v0
	v_add_u32_e32 v76, 0x800, v98
	s_nop 0
	v_addc_co_u32_e32 v63, vcc, 0, v1, vcc
	v_ashrrev_i32_e32 v77, 31, v76
	v_add_u32_e32 v82, 0xa00, v98
	v_add_co_u32_e32 v66, vcc, s58, v0
	v_lshl_add_u64 v[76:77], v[76:77], 3, s[16:17]
	v_ashrrev_i32_e32 v83, 31, v82
	v_addc_co_u32_e32 v67, vcc, 0, v1, vcc
	v_lshl_add_u64 v[82:83], v[82:83], 3, s[16:17]
	global_load_dwordx2 v[0:1], v[0:1], off
	s_nop 0
	global_load_dwordx2 v[208:209], v[66:67], off
	global_load_dwordx2 v[206:207], v[76:77], off
	global_load_dwordx2 v[204:205], v[82:83], off
	v_add_u32_e32 v66, 0xc00, v98
	v_add_u32_e32 v76, 0xe00, v98
	v_ashrrev_i32_e32 v67, 31, v66
	v_ashrrev_i32_e32 v77, 31, v76
	v_lshl_add_u64 v[66:67], v[66:67], 3, s[16:17]
	v_lshl_add_u64 v[76:77], v[76:77], 3, s[16:17]
	global_load_dwordx2 v[212:213], v[62:63], off offset:-4096
	global_load_dwordx2 v[210:211], v[62:63], off
	global_load_dwordx2 v[202:203], v[66:67], off
	global_load_dwordx2 v[200:201], v[76:77], off
	v_add_u32_e32 v62, 0x1000, v98
	v_ashrrev_i32_e32 v63, 31, v62
	v_add_u32_e32 v66, 0x1200, v98
	v_add_u32_e32 v76, 0x1400, v98
	v_add_u32_e32 v82, 0x1600, v98
	v_lshl_add_u64 v[62:63], v[62:63], 3, s[16:17]
	v_ashrrev_i32_e32 v67, 31, v66
	v_ashrrev_i32_e32 v77, 31, v76
	v_ashrrev_i32_e32 v83, 31, v82
	v_lshl_add_u64 v[66:67], v[66:67], 3, s[16:17]
	v_lshl_add_u64 v[76:77], v[76:77], 3, s[16:17]
	v_lshl_add_u64 v[82:83], v[82:83], 3, s[16:17]
	global_load_dwordx2 v[198:199], v[62:63], off
	global_load_dwordx2 v[196:197], v[66:67], off
	global_load_dwordx2 v[194:195], v[76:77], off
	global_load_dwordx2 v[192:193], v[82:83], off
	v_add_u32_e32 v62, 0x1800, v98
	v_ashrrev_i32_e32 v63, 31, v62
	v_add_u32_e32 v66, 0x1a00, v98
	v_add_u32_e32 v76, 0x1c00, v98
	v_add_u32_e32 v82, 0x1e00, v98
	v_lshl_add_u64 v[62:63], v[62:63], 3, s[16:17]
	v_ashrrev_i32_e32 v67, 31, v66
	v_ashrrev_i32_e32 v77, 31, v76
	v_ashrrev_i32_e32 v83, 31, v82
	v_lshl_add_u64 v[66:67], v[66:67], 3, s[16:17]
	v_lshl_add_u64 v[76:77], v[76:77], 3, s[16:17]
	v_lshl_add_u64 v[82:83], v[82:83], 3, s[16:17]
	global_load_dwordx2 v[190:191], v[62:63], off
	global_load_dwordx2 v[188:189], v[66:67], off
	global_load_dwordx2 v[186:187], v[76:77], off
	s_nop 0
	global_load_dwordx2 v[62:63], v[82:83], off
	v_add_u32_e32 v66, 0x2000, v98
	v_add_u32_e32 v76, 0x2200, v98
	v_add_u32_e32 v82, 0x2400, v98
	v_ashrrev_i32_e32 v67, 31, v66
	v_ashrrev_i32_e32 v77, 31, v76
	v_ashrrev_i32_e32 v83, 31, v82
	v_add_u32_e32 v88, 0x2600, v98
	v_lshl_add_u64 v[66:67], v[66:67], 3, s[16:17]
	v_lshl_add_u64 v[76:77], v[76:77], 3, s[16:17]
	v_lshl_add_u64 v[82:83], v[82:83], 3, s[16:17]
	v_ashrrev_i32_e32 v89, 31, v88
	v_lshl_add_u64 v[88:89], v[88:89], 3, s[16:17]
	global_load_dwordx2 v[66:67], v[66:67], off
	s_nop 0
	global_load_dwordx2 v[184:185], v[76:77], off
	s_nop 0
	global_load_dwordx2 v[76:77], v[82:83], off
	s_nop 0
	global_load_dwordx2 v[82:83], v[88:89], off
	v_add_u32_e32 v88, 0x2800, v98
	v_ashrrev_i32_e32 v89, 31, v88
	v_add_u32_e32 v100, 0x2a00, v98
	v_add_u32_e32 v146, 0x2c00, v98
	v_add_u32_e32 v148, 0x2e00, v98
	v_lshl_add_u64 v[88:89], v[88:89], 3, s[16:17]
	v_ashrrev_i32_e32 v101, 31, v100
	v_ashrrev_i32_e32 v147, 31, v146
	v_ashrrev_i32_e32 v149, 31, v148
	v_lshl_add_u64 v[100:101], v[100:101], 3, s[16:17]
	v_lshl_add_u64 v[146:147], v[146:147], 3, s[16:17]
	v_lshl_add_u64 v[148:149], v[148:149], 3, s[16:17]
	global_load_dwordx2 v[88:89], v[88:89], off
	s_nop 0
	global_load_dwordx2 v[182:183], v[100:101], off
	global_load_dwordx2 v[180:181], v[146:147], off
	global_load_dwordx2 v[178:179], v[148:149], off
	v_add_u32_e32 v100, 0x3000, v98
	v_ashrrev_i32_e32 v101, 31, v100
	v_add_u32_e32 v146, 0x3200, v98
	v_add_u32_e32 v148, 0x3400, v98
	v_add_u32_e32 v150, 0x3600, v98
	v_lshl_add_u64 v[100:101], v[100:101], 3, s[16:17]
	v_ashrrev_i32_e32 v147, 31, v146
	v_ashrrev_i32_e32 v149, 31, v148
	v_ashrrev_i32_e32 v151, 31, v150
	v_lshl_add_u64 v[146:147], v[146:147], 3, s[16:17]
	v_lshl_add_u64 v[148:149], v[148:149], 3, s[16:17]
	v_lshl_add_u64 v[150:151], v[150:151], 3, s[16:17]
	global_load_dwordx2 v[176:177], v[100:101], off
	global_load_dwordx2 v[174:175], v[146:147], off
	global_load_dwordx2 v[172:173], v[148:149], off
	global_load_dwordx2 v[170:171], v[150:151], off
	v_add_u32_e32 v100, 0x3800, v98
	v_ashrrev_i32_e32 v101, 31, v100
	v_add_u32_e32 v146, 0x3a00, v98
	v_add_u32_e32 v148, 0x3c00, v98
	v_add_u32_e32 v98, 0x3e00, v98
	v_lshl_add_u64 v[100:101], v[100:101], 3, s[16:17]
	v_ashrrev_i32_e32 v147, 31, v146
	v_ashrrev_i32_e32 v149, 31, v148
	v_ashrrev_i32_e32 v99, 31, v98
	v_lshl_add_u64 v[146:147], v[146:147], 3, s[16:17]
	v_lshl_add_u64 v[148:149], v[148:149], 3, s[16:17]
	v_lshl_add_u64 v[98:99], v[98:99], 3, s[16:17]
	global_load_dwordx2 v[156:157], v[100:101], off
	global_load_dwordx2 v[154:155], v[146:147], off
	global_load_dwordx2 v[152:153], v[148:149], off
	global_load_dwordx2 v[150:151], v[98:99], off
	s_mul_i32 s7, s36, 0x1600
	v_readlane_b32 s22, v253, 62
	s_mul_hi_i32 s3, s36, 0x1600
	v_readlane_b32 s23, v253, 63
	s_add_u32 s22, s22, s7
	s_addc_u32 s23, s23, s3
	s_mul_i32 s28, s42, 0x1600
	v_readlane_b32 s46, v252, 38
	s_mul_hi_i32 s29, s42, 0x1600
	v_readlane_b32 s47, v252, 39
	s_add_u32 s44, s46, s28
	s_addc_u32 s45, s47, s29
	s_mul_i32 s7, s8, 0x1600
	s_mul_hi_i32 s3, s8, 0x1600
	s_add_u32 s8, s46, s7
	s_addc_u32 s9, s47, s3
	s_getreg_b32 s3, hwreg(HW_REG_HW_ID, 0, 6)
	s_lshl_b32 s3, s3, 2
	s_and_b32 s3, s3, 0xfc
	s_add_i32 s3, s3, 0x20040
	v_mov_b32_e32 v64, s3
	ds_read_b32 v64, v64
	s_waitcnt lgkmcnt(0)
; DI int my_tid() { int t = tid_raw(); asm volatile("" : "+v"(t)); return t; }
; #define STAGE_A(b, h, kt) { const u16* ap_ = A + (size_t)((h) * ahalf + (unsigned)(kt) * 64u); glds16(ap_ + ao0, l0 + SA_(b, h)); glds16(ap_ + ao1, l0 + SA_(b, h) + 8192); }
; #define STAGE_B(b, h, kt) { const u16* bp_ = ((h) ? B1 : B0) + (unsigned)(kt) * 64u; glds16(bp_ + bo0, l0 + SB_(b, h)); glds16(bp_ + bo1, l0 + SB_(b, h) + 8192); }
; #define WAIT_V(n) asm volatile("s_waitcnt vmcnt(" #n ")" ::: "memory");
; #define BAR __builtin_amdgcn_s_barrier();
; DI void gemm256(const u16* __restrict__ A, int lda, const u16* __restrict__ B0, const u16* __restrict__ B1, int ldb, int nt, acc_t& acc, char* lds) {
;   const int tid = my_tid();
;   const int lane = tid & 63, wid = tid >> 6, wr = wid >> 2, wc = wid & 3, fr = lane & 15, fq = lane >> 4;
;   int r0, c0, r1, c1;
;   stage_rc(tid * 16, r0, c0); stage_rc(tid * 16 + 8192, r1, c1);
;   const unsigned ao0 = (unsigned)(r0 * lda + c0), ao1 = (unsigned)(r1 * lda + c1);
;   const unsigned ahalf = 128u * (unsigned)lda;
;   const int p0 = (r0 & ~31) + (((r0 & 15) >> 2) * 8) + (((r0 >> 4) & 1) * 4) + (r0 & 3), p1 = (r1 & ~31) + (((r1 & 15) >> 2) * 8) + (((r1 >> 4) & 1) * 4) + (r1 & 3);
;   const unsigned bo0 = (unsigned)(p0 * ldb + c0), bo1 = (unsigned)(p1 * ldb + c1);
;   char* l0 = lds + tid * 16;
;     ...
;   bf16x8 At[4][2], Bq0[2][2], Bq1[2][2];
;   WAIT_V(0)
;   STAGE_B(0, 0, 0) STAGE_A(0, 0, 0) STAGE_B(0, 1, 0) STAGE_A(0, 1, 0)
;   if (wr == 1) BAR
;   WAIT_V(4) BAR
;   STAGE_B(1, 0, 1) STAGE_A(1, 0, 1) STAGE_B(1, 1, 1)
;   WAIT_V(6) BAR
	v_readfirstlane_b32 s3, v64
	s_nop 1
	v_lshl_or_b32 v225, s3, 6, v214
	s_nop 0
	v_bfe_i32 v98, v225, 27, 1
	v_lshlrev_b32_e32 v158, 4, v225
	v_lshrrev_b32_e32 v98, 22, v98
	v_add_u32_e32 v98, v158, v98
	v_and_b32_e32 v98, 0xfffffc00, v98
	v_sub_u32_e32 v98, v158, v98
	v_ashrrev_i32_e32 v64, 31, v225
	v_lshrrev_b32_e32 v99, 4, v98
	v_lshrrev_b32_e32 v64, 26, v64
	v_bitop3_b32 v99, v99, v98, 32 bitop3:0x6c
	v_ashrrev_i32_e32 v98, 31, v98
	v_add_u32_e32 v64, v225, v64
	v_lshrrev_b32_e32 v98, 26, v98
	v_ashrrev_i32_e32 v64, 6, v64
	v_add_u32_e32 v98, v99, v98
	v_lshlrev_b32_e32 v100, 3, v64
	v_ashrrev_i32_e32 v148, 6, v98
	v_lshlrev_b32_e32 v64, 5, v64
	v_and_b32_e32 v235, 32, v64
	v_mul_i32_i24_e32 v64, 64, v148
	v_add_u32_e32 v98, 0x2000, v158
	v_sub_u32_e32 v64, v99, v64
	v_ashrrev_i32_e32 v99, 31, v98
	v_lshrrev_b32_e32 v99, 22, v99
	v_add_u32_e32 v99, v98, v99
	v_ashrrev_i32_e32 v234, 10, v99
	v_mul_i32_i24_e32 v99, 0x400, v234
	v_sub_u32_e32 v98, v98, v99
	v_lshrrev_b32_e32 v99, 4, v98
	v_and_b32_e32 v100, -16, v100
	v_bitop3_b32 v98, v99, v98, 32 bitop3:0x6c
	v_add_u32_e32 v149, v148, v100
	v_ashrrev_i32_e32 v100, 31, v98
	v_lshrrev_b32_e32 v100, 26, v100
	v_add_u32_e32 v100, v98, v100
	v_ashrrev_i16_sdwa v238, v215, sext(v64) dst_sel:DWORD dst_unused:UNUSED_PAD src0_sel:DWORD src1_sel:BYTE_0
	v_ashrrev_i32_e32 v236, 6, v100
	v_and_b32_e32 v100, 0xc0, v100
	v_add_u32_sdwa v64, v235, sext(v238) dst_sel:DWORD dst_unused:UNUSED_PAD src0_sel:DWORD src1_sel:WORD_0
	v_lshlrev_b32_e32 v99, 3, v234
	v_lshlrev_b32_e32 v101, 5, v234
	v_sub_u32_e32 v98, v98, v100
	v_and_b32_e32 v99, -16, v99
	v_and_b32_e32 v237, 32, v101
	v_ashrrev_i16_sdwa v239, v215, sext(v98) dst_sel:DWORD dst_unused:UNUSED_PAD src0_sel:DWORD src1_sel:BYTE_0
	v_mad_u64_u32 v[100:101], s[46:47], v149, s67, v[64:65]
	v_add_u32_e32 v99, v236, v99
	v_add_u32_sdwa v98, v237, sext(v239) dst_sel:DWORD dst_unused:UNUSED_PAD src0_sel:DWORD src1_sel:WORD_0
	v_lshlrev_b32_e32 v101, 1, v149
	v_mad_u64_u32 v[146:147], s[46:47], v99, s67, v[98:99]
	v_and_b32_e32 v240, 0xffffffe0, v149
	v_and_b32_e32 v242, 24, v101
	v_lshrrev_b32_e32 v101, 2, v149
	v_and_b32_e32 v246, 3, v148
	v_and_b32_e32 v244, 4, v101
	v_or_b32_e32 v101, v240, v246
	v_and_b32_e32 v241, 0xffffffe0, v99
	v_lshlrev_b32_e32 v147, 1, v99
	v_lshrrev_b32_e32 v99, 2, v99
	v_and_b32_e32 v247, 3, v236
	v_or3_b32 v101, v101, v242, v244
	v_and_b32_e32 v243, 24, v147
	v_and_b32_e32 v245, 4, v99
	v_or_b32_e32 v99, v241, v247
	v_or3_b32 v99, v99, v243, v245
	v_mad_u64_u32 v[148:149], s[46:47], v101, s67, v[64:65]
	v_add_u32_e32 v226, 0, v158
	v_mad_u64_u32 v[98:99], s[46:47], v99, s67, v[98:99]
	v_mov_b32_e32 v149, v65
	v_add_u32_e32 v227, 0x10000, v226
	v_lshlrev_b64 v[164:165], 1, v[148:149]
	v_readfirstlane_b32 s3, v227
	v_mov_b32_e32 v99, v65
	v_add_u32_e32 v228, 0x12000, v226
	v_lshl_add_u64 v[158:159], s[44:45], 0, v[164:165]
	s_mov_b32 m0, s3
	v_lshlrev_b64 v[98:99], 1, v[98:99]
	v_readfirstlane_b32 s3, v228
	v_mov_b32_e32 v64, v100
	global_load_lds_dwordx4 v[158:159], off
	v_lshl_add_u64 v[160:161], s[44:45], 0, v[98:99]
	s_mov_b32 m0, s3
	v_lshlrev_b64 v[148:149], 1, v[64:65]
	v_readfirstlane_b32 s3, v226
	v_mov_b32_e32 v147, v65
	v_add_u32_e32 v229, 0x2000, v226
	global_load_lds_dwordx4 v[160:161], off
	v_lshl_add_u64 v[162:163], s[22:23], 0, v[148:149]
	s_mov_b32 m0, s3
	v_lshlrev_b64 v[100:101], 1, v[146:147]
	v_readfirstlane_b32 s3, v229
	v_add_u32_e32 v230, 0x14000, v226
	global_load_lds_dwordx4 v[162:163], off
	v_lshl_add_u64 v[166:167], s[22:23], 0, v[100:101]
	s_mov_b32 m0, s3
	v_readfirstlane_b32 s3, v230
	v_add_u32_e32 v231, 0x16000, v226
	global_load_lds_dwordx4 v[166:167], off
	v_lshl_add_u64 v[168:169], s[8:9], 0, v[164:165]
	s_mov_b32 m0, s3
	v_lshl_add_u64 v[164:165], s[8:9], 0, v[98:99]
	v_readfirstlane_b32 s3, v231
	s_add_u32 s8, s22, 0xb0000
	v_add_u32_e32 v232, 0x4000, v226
	global_load_lds_dwordx4 v[168:169], off
	s_mov_b32 m0, s3
	s_addc_u32 s9, s23, 0
	v_readfirstlane_b32 s3, v232
	v_add_u32_e32 v233, 0x6000, v226
	global_load_lds_dwordx4 v[164:165], off
	v_lshl_add_u64 v[98:99], s[8:9], 0, v[148:149]
	s_mov_b32 m0, s3
	v_readfirstlane_b32 s3, v233
	global_load_lds_dwordx4 v[98:99], off
	v_lshl_add_u64 v[98:99], s[8:9], 0, v[100:101]
	s_mov_b32 m0, s3
	v_ashrrev_i32_e32 v248, 8, v225
	global_load_lds_dwordx4 v[98:99], off
	v_cmp_eq_u32_e32 vcc, 1, v248
	s_and_saveexec_b64 s[8:9], vcc
	s_cbranch_execz .LBB0_1265
	s_barrier
